# GEMM main loops: MFMAs reordered so the two K-halves of each accumulator issue back to back (accumulate chain forwarding) instead of 8 apart
# speedup vs baseline: 1.0136x; 1.0097x over previous
.LBB0_472:
	ds_read_b128 v[152:155], v148
	ds_read_b128 v[156:159], v148 offset:1024
	ds_read_b128 v[166:169], v148 offset:2048
	ds_read_b128 v[170:173], v148 offset:3072
	ds_read_b128 v[174:177], v149
	ds_read_b128 v[178:181], v149 offset:1024
	ds_read_b128 v[182:185], v149 offset:2048
	ds_read_b128 v[186:189], v149 offset:3072
	s_add_u32 s44, s54, 0xfff00080
	s_addc_u32 s56, s55, -1
	s_cmp_eq_u32 s72, 60
	s_cselect_b32 s59, s17, s56
	s_cselect_b32 s58, s68, s44
	s_cselect_b32 s57, s15, s71
	s_cselect_b32 s56, s69, s70
	v_lshl_add_u64 v[160:161], s[54:55], 0, v[138:139]
	s_add_i32 m0, s41, 0xc000
	ds_read_b128 v[190:193], v150
	ds_read_b128 v[194:197], v150 offset:1024
	ds_read_b128 v[198:201], v150 offset:2048
	ds_read_b128 v[202:205], v150 offset:3072
	ds_read_b128 v[206:209], v150 offset:4096
	ds_read_b128 v[210:213], v150 offset:5120
	ds_read_b128 v[214:217], v150 offset:6144
	ds_read_b128 v[218:221], v150 offset:7168
	global_load_lds_dwordx4 v[160:161], off
	v_lshl_add_u64 v[160:161], s[54:55], 0, v[140:141]
	s_add_i32 m0, s41, 0xe000
	s_nop 0
	global_load_lds_dwordx4 v[160:161], off
	s_waitcnt vmcnt(8)
	s_waitcnt lgkmcnt(0)
	s_barrier
	s_setprio 1
	s_waitcnt lgkmcnt(0)
	v_mfma_f32_16x16x32_bf16 v[126:129], v[152:155], v[190:193], v[126:129]
	v_mfma_f32_16x16x32_bf16 v[126:129], v[156:159], v[194:197], v[126:129]
	v_mfma_f32_16x16x32_bf16 v[122:125], v[166:169], v[190:193], v[122:125]
	v_mfma_f32_16x16x32_bf16 v[122:125], v[170:173], v[194:197], v[122:125]
	v_mfma_f32_16x16x32_bf16 v[118:121], v[152:155], v[198:201], v[118:121]
	v_mfma_f32_16x16x32_bf16 v[118:121], v[156:159], v[202:205], v[118:121]
	v_mfma_f32_16x16x32_bf16 v[110:113], v[166:169], v[198:201], v[110:113]
	v_mfma_f32_16x16x32_bf16 v[110:113], v[170:173], v[202:205], v[110:113]
	v_mfma_f32_16x16x32_bf16 v[102:105], v[152:155], v[206:209], v[102:105]
	v_mfma_f32_16x16x32_bf16 v[102:105], v[156:159], v[210:213], v[102:105]
	v_mfma_f32_16x16x32_bf16 v[94:97], v[166:169], v[206:209], v[94:97]
	v_mfma_f32_16x16x32_bf16 v[94:97], v[170:173], v[210:213], v[94:97]
	v_mfma_f32_16x16x32_bf16 v[86:89], v[152:155], v[214:217], v[86:89]
	v_mfma_f32_16x16x32_bf16 v[86:89], v[156:159], v[218:221], v[86:89]
	v_mfma_f32_16x16x32_bf16 v[78:81], v[166:169], v[214:217], v[78:81]
	v_mfma_f32_16x16x32_bf16 v[78:81], v[170:173], v[218:221], v[78:81]
	s_setprio 0
	s_setprio 1
	v_mfma_f32_16x16x32_bf16 v[114:117], v[174:177], v[190:193], v[114:117]
	v_mfma_f32_16x16x32_bf16 v[114:117], v[178:181], v[194:197], v[114:117]
	v_mfma_f32_16x16x32_bf16 v[106:109], v[182:185], v[190:193], v[106:109]
	v_mfma_f32_16x16x32_bf16 v[106:109], v[186:189], v[194:197], v[106:109]
	v_mfma_f32_16x16x32_bf16 v[98:101], v[174:177], v[198:201], v[98:101]
	v_mfma_f32_16x16x32_bf16 v[98:101], v[178:181], v[202:205], v[98:101]
	v_mfma_f32_16x16x32_bf16 v[90:93], v[182:185], v[198:201], v[90:93]
	v_mfma_f32_16x16x32_bf16 v[90:93], v[186:189], v[202:205], v[90:93]
	v_mfma_f32_16x16x32_bf16 v[82:85], v[174:177], v[206:209], v[82:85]
	v_mfma_f32_16x16x32_bf16 v[82:85], v[178:181], v[210:213], v[82:85]
	v_mfma_f32_16x16x32_bf16 v[74:77], v[182:185], v[206:209], v[74:77]
	v_mfma_f32_16x16x32_bf16 v[74:77], v[186:189], v[210:213], v[74:77]
	v_mfma_f32_16x16x32_bf16 v[70:73], v[174:177], v[214:217], v[70:73]
	v_mfma_f32_16x16x32_bf16 v[70:73], v[178:181], v[218:221], v[70:73]
	v_mfma_f32_16x16x32_bf16 v[66:69], v[182:185], v[214:217], v[66:69]
	v_mfma_f32_16x16x32_bf16 v[66:69], v[186:189], v[218:221], v[66:69]
	s_setprio 0
	s_barrier
	s_add_i32 s44, s64, s27
	v_lshl_add_u64 v[160:161], s[56:57], 0, v[134:135]
	s_mov_b32 m0, s44
	ds_read_b128 v[190:193], v150 offset:16384
	ds_read_b128 v[194:197], v150 offset:17408
	ds_read_b128 v[198:201], v150 offset:18432
	ds_read_b128 v[202:205], v150 offset:19456
	ds_read_b128 v[206:209], v150 offset:20480
	ds_read_b128 v[210:213], v150 offset:21504
	ds_read_b128 v[214:217], v150 offset:22528
	ds_read_b128 v[218:221], v150 offset:23552
	global_load_lds_dwordx4 v[160:161], off
	s_add_i32 m0, s44, 0x2000
	s_add_u32 s74, s56, 0x100000
	v_lshl_add_u64 v[222:223], s[56:57], 0, v[130:131]
	s_addc_u32 s75, s57, 0
	s_add_i32 s44, s65, s27
	global_load_lds_dwordx4 v[222:223], off
	v_lshl_add_u64 v[224:225], s[74:75], 0, v[134:135]
	s_mov_b32 m0, s44
	v_lshl_add_u64 v[226:227], s[58:59], 0, v[132:133]
	global_load_lds_dwordx4 v[224:225], off
	v_lshl_add_u64 v[224:225], s[74:75], 0, v[130:131]
	s_add_i32 m0, s44, 0x2000
	s_nop 0
	global_load_lds_dwordx4 v[224:225], off
	v_lshl_add_u64 v[224:225], s[58:59], 0, v[136:137]
	s_mov_b32 m0, s41
	s_nop 0
	global_load_lds_dwordx4 v[224:225], off
	s_mov_b32 m0, s43
	s_nop 0
	global_load_lds_dwordx4 v[226:227], off
	s_waitcnt vmcnt(8)
	s_waitcnt lgkmcnt(0)
	s_barrier
	s_setprio 1
	s_waitcnt lgkmcnt(0)
	v_mfma_f32_16x16x32_bf16 v[62:65], v[152:155], v[190:193], v[62:65]
	v_mfma_f32_16x16x32_bf16 v[62:65], v[156:159], v[194:197], v[62:65]
	v_mfma_f32_16x16x32_bf16 v[58:61], v[166:169], v[190:193], v[58:61]
	v_mfma_f32_16x16x32_bf16 v[58:61], v[170:173], v[194:197], v[58:61]
	v_mfma_f32_16x16x32_bf16 v[54:57], v[152:155], v[198:201], v[54:57]
	v_mfma_f32_16x16x32_bf16 v[54:57], v[156:159], v[202:205], v[54:57]
	v_mfma_f32_16x16x32_bf16 v[46:49], v[166:169], v[198:201], v[46:49]
	v_mfma_f32_16x16x32_bf16 v[46:49], v[170:173], v[202:205], v[46:49]
	v_mfma_f32_16x16x32_bf16 v[38:41], v[152:155], v[206:209], v[38:41]
	v_mfma_f32_16x16x32_bf16 v[38:41], v[156:159], v[210:213], v[38:41]
	v_mfma_f32_16x16x32_bf16 v[30:33], v[166:169], v[206:209], v[30:33]
	v_mfma_f32_16x16x32_bf16 v[30:33], v[170:173], v[210:213], v[30:33]
	v_mfma_f32_16x16x32_bf16 v[22:25], v[152:155], v[214:217], v[22:25]
	v_mfma_f32_16x16x32_bf16 v[22:25], v[156:159], v[218:221], v[22:25]
	v_mfma_f32_16x16x32_bf16 v[14:17], v[166:169], v[214:217], v[14:17]
	v_mfma_f32_16x16x32_bf16 v[14:17], v[170:173], v[218:221], v[14:17]
	s_setprio 0
	s_setprio 1
	v_mfma_f32_16x16x32_bf16 v[50:53], v[174:177], v[190:193], v[50:53]
	v_mfma_f32_16x16x32_bf16 v[50:53], v[178:181], v[194:197], v[50:53]
	v_mfma_f32_16x16x32_bf16 v[42:45], v[182:185], v[190:193], v[42:45]
	v_mfma_f32_16x16x32_bf16 v[42:45], v[186:189], v[194:197], v[42:45]
	v_mfma_f32_16x16x32_bf16 v[34:37], v[174:177], v[198:201], v[34:37]
	v_mfma_f32_16x16x32_bf16 v[34:37], v[178:181], v[202:205], v[34:37]
	v_mfma_f32_16x16x32_bf16 v[26:29], v[182:185], v[198:201], v[26:29]
	v_mfma_f32_16x16x32_bf16 v[26:29], v[186:189], v[202:205], v[26:29]
	v_mfma_f32_16x16x32_bf16 v[18:21], v[174:177], v[206:209], v[18:21]
	v_mfma_f32_16x16x32_bf16 v[18:21], v[178:181], v[210:213], v[18:21]
	v_mfma_f32_16x16x32_bf16 v[10:13], v[182:185], v[206:209], v[10:13]
	v_mfma_f32_16x16x32_bf16 v[10:13], v[186:189], v[210:213], v[10:13]
	v_mfma_f32_16x16x32_bf16 v[6:9], v[174:177], v[214:217], v[6:9]
	v_mfma_f32_16x16x32_bf16 v[6:9], v[178:181], v[218:221], v[6:9]
	v_mfma_f32_16x16x32_bf16 v[2:5], v[182:185], v[214:217], v[2:5]
	v_mfma_f32_16x16x32_bf16 v[2:5], v[186:189], v[218:221], v[2:5]
	s_setprio 0
	s_barrier
	s_add_i32 s44, 0, 0x18000
	v_add_u32_e32 v151, s44, v146
	s_add_i32 s73, 0, 0x1c000
	ds_read_b128 v[152:155], v151
	ds_read_b128 v[156:159], v151 offset:1024
	ds_read_b128 v[166:169], v151 offset:2048
	ds_read_b128 v[170:173], v151 offset:3072
	v_add_u32_e32 v151, s73, v146
	ds_read_b128 v[174:177], v151
	ds_read_b128 v[178:181], v151 offset:1024
	ds_read_b128 v[182:185], v151 offset:2048
	ds_read_b128 v[186:189], v151 offset:3072
	s_add_u32 s58, s58, 0x100000
	s_addc_u32 s59, s59, 0
	s_mov_b32 m0, s45
	v_lshl_add_u64 v[228:229], s[58:59], 0, v[136:137]
	ds_read_b128 v[190:193], v150 offset:32768
	ds_read_b128 v[194:197], v150 offset:33792
	ds_read_b128 v[198:201], v150 offset:34816
	ds_read_b128 v[202:205], v150 offset:35840
	ds_read_b128 v[206:209], v150 offset:36864
	ds_read_b128 v[210:213], v150 offset:37888
	ds_read_b128 v[214:217], v150 offset:38912
	ds_read_b128 v[218:221], v150 offset:39936
	global_load_lds_dwordx4 v[228:229], off
	v_lshl_add_u64 v[228:229], s[58:59], 0, v[132:133]
	s_mov_b32 m0, s53
	s_nop 0
	global_load_lds_dwordx4 v[228:229], off
	s_waitcnt vmcnt(8)
	s_waitcnt lgkmcnt(0)
	s_barrier
	s_setprio 1
	s_waitcnt lgkmcnt(0)
	v_mfma_f32_16x16x32_bf16 v[126:129], v[152:155], v[190:193], v[126:129]
	v_mfma_f32_16x16x32_bf16 v[126:129], v[156:159], v[194:197], v[126:129]
	v_mfma_f32_16x16x32_bf16 v[122:125], v[166:169], v[190:193], v[122:125]
	v_mfma_f32_16x16x32_bf16 v[122:125], v[170:173], v[194:197], v[122:125]
	v_mfma_f32_16x16x32_bf16 v[118:121], v[152:155], v[198:201], v[118:121]
	v_mfma_f32_16x16x32_bf16 v[118:121], v[156:159], v[202:205], v[118:121]
	v_mfma_f32_16x16x32_bf16 v[110:113], v[166:169], v[198:201], v[110:113]
	v_mfma_f32_16x16x32_bf16 v[110:113], v[170:173], v[202:205], v[110:113]
	v_mfma_f32_16x16x32_bf16 v[102:105], v[152:155], v[206:209], v[102:105]
	v_mfma_f32_16x16x32_bf16 v[102:105], v[156:159], v[210:213], v[102:105]
	v_mfma_f32_16x16x32_bf16 v[94:97], v[166:169], v[206:209], v[94:97]
	v_mfma_f32_16x16x32_bf16 v[94:97], v[170:173], v[210:213], v[94:97]
	v_mfma_f32_16x16x32_bf16 v[86:89], v[152:155], v[214:217], v[86:89]
	v_mfma_f32_16x16x32_bf16 v[86:89], v[156:159], v[218:221], v[86:89]
	v_mfma_f32_16x16x32_bf16 v[78:81], v[166:169], v[214:217], v[78:81]
	v_mfma_f32_16x16x32_bf16 v[78:81], v[170:173], v[218:221], v[78:81]
	s_setprio 0
	s_setprio 1
	v_mfma_f32_16x16x32_bf16 v[114:117], v[174:177], v[190:193], v[114:117]
	v_mfma_f32_16x16x32_bf16 v[114:117], v[178:181], v[194:197], v[114:117]
	v_mfma_f32_16x16x32_bf16 v[106:109], v[182:185], v[190:193], v[106:109]
	v_mfma_f32_16x16x32_bf16 v[106:109], v[186:189], v[194:197], v[106:109]
	v_mfma_f32_16x16x32_bf16 v[98:101], v[174:177], v[198:201], v[98:101]
	v_mfma_f32_16x16x32_bf16 v[98:101], v[178:181], v[202:205], v[98:101]
	v_mfma_f32_16x16x32_bf16 v[90:93], v[182:185], v[198:201], v[90:93]
	v_mfma_f32_16x16x32_bf16 v[90:93], v[186:189], v[202:205], v[90:93]
	v_mfma_f32_16x16x32_bf16 v[82:85], v[174:177], v[206:209], v[82:85]
	v_mfma_f32_16x16x32_bf16 v[82:85], v[178:181], v[210:213], v[82:85]
	v_mfma_f32_16x16x32_bf16 v[74:77], v[182:185], v[206:209], v[74:77]
	v_mfma_f32_16x16x32_bf16 v[74:77], v[186:189], v[210:213], v[74:77]
	v_mfma_f32_16x16x32_bf16 v[70:73], v[174:177], v[214:217], v[70:73]
	v_mfma_f32_16x16x32_bf16 v[70:73], v[178:181], v[218:221], v[70:73]
	v_mfma_f32_16x16x32_bf16 v[66:69], v[182:185], v[214:217], v[66:69]
	v_mfma_f32_16x16x32_bf16 v[66:69], v[186:189], v[218:221], v[66:69]
	s_setprio 0
	s_barrier
	s_add_i32 s44, s44, s27
	v_lshl_add_u64 v[160:161], v[160:161], 0, s[10:11]
	s_mov_b32 m0, s44
	ds_read_b128 v[190:193], v150 offset:49152
	ds_read_b128 v[194:197], v150 offset:50176
	ds_read_b128 v[198:201], v150 offset:51200
	ds_read_b128 v[202:205], v150 offset:52224
	ds_read_b128 v[206:209], v150 offset:53248
	ds_read_b128 v[210:213], v150 offset:54272
	ds_read_b128 v[214:217], v150 offset:55296
	ds_read_b128 v[218:221], v150 offset:56320
	global_load_lds_dwordx4 v[160:161], off
	s_add_i32 m0, s44, 0x2000
	s_add_u32 s56, s56, 0x100080
	v_lshl_add_u64 v[160:161], v[222:223], 0, s[10:11]
	s_addc_u32 s57, s57, 0
	s_add_i32 s44, s73, s27
	global_load_lds_dwordx4 v[160:161], off
	v_lshl_add_u64 v[160:161], s[56:57], 0, v[134:135]
	s_mov_b32 m0, s44
	s_nop 0
	global_load_lds_dwordx4 v[160:161], off
	v_lshl_add_u64 v[160:161], s[56:57], 0, v[130:131]
	s_add_i32 m0, s44, 0x2000
	s_nop 0
	global_load_lds_dwordx4 v[160:161], off
	v_lshl_add_u64 v[160:161], v[224:225], 0, s[10:11]
	s_mov_b32 m0, s61
	s_nop 0
	global_load_lds_dwordx4 v[160:161], off
	v_lshl_add_u64 v[160:161], v[226:227], 0, s[10:11]
	s_mov_b32 m0, s62
	s_nop 0
	global_load_lds_dwordx4 v[160:161], off
	s_waitcnt vmcnt(8)
	s_waitcnt lgkmcnt(0)
	s_barrier
	s_setprio 1
	s_waitcnt lgkmcnt(0)
	v_mfma_f32_16x16x32_bf16 v[62:65], v[152:155], v[190:193], v[62:65]
	v_mfma_f32_16x16x32_bf16 v[62:65], v[156:159], v[194:197], v[62:65]
	v_mfma_f32_16x16x32_bf16 v[58:61], v[166:169], v[190:193], v[58:61]
	v_mfma_f32_16x16x32_bf16 v[58:61], v[170:173], v[194:197], v[58:61]
	v_mfma_f32_16x16x32_bf16 v[54:57], v[152:155], v[198:201], v[54:57]
	v_mfma_f32_16x16x32_bf16 v[54:57], v[156:159], v[202:205], v[54:57]
	v_mfma_f32_16x16x32_bf16 v[46:49], v[166:169], v[198:201], v[46:49]
	v_mfma_f32_16x16x32_bf16 v[46:49], v[170:173], v[202:205], v[46:49]
	v_mfma_f32_16x16x32_bf16 v[38:41], v[152:155], v[206:209], v[38:41]
	v_mfma_f32_16x16x32_bf16 v[38:41], v[156:159], v[210:213], v[38:41]
	v_mfma_f32_16x16x32_bf16 v[30:33], v[166:169], v[206:209], v[30:33]
	v_mfma_f32_16x16x32_bf16 v[30:33], v[170:173], v[210:213], v[30:33]
	v_mfma_f32_16x16x32_bf16 v[22:25], v[152:155], v[214:217], v[22:25]
	v_mfma_f32_16x16x32_bf16 v[22:25], v[156:159], v[218:221], v[22:25]
	v_mfma_f32_16x16x32_bf16 v[14:17], v[166:169], v[214:217], v[14:17]
	v_mfma_f32_16x16x32_bf16 v[14:17], v[170:173], v[218:221], v[14:17]
	s_setprio 0
	s_setprio 1
	v_mfma_f32_16x16x32_bf16 v[50:53], v[174:177], v[190:193], v[50:53]
	v_mfma_f32_16x16x32_bf16 v[50:53], v[178:181], v[194:197], v[50:53]
	v_mfma_f32_16x16x32_bf16 v[42:45], v[182:185], v[190:193], v[42:45]
	v_mfma_f32_16x16x32_bf16 v[42:45], v[186:189], v[194:197], v[42:45]
	v_mfma_f32_16x16x32_bf16 v[34:37], v[174:177], v[198:201], v[34:37]
	v_mfma_f32_16x16x32_bf16 v[34:37], v[178:181], v[202:205], v[34:37]
	v_mfma_f32_16x16x32_bf16 v[26:29], v[182:185], v[198:201], v[26:29]
	v_mfma_f32_16x16x32_bf16 v[26:29], v[186:189], v[202:205], v[26:29]
	v_mfma_f32_16x16x32_bf16 v[18:21], v[174:177], v[206:209], v[18:21]
	v_mfma_f32_16x16x32_bf16 v[18:21], v[178:181], v[210:213], v[18:21]
	v_mfma_f32_16x16x32_bf16 v[10:13], v[182:185], v[206:209], v[10:13]
	v_mfma_f32_16x16x32_bf16 v[10:13], v[186:189], v[210:213], v[10:13]
	v_mfma_f32_16x16x32_bf16 v[6:9], v[174:177], v[214:217], v[6:9]
	v_mfma_f32_16x16x32_bf16 v[6:9], v[178:181], v[218:221], v[6:9]
	v_mfma_f32_16x16x32_bf16 v[2:5], v[182:185], v[214:217], v[2:5]
	v_mfma_f32_16x16x32_bf16 v[2:5], v[186:189], v[218:221], v[2:5]
	s_setprio 0
	s_barrier
	s_add_i32 s72, s72, 2
	s_add_u32 s54, s54, 0x100
	s_addc_u32 s55, s55, 0
	s_add_u32 s70, s70, 0x100
	s_addc_u32 s71, s71, 0
	s_cmp_gt_u32 s72, 61
	s_cbranch_scc0 .LBB0_472
	s_and_b64 vcc, exec, s[12:13]
	s_cbranch_vccz .LBB0_475
	s_barrier

.LBB0_706:
	s_add_u32 s72, s60, s44
	s_addc_u32 s73, s61, 0
	s_add_u32 s68, s72, 0x100
	s_addc_u32 s69, s73, 0
	s_and_b64 s[66:67], s[64:65], exec
	s_cselect_b32 s69, s17, s69
	s_cselect_b32 s68, s86, s68
	s_add_u32 s44, s56, s44
	s_addc_u32 s66, s57, 0
	s_add_u32 s44, s44, 0x100
	s_addc_u32 s66, s66, 0
	s_and_b64 s[64:65], s[64:65], exec
	s_cselect_b32 s71, s15, s66
	s_cselect_b32 s70, s87, s44
	s_add_u32 s74, s72, 0x10080
	s_addc_u32 s75, s73, 0
	s_add_i32 vcc_hi, s82, s27
	ds_read_b128 v[150:153], v147
	ds_read_b128 v[154:157], v147 offset:1024
	ds_read_b128 v[158:161], v147 offset:2048
	ds_read_b128 v[166:169], v147 offset:3072
	ds_read_b128 v[170:173], v148
	ds_read_b128 v[174:177], v148 offset:1024
	ds_read_b128 v[178:181], v148 offset:2048
	ds_read_b128 v[182:185], v148 offset:3072
	s_add_i32 m0, s36, 0xc000
	s_add_i32 s45, s36, 0xe000
	s_add_i32 s96, vcc_hi, 0x2000
	s_add_u32 s72, s70, 0x10000
	s_addc_u32 s73, s71, 0
	s_add_i32 vcc_lo, s83, s27
	s_add_i32 s97, vcc_lo, 0x2000
	s_add_i32 s95, 0, 0x18000
	s_add_i32 s94, 0, 0x1c000
	s_add_u32 s66, s68, 0x10000
	s_addc_u32 s67, s69, 0
	s_add_i32 s93, s95, s27
	s_add_i32 s89, s93, 0x2000
	s_add_u32 s64, s70, 0x10080
	s_addc_u32 s65, s71, 0
	s_add_i32 s92, s94, s27
	s_add_i32 s44, s92, 0x2000
	v_lshl_add_u64 v[198:199], s[74:75], 0, v[130:131]
	ds_read_b128 v[186:189], v149
	ds_read_b128 v[190:193], v149 offset:1024
	ds_read_b128 v[194:197], v149 offset:2048
	ds_read_b128 v[202:205], v149 offset:3072
	ds_read_b128 v[206:209], v149 offset:4096
	ds_read_b128 v[210:213], v149 offset:5120
	ds_read_b128 v[214:217], v149 offset:6144
	ds_read_b128 v[218:221], v149 offset:7168
	global_load_lds_dwordx4 v[198:199], off
	v_lshl_add_u64 v[198:199], s[74:75], 0, v[134:135]
	s_mov_b32 m0, s45
	s_nop 0
	global_load_lds_dwordx4 v[198:199], off
	s_waitcnt vmcnt(8)
	s_waitcnt lgkmcnt(0)
	s_barrier
	s_setprio 1
	s_waitcnt lgkmcnt(0)
	v_mfma_f32_16x16x32_bf16 v[126:129], v[150:153], v[186:189], v[126:129]
	v_mfma_f32_16x16x32_bf16 v[126:129], v[154:157], v[190:193], v[126:129]
	v_mfma_f32_16x16x32_bf16 v[122:125], v[158:161], v[186:189], v[122:125]
	v_mfma_f32_16x16x32_bf16 v[122:125], v[166:169], v[190:193], v[122:125]
	v_mfma_f32_16x16x32_bf16 v[118:121], v[150:153], v[194:197], v[118:121]
	v_mfma_f32_16x16x32_bf16 v[118:121], v[154:157], v[202:205], v[118:121]
	v_mfma_f32_16x16x32_bf16 v[110:113], v[158:161], v[194:197], v[110:113]
	v_mfma_f32_16x16x32_bf16 v[110:113], v[166:169], v[202:205], v[110:113]
	v_mfma_f32_16x16x32_bf16 v[102:105], v[150:153], v[206:209], v[102:105]
	v_mfma_f32_16x16x32_bf16 v[102:105], v[154:157], v[210:213], v[102:105]
	v_mfma_f32_16x16x32_bf16 v[94:97], v[158:161], v[206:209], v[94:97]
	v_mfma_f32_16x16x32_bf16 v[94:97], v[166:169], v[210:213], v[94:97]
	v_mfma_f32_16x16x32_bf16 v[86:89], v[150:153], v[214:217], v[86:89]
	v_mfma_f32_16x16x32_bf16 v[86:89], v[154:157], v[218:221], v[86:89]
	v_mfma_f32_16x16x32_bf16 v[78:81], v[158:161], v[214:217], v[78:81]
	v_mfma_f32_16x16x32_bf16 v[78:81], v[166:169], v[218:221], v[78:81]
	s_setprio 0
	s_setprio 1
	v_mfma_f32_16x16x32_bf16 v[114:117], v[170:173], v[186:189], v[114:117]
	v_mfma_f32_16x16x32_bf16 v[114:117], v[174:177], v[190:193], v[114:117]
	v_mfma_f32_16x16x32_bf16 v[106:109], v[178:181], v[186:189], v[106:109]
	v_mfma_f32_16x16x32_bf16 v[106:109], v[182:185], v[190:193], v[106:109]
	v_mfma_f32_16x16x32_bf16 v[98:101], v[170:173], v[194:197], v[98:101]
	v_mfma_f32_16x16x32_bf16 v[98:101], v[174:177], v[202:205], v[98:101]
	v_mfma_f32_16x16x32_bf16 v[90:93], v[178:181], v[194:197], v[90:93]
	v_mfma_f32_16x16x32_bf16 v[90:93], v[182:185], v[202:205], v[90:93]
	v_mfma_f32_16x16x32_bf16 v[82:85], v[170:173], v[206:209], v[82:85]
	v_mfma_f32_16x16x32_bf16 v[82:85], v[174:177], v[210:213], v[82:85]
	v_mfma_f32_16x16x32_bf16 v[74:77], v[178:181], v[206:209], v[74:77]
	v_mfma_f32_16x16x32_bf16 v[74:77], v[182:185], v[210:213], v[74:77]
	v_mfma_f32_16x16x32_bf16 v[70:73], v[170:173], v[214:217], v[70:73]
	v_mfma_f32_16x16x32_bf16 v[70:73], v[174:177], v[218:221], v[70:73]
	v_mfma_f32_16x16x32_bf16 v[66:69], v[178:181], v[214:217], v[66:69]
	v_mfma_f32_16x16x32_bf16 v[66:69], v[182:185], v[218:221], v[66:69]
	s_setprio 0
	s_barrier
	s_mov_b32 m0, vcc_hi
	v_lshl_add_u64 v[198:199], s[70:71], 0, v[132:133]
	ds_read_b128 v[186:189], v149 offset:16384
	ds_read_b128 v[190:193], v149 offset:17408
	ds_read_b128 v[194:197], v149 offset:18432
	ds_read_b128 v[202:205], v149 offset:19456
	ds_read_b128 v[206:209], v149 offset:20480
	ds_read_b128 v[210:213], v149 offset:21504
	ds_read_b128 v[214:217], v149 offset:22528
	ds_read_b128 v[218:221], v149 offset:23552
	global_load_lds_dwordx4 v[198:199], off
	v_lshl_add_u64 v[222:223], s[70:71], 0, v[136:137]
	s_mov_b32 m0, s96
	v_lshl_add_u64 v[224:225], s[72:73], 0, v[132:133]
	global_load_lds_dwordx4 v[222:223], off
	s_mov_b32 m0, vcc_lo
	v_lshl_add_u64 v[226:227], s[68:69], 0, v[134:135]
	global_load_lds_dwordx4 v[224:225], off
	v_lshl_add_u64 v[224:225], s[72:73], 0, v[136:137]
	s_mov_b32 m0, s97
	s_nop 0
	global_load_lds_dwordx4 v[224:225], off
	v_lshl_add_u64 v[224:225], s[68:69], 0, v[130:131]
	s_mov_b32 m0, s36
	s_nop 0
	global_load_lds_dwordx4 v[224:225], off
	s_mov_b32 m0, s55
	s_nop 0
	global_load_lds_dwordx4 v[226:227], off
	s_waitcnt vmcnt(8)
	s_waitcnt lgkmcnt(0)
	s_barrier
	s_setprio 1
	s_waitcnt lgkmcnt(0)
	v_mfma_f32_16x16x32_bf16 v[62:65], v[150:153], v[186:189], v[62:65]
	v_mfma_f32_16x16x32_bf16 v[62:65], v[154:157], v[190:193], v[62:65]
	v_mfma_f32_16x16x32_bf16 v[58:61], v[158:161], v[186:189], v[58:61]
	v_mfma_f32_16x16x32_bf16 v[58:61], v[166:169], v[190:193], v[58:61]
	v_mfma_f32_16x16x32_bf16 v[54:57], v[150:153], v[194:197], v[54:57]
	v_mfma_f32_16x16x32_bf16 v[54:57], v[154:157], v[202:205], v[54:57]
	v_mfma_f32_16x16x32_bf16 v[46:49], v[158:161], v[194:197], v[46:49]
	v_mfma_f32_16x16x32_bf16 v[46:49], v[166:169], v[202:205], v[46:49]
	v_mfma_f32_16x16x32_bf16 v[38:41], v[150:153], v[206:209], v[38:41]
	v_mfma_f32_16x16x32_bf16 v[38:41], v[154:157], v[210:213], v[38:41]
	v_mfma_f32_16x16x32_bf16 v[30:33], v[158:161], v[206:209], v[30:33]
	v_mfma_f32_16x16x32_bf16 v[30:33], v[166:169], v[210:213], v[30:33]
	v_mfma_f32_16x16x32_bf16 v[22:25], v[150:153], v[214:217], v[22:25]
	v_mfma_f32_16x16x32_bf16 v[22:25], v[154:157], v[218:221], v[22:25]
	v_mfma_f32_16x16x32_bf16 v[14:17], v[158:161], v[214:217], v[14:17]
	v_mfma_f32_16x16x32_bf16 v[14:17], v[166:169], v[218:221], v[14:17]
	s_setprio 0
	s_setprio 1
	v_mfma_f32_16x16x32_bf16 v[50:53], v[170:173], v[186:189], v[50:53]
	v_mfma_f32_16x16x32_bf16 v[50:53], v[174:177], v[190:193], v[50:53]
	v_mfma_f32_16x16x32_bf16 v[42:45], v[178:181], v[186:189], v[42:45]
	v_mfma_f32_16x16x32_bf16 v[42:45], v[182:185], v[190:193], v[42:45]
	v_mfma_f32_16x16x32_bf16 v[34:37], v[170:173], v[194:197], v[34:37]
	v_mfma_f32_16x16x32_bf16 v[34:37], v[174:177], v[202:205], v[34:37]
	v_mfma_f32_16x16x32_bf16 v[26:29], v[178:181], v[194:197], v[26:29]
	v_mfma_f32_16x16x32_bf16 v[26:29], v[182:185], v[202:205], v[26:29]
	v_mfma_f32_16x16x32_bf16 v[18:21], v[170:173], v[206:209], v[18:21]
	v_mfma_f32_16x16x32_bf16 v[18:21], v[174:177], v[210:213], v[18:21]
	v_mfma_f32_16x16x32_bf16 v[10:13], v[178:181], v[206:209], v[10:13]
	v_mfma_f32_16x16x32_bf16 v[10:13], v[182:185], v[210:213], v[10:13]
	v_mfma_f32_16x16x32_bf16 v[6:9], v[170:173], v[214:217], v[6:9]
	v_mfma_f32_16x16x32_bf16 v[6:9], v[174:177], v[218:221], v[6:9]
	v_mfma_f32_16x16x32_bf16 v[2:5], v[178:181], v[214:217], v[2:5]
	v_mfma_f32_16x16x32_bf16 v[2:5], v[182:185], v[218:221], v[2:5]
	s_setprio 0
	s_barrier
	v_add_u32_e32 v166, s95, v145
	v_add_u32_e32 v182, s94, v145
	ds_read_b128 v[150:153], v166
	ds_read_b128 v[154:157], v166 offset:1024
	ds_read_b128 v[158:161], v166 offset:2048
	ds_read_b128 v[166:169], v166 offset:3072
	ds_read_b128 v[170:173], v182
	ds_read_b128 v[174:177], v182 offset:1024
	ds_read_b128 v[178:181], v182 offset:2048
	ds_read_b128 v[182:185], v182 offset:3072
	s_mov_b32 m0, s76
	v_lshl_add_u64 v[228:229], s[66:67], 0, v[130:131]
	ds_read_b128 v[186:189], v149 offset:32768
	ds_read_b128 v[190:193], v149 offset:33792
	ds_read_b128 v[194:197], v149 offset:34816
	ds_read_b128 v[202:205], v149 offset:35840
	ds_read_b128 v[206:209], v149 offset:36864
	ds_read_b128 v[210:213], v149 offset:37888
	ds_read_b128 v[214:217], v149 offset:38912
	ds_read_b128 v[218:221], v149 offset:39936
	global_load_lds_dwordx4 v[228:229], off
	v_lshl_add_u64 v[228:229], s[66:67], 0, v[134:135]
	s_mov_b32 m0, s77
	s_nop 0
	global_load_lds_dwordx4 v[228:229], off
	s_waitcnt vmcnt(8)
	s_waitcnt lgkmcnt(0)
	s_barrier
	s_setprio 1
	s_waitcnt lgkmcnt(0)
	v_mfma_f32_16x16x32_bf16 v[126:129], v[150:153], v[186:189], v[126:129]
	v_mfma_f32_16x16x32_bf16 v[126:129], v[154:157], v[190:193], v[126:129]
	v_mfma_f32_16x16x32_bf16 v[122:125], v[158:161], v[186:189], v[122:125]
	v_mfma_f32_16x16x32_bf16 v[122:125], v[166:169], v[190:193], v[122:125]
	v_mfma_f32_16x16x32_bf16 v[118:121], v[150:153], v[194:197], v[118:121]
	v_mfma_f32_16x16x32_bf16 v[118:121], v[154:157], v[202:205], v[118:121]
	v_mfma_f32_16x16x32_bf16 v[110:113], v[158:161], v[194:197], v[110:113]
	v_mfma_f32_16x16x32_bf16 v[110:113], v[166:169], v[202:205], v[110:113]
	v_mfma_f32_16x16x32_bf16 v[102:105], v[150:153], v[206:209], v[102:105]
	v_mfma_f32_16x16x32_bf16 v[102:105], v[154:157], v[210:213], v[102:105]
	v_mfma_f32_16x16x32_bf16 v[94:97], v[158:161], v[206:209], v[94:97]
	v_mfma_f32_16x16x32_bf16 v[94:97], v[166:169], v[210:213], v[94:97]
	v_mfma_f32_16x16x32_bf16 v[86:89], v[150:153], v[214:217], v[86:89]
	v_mfma_f32_16x16x32_bf16 v[86:89], v[154:157], v[218:221], v[86:89]
	v_mfma_f32_16x16x32_bf16 v[78:81], v[158:161], v[214:217], v[78:81]
	v_mfma_f32_16x16x32_bf16 v[78:81], v[166:169], v[218:221], v[78:81]
	s_setprio 0
	s_setprio 1
	v_mfma_f32_16x16x32_bf16 v[114:117], v[170:173], v[186:189], v[114:117]
	v_mfma_f32_16x16x32_bf16 v[114:117], v[174:177], v[190:193], v[114:117]
	v_mfma_f32_16x16x32_bf16 v[106:109], v[178:181], v[186:189], v[106:109]
	v_mfma_f32_16x16x32_bf16 v[106:109], v[182:185], v[190:193], v[106:109]
	v_mfma_f32_16x16x32_bf16 v[98:101], v[170:173], v[194:197], v[98:101]
	v_mfma_f32_16x16x32_bf16 v[98:101], v[174:177], v[202:205], v[98:101]
	v_mfma_f32_16x16x32_bf16 v[90:93], v[178:181], v[194:197], v[90:93]
	v_mfma_f32_16x16x32_bf16 v[90:93], v[182:185], v[202:205], v[90:93]
	v_mfma_f32_16x16x32_bf16 v[82:85], v[170:173], v[206:209], v[82:85]
	v_mfma_f32_16x16x32_bf16 v[82:85], v[174:177], v[210:213], v[82:85]
	v_mfma_f32_16x16x32_bf16 v[74:77], v[178:181], v[206:209], v[74:77]
	v_mfma_f32_16x16x32_bf16 v[74:77], v[182:185], v[210:213], v[74:77]
	v_mfma_f32_16x16x32_bf16 v[70:73], v[170:173], v[214:217], v[70:73]
	v_mfma_f32_16x16x32_bf16 v[70:73], v[174:177], v[218:221], v[70:73]
	v_mfma_f32_16x16x32_bf16 v[66:69], v[178:181], v[214:217], v[66:69]
	v_mfma_f32_16x16x32_bf16 v[66:69], v[182:185], v[218:221], v[66:69]
	s_setprio 0
	s_barrier
	s_mov_b32 m0, s93
	v_lshl_add_u64 v[198:199], v[198:199], 0, s[10:11]
	ds_read_b128 v[186:189], v149 offset:49152
	ds_read_b128 v[190:193], v149 offset:50176
	ds_read_b128 v[194:197], v149 offset:51200
	ds_read_b128 v[202:205], v149 offset:52224
	ds_read_b128 v[206:209], v149 offset:53248
	ds_read_b128 v[210:213], v149 offset:54272
	ds_read_b128 v[214:217], v149 offset:55296
	ds_read_b128 v[218:221], v149 offset:56320
	global_load_lds_dwordx4 v[198:199], off
	v_lshl_add_u64 v[198:199], v[222:223], 0, s[10:11]
	s_mov_b32 m0, s89
	s_nop 0
	global_load_lds_dwordx4 v[198:199], off
	v_lshl_add_u64 v[198:199], s[64:65], 0, v[132:133]
	s_mov_b32 m0, s92
	s_nop 0
	global_load_lds_dwordx4 v[198:199], off
	v_lshl_add_u64 v[198:199], s[64:65], 0, v[136:137]
	s_mov_b32 m0, s44
	s_nop 0
	global_load_lds_dwordx4 v[198:199], off
	v_lshl_add_u64 v[198:199], v[224:225], 0, s[10:11]
	s_mov_b32 m0, s79
	s_nop 0
	global_load_lds_dwordx4 v[198:199], off
	v_lshl_add_u64 v[198:199], v[226:227], 0, s[10:11]
	s_mov_b32 m0, s80
	s_nop 0
	global_load_lds_dwordx4 v[198:199], off
	s_waitcnt vmcnt(8)
	s_waitcnt lgkmcnt(0)
	s_barrier
	s_setprio 1
	s_waitcnt lgkmcnt(0)
	v_mfma_f32_16x16x32_bf16 v[62:65], v[150:153], v[186:189], v[62:65]
	v_mfma_f32_16x16x32_bf16 v[62:65], v[154:157], v[190:193], v[62:65]
	v_mfma_f32_16x16x32_bf16 v[58:61], v[158:161], v[186:189], v[58:61]
	v_mfma_f32_16x16x32_bf16 v[58:61], v[166:169], v[190:193], v[58:61]
	v_mfma_f32_16x16x32_bf16 v[54:57], v[150:153], v[194:197], v[54:57]
	v_mfma_f32_16x16x32_bf16 v[54:57], v[154:157], v[202:205], v[54:57]
	v_mfma_f32_16x16x32_bf16 v[46:49], v[158:161], v[194:197], v[46:49]
	v_mfma_f32_16x16x32_bf16 v[46:49], v[166:169], v[202:205], v[46:49]
	v_mfma_f32_16x16x32_bf16 v[38:41], v[150:153], v[206:209], v[38:41]
	v_mfma_f32_16x16x32_bf16 v[38:41], v[154:157], v[210:213], v[38:41]
	v_mfma_f32_16x16x32_bf16 v[30:33], v[158:161], v[206:209], v[30:33]
	v_mfma_f32_16x16x32_bf16 v[30:33], v[166:169], v[210:213], v[30:33]
	v_mfma_f32_16x16x32_bf16 v[22:25], v[150:153], v[214:217], v[22:25]
	v_mfma_f32_16x16x32_bf16 v[22:25], v[154:157], v[218:221], v[22:25]
	v_mfma_f32_16x16x32_bf16 v[14:17], v[158:161], v[214:217], v[14:17]
	v_mfma_f32_16x16x32_bf16 v[14:17], v[166:169], v[218:221], v[14:17]
	s_setprio 0
	s_setprio 1
	v_mfma_f32_16x16x32_bf16 v[50:53], v[170:173], v[186:189], v[50:53]
	v_mfma_f32_16x16x32_bf16 v[50:53], v[174:177], v[190:193], v[50:53]
	v_mfma_f32_16x16x32_bf16 v[42:45], v[178:181], v[186:189], v[42:45]
	v_mfma_f32_16x16x32_bf16 v[42:45], v[182:185], v[190:193], v[42:45]
	v_mfma_f32_16x16x32_bf16 v[34:37], v[170:173], v[194:197], v[34:37]
	v_mfma_f32_16x16x32_bf16 v[34:37], v[174:177], v[202:205], v[34:37]
	v_mfma_f32_16x16x32_bf16 v[26:29], v[178:181], v[194:197], v[26:29]
	v_mfma_f32_16x16x32_bf16 v[26:29], v[182:185], v[202:205], v[26:29]
	v_mfma_f32_16x16x32_bf16 v[18:21], v[170:173], v[206:209], v[18:21]
	v_mfma_f32_16x16x32_bf16 v[18:21], v[174:177], v[210:213], v[18:21]
	v_mfma_f32_16x16x32_bf16 v[10:13], v[178:181], v[206:209], v[10:13]
	v_mfma_f32_16x16x32_bf16 v[10:13], v[182:185], v[210:213], v[10:13]
	v_mfma_f32_16x16x32_bf16 v[6:9], v[170:173], v[214:217], v[6:9]
	v_mfma_f32_16x16x32_bf16 v[6:9], v[174:177], v[218:221], v[6:9]
	v_mfma_f32_16x16x32_bf16 v[2:5], v[178:181], v[214:217], v[2:5]
	v_mfma_f32_16x16x32_bf16 v[2:5], v[182:185], v[218:221], v[2:5]
	s_setprio 0
	s_barrier
	s_movk_i32 s44, 0x100
	s_andn2_b64 vcc, exec, s[62:63]
	s_mov_b64 s[64:65], -1
	s_mov_b64 s[62:63], 0
	s_cbranch_vccz .LBB0_706
	s_and_b64 vcc, exec, s[12:13]
	s_cbranch_vccz .LBB0_709
	s_barrier

.LBB0_722:
	s_add_u32 s36, s56, s44
	s_addc_u32 s37, s57, 0
	s_add_u32 s66, s36, 0x100
	s_addc_u32 s67, s37, 0
	s_and_b64 s[64:65], s[62:63], exec
	s_cselect_b32 s67, s17, s67
	s_cselect_b32 s66, s83, s66
	s_add_u32 s44, s54, s44
	s_addc_u32 s64, s55, 0
	s_add_u32 s44, s44, 0x100
	s_addc_u32 s64, s64, 0
	s_and_b64 s[62:63], s[62:63], exec
	s_cselect_b32 s69, s15, s64
	s_cselect_b32 s68, s84, s44
	s_add_u32 s72, s36, 0x10080
	s_addc_u32 s73, s37, 0
	s_add_i32 s96, s79, s27
	ds_read_b128 v[148:151], v143
	ds_read_b128 v[152:155], v143 offset:1024
	ds_read_b128 v[156:159], v143 offset:2048
	ds_read_b128 v[166:169], v143 offset:3072
	ds_read_b128 v[170:173], v145
	ds_read_b128 v[174:177], v145 offset:1024
	ds_read_b128 v[178:181], v145 offset:2048
	ds_read_b128 v[182:185], v145 offset:3072
	s_add_i32 m0, s43, 0xc000
	s_add_i32 s97, s43, 0xe000
	s_add_i32 s93, s96, 0x2000
	s_add_u32 s70, s68, 0x10000
	s_addc_u32 s71, s69, 0
	s_add_i32 s95, s80, s27
	s_add_i32 s94, s95, 0x2000
	s_add_i32 s92, 0, 0x18000
	s_add_i32 s89, 0, 0x1c000
	s_add_u32 s64, s66, 0x10000
	s_addc_u32 s65, s67, 0
	s_add_i32 s87, s92, s27
	s_add_i32 s85, s87, 0x2000
	s_add_u32 s62, s68, 0x10080
	s_addc_u32 s63, s69, 0
	s_add_i32 s86, s89, s27
	s_add_i32 s44, s86, 0x2000
	v_lshl_add_u64 v[160:161], s[72:73], 0, v[130:131]
	ds_read_b128 v[186:189], v146
	ds_read_b128 v[190:193], v146 offset:1024
	ds_read_b128 v[194:197], v146 offset:2048
	ds_read_b128 v[202:205], v146 offset:3072
	ds_read_b128 v[206:209], v146 offset:4096
	ds_read_b128 v[210:213], v146 offset:5120
	ds_read_b128 v[214:217], v146 offset:6144
	ds_read_b128 v[218:221], v146 offset:7168
	global_load_lds_dwordx4 v[160:161], off
	v_lshl_add_u64 v[160:161], s[72:73], 0, v[134:135]
	s_mov_b32 m0, s97
	s_nop 0
	global_load_lds_dwordx4 v[160:161], off
	s_waitcnt vmcnt(8)
	s_waitcnt lgkmcnt(0)
	s_barrier
	s_setprio 1
	s_waitcnt lgkmcnt(0)
	v_mfma_f32_16x16x32_bf16 v[126:129], v[148:151], v[186:189], v[126:129]
	v_mfma_f32_16x16x32_bf16 v[126:129], v[152:155], v[190:193], v[126:129]
	v_mfma_f32_16x16x32_bf16 v[122:125], v[156:159], v[186:189], v[122:125]
	v_mfma_f32_16x16x32_bf16 v[122:125], v[166:169], v[190:193], v[122:125]
	v_mfma_f32_16x16x32_bf16 v[118:121], v[148:151], v[194:197], v[118:121]
	v_mfma_f32_16x16x32_bf16 v[118:121], v[152:155], v[202:205], v[118:121]
	v_mfma_f32_16x16x32_bf16 v[110:113], v[156:159], v[194:197], v[110:113]
	v_mfma_f32_16x16x32_bf16 v[110:113], v[166:169], v[202:205], v[110:113]
	v_mfma_f32_16x16x32_bf16 v[102:105], v[148:151], v[206:209], v[102:105]
	v_mfma_f32_16x16x32_bf16 v[102:105], v[152:155], v[210:213], v[102:105]
	v_mfma_f32_16x16x32_bf16 v[94:97], v[156:159], v[206:209], v[94:97]
	v_mfma_f32_16x16x32_bf16 v[94:97], v[166:169], v[210:213], v[94:97]
	v_mfma_f32_16x16x32_bf16 v[86:89], v[148:151], v[214:217], v[86:89]
	v_mfma_f32_16x16x32_bf16 v[86:89], v[152:155], v[218:221], v[86:89]
	v_mfma_f32_16x16x32_bf16 v[78:81], v[156:159], v[214:217], v[78:81]
	v_mfma_f32_16x16x32_bf16 v[78:81], v[166:169], v[218:221], v[78:81]
	s_setprio 0
	s_setprio 1
	v_mfma_f32_16x16x32_bf16 v[114:117], v[170:173], v[186:189], v[114:117]
	v_mfma_f32_16x16x32_bf16 v[114:117], v[174:177], v[190:193], v[114:117]
	v_mfma_f32_16x16x32_bf16 v[106:109], v[178:181], v[186:189], v[106:109]
	v_mfma_f32_16x16x32_bf16 v[106:109], v[182:185], v[190:193], v[106:109]
	v_mfma_f32_16x16x32_bf16 v[98:101], v[170:173], v[194:197], v[98:101]
	v_mfma_f32_16x16x32_bf16 v[98:101], v[174:177], v[202:205], v[98:101]
	v_mfma_f32_16x16x32_bf16 v[90:93], v[178:181], v[194:197], v[90:93]
	v_mfma_f32_16x16x32_bf16 v[90:93], v[182:185], v[202:205], v[90:93]
	v_mfma_f32_16x16x32_bf16 v[82:85], v[170:173], v[206:209], v[82:85]
	v_mfma_f32_16x16x32_bf16 v[82:85], v[174:177], v[210:213], v[82:85]
	v_mfma_f32_16x16x32_bf16 v[74:77], v[178:181], v[206:209], v[74:77]
	v_mfma_f32_16x16x32_bf16 v[74:77], v[182:185], v[210:213], v[74:77]
	v_mfma_f32_16x16x32_bf16 v[70:73], v[170:173], v[214:217], v[70:73]
	v_mfma_f32_16x16x32_bf16 v[70:73], v[174:177], v[218:221], v[70:73]
	v_mfma_f32_16x16x32_bf16 v[66:69], v[178:181], v[214:217], v[66:69]
	v_mfma_f32_16x16x32_bf16 v[66:69], v[182:185], v[218:221], v[66:69]
	s_setprio 0
	s_barrier
	s_mov_b32 m0, s96
	v_lshl_add_u64 v[160:161], s[68:69], 0, v[132:133]
	ds_read_b128 v[186:189], v146 offset:16384
	ds_read_b128 v[190:193], v146 offset:17408
	ds_read_b128 v[194:197], v146 offset:18432
	ds_read_b128 v[202:205], v146 offset:19456
	ds_read_b128 v[206:209], v146 offset:20480
	ds_read_b128 v[210:213], v146 offset:21504
	ds_read_b128 v[214:217], v146 offset:22528
	ds_read_b128 v[218:221], v146 offset:23552
	global_load_lds_dwordx4 v[160:161], off
	v_lshl_add_u64 v[198:199], s[68:69], 0, v[136:137]
	s_mov_b32 m0, s93
	v_lshl_add_u64 v[222:223], s[70:71], 0, v[132:133]
	global_load_lds_dwordx4 v[198:199], off
	s_mov_b32 m0, s95
	v_lshl_add_u64 v[224:225], s[66:67], 0, v[134:135]
	global_load_lds_dwordx4 v[222:223], off
	v_lshl_add_u64 v[222:223], s[70:71], 0, v[136:137]
	s_mov_b32 m0, s94
	s_nop 0
	global_load_lds_dwordx4 v[222:223], off
	v_lshl_add_u64 v[222:223], s[66:67], 0, v[130:131]
	s_mov_b32 m0, s43
	s_nop 0
	global_load_lds_dwordx4 v[222:223], off
	s_mov_b32 m0, s45
	s_nop 0
	global_load_lds_dwordx4 v[224:225], off
	s_waitcnt vmcnt(8)
	s_waitcnt lgkmcnt(0)
	s_barrier
	s_setprio 1
	s_waitcnt lgkmcnt(0)
	v_mfma_f32_16x16x32_bf16 v[62:65], v[148:151], v[186:189], v[62:65]
	v_mfma_f32_16x16x32_bf16 v[62:65], v[152:155], v[190:193], v[62:65]
	v_mfma_f32_16x16x32_bf16 v[58:61], v[156:159], v[186:189], v[58:61]
	v_mfma_f32_16x16x32_bf16 v[58:61], v[166:169], v[190:193], v[58:61]
	v_mfma_f32_16x16x32_bf16 v[54:57], v[148:151], v[194:197], v[54:57]
	v_mfma_f32_16x16x32_bf16 v[54:57], v[152:155], v[202:205], v[54:57]
	v_mfma_f32_16x16x32_bf16 v[46:49], v[156:159], v[194:197], v[46:49]
	v_mfma_f32_16x16x32_bf16 v[46:49], v[166:169], v[202:205], v[46:49]
	v_mfma_f32_16x16x32_bf16 v[38:41], v[148:151], v[206:209], v[38:41]
	v_mfma_f32_16x16x32_bf16 v[38:41], v[152:155], v[210:213], v[38:41]
	v_mfma_f32_16x16x32_bf16 v[30:33], v[156:159], v[206:209], v[30:33]
	v_mfma_f32_16x16x32_bf16 v[30:33], v[166:169], v[210:213], v[30:33]
	v_mfma_f32_16x16x32_bf16 v[22:25], v[148:151], v[214:217], v[22:25]
	v_mfma_f32_16x16x32_bf16 v[22:25], v[152:155], v[218:221], v[22:25]
	v_mfma_f32_16x16x32_bf16 v[14:17], v[156:159], v[214:217], v[14:17]
	v_mfma_f32_16x16x32_bf16 v[14:17], v[166:169], v[218:221], v[14:17]
	s_setprio 0
	s_setprio 1
	v_mfma_f32_16x16x32_bf16 v[50:53], v[170:173], v[186:189], v[50:53]
	v_mfma_f32_16x16x32_bf16 v[50:53], v[174:177], v[190:193], v[50:53]
	v_mfma_f32_16x16x32_bf16 v[42:45], v[178:181], v[186:189], v[42:45]
	v_mfma_f32_16x16x32_bf16 v[42:45], v[182:185], v[190:193], v[42:45]
	v_mfma_f32_16x16x32_bf16 v[34:37], v[170:173], v[194:197], v[34:37]
	v_mfma_f32_16x16x32_bf16 v[34:37], v[174:177], v[202:205], v[34:37]
	v_mfma_f32_16x16x32_bf16 v[26:29], v[178:181], v[194:197], v[26:29]
	v_mfma_f32_16x16x32_bf16 v[26:29], v[182:185], v[202:205], v[26:29]
	v_mfma_f32_16x16x32_bf16 v[18:21], v[170:173], v[206:209], v[18:21]
	v_mfma_f32_16x16x32_bf16 v[18:21], v[174:177], v[210:213], v[18:21]
	v_mfma_f32_16x16x32_bf16 v[10:13], v[178:181], v[206:209], v[10:13]
	v_mfma_f32_16x16x32_bf16 v[10:13], v[182:185], v[210:213], v[10:13]
	v_mfma_f32_16x16x32_bf16 v[6:9], v[170:173], v[214:217], v[6:9]
	v_mfma_f32_16x16x32_bf16 v[6:9], v[174:177], v[218:221], v[6:9]
	v_mfma_f32_16x16x32_bf16 v[2:5], v[178:181], v[214:217], v[2:5]
	v_mfma_f32_16x16x32_bf16 v[2:5], v[182:185], v[218:221], v[2:5]
	s_setprio 0
	s_barrier
	v_add_u32_e32 v147, s92, v142
	ds_read_b128 v[148:151], v147
	ds_read_b128 v[152:155], v147 offset:1024
	ds_read_b128 v[156:159], v147 offset:2048
	ds_read_b128 v[166:169], v147 offset:3072
	v_add_u32_e32 v147, s89, v142
	ds_read_b128 v[170:173], v147
	ds_read_b128 v[174:177], v147 offset:1024
	ds_read_b128 v[178:181], v147 offset:2048
	ds_read_b128 v[182:185], v147 offset:3072
	s_mov_b32 m0, s49
	v_lshl_add_u64 v[226:227], s[64:65], 0, v[130:131]
	ds_read_b128 v[186:189], v146 offset:32768
	ds_read_b128 v[190:193], v146 offset:33792
	ds_read_b128 v[194:197], v146 offset:34816
	ds_read_b128 v[202:205], v146 offset:35840
	ds_read_b128 v[206:209], v146 offset:36864
	ds_read_b128 v[210:213], v146 offset:37888
	ds_read_b128 v[214:217], v146 offset:38912
	ds_read_b128 v[218:221], v146 offset:39936
	global_load_lds_dwordx4 v[226:227], off
	v_lshl_add_u64 v[226:227], s[64:65], 0, v[134:135]
	s_mov_b32 m0, s74
	s_nop 0
	global_load_lds_dwordx4 v[226:227], off
	s_waitcnt vmcnt(8)
	s_waitcnt lgkmcnt(0)
	s_barrier
	s_setprio 1
	s_waitcnt lgkmcnt(0)
	v_mfma_f32_16x16x32_bf16 v[126:129], v[148:151], v[186:189], v[126:129]
	v_mfma_f32_16x16x32_bf16 v[126:129], v[152:155], v[190:193], v[126:129]
	v_mfma_f32_16x16x32_bf16 v[122:125], v[156:159], v[186:189], v[122:125]
	v_mfma_f32_16x16x32_bf16 v[122:125], v[166:169], v[190:193], v[122:125]
	v_mfma_f32_16x16x32_bf16 v[118:121], v[148:151], v[194:197], v[118:121]
	v_mfma_f32_16x16x32_bf16 v[118:121], v[152:155], v[202:205], v[118:121]
	v_mfma_f32_16x16x32_bf16 v[110:113], v[156:159], v[194:197], v[110:113]
	v_mfma_f32_16x16x32_bf16 v[110:113], v[166:169], v[202:205], v[110:113]
	v_mfma_f32_16x16x32_bf16 v[102:105], v[148:151], v[206:209], v[102:105]
	v_mfma_f32_16x16x32_bf16 v[102:105], v[152:155], v[210:213], v[102:105]
	v_mfma_f32_16x16x32_bf16 v[94:97], v[156:159], v[206:209], v[94:97]
	v_mfma_f32_16x16x32_bf16 v[94:97], v[166:169], v[210:213], v[94:97]
	v_mfma_f32_16x16x32_bf16 v[86:89], v[148:151], v[214:217], v[86:89]
	v_mfma_f32_16x16x32_bf16 v[86:89], v[152:155], v[218:221], v[86:89]
	v_mfma_f32_16x16x32_bf16 v[78:81], v[156:159], v[214:217], v[78:81]
	v_mfma_f32_16x16x32_bf16 v[78:81], v[166:169], v[218:221], v[78:81]
	s_setprio 0
	s_setprio 1
	v_mfma_f32_16x16x32_bf16 v[114:117], v[170:173], v[186:189], v[114:117]
	v_mfma_f32_16x16x32_bf16 v[114:117], v[174:177], v[190:193], v[114:117]
	v_mfma_f32_16x16x32_bf16 v[106:109], v[178:181], v[186:189], v[106:109]
	v_mfma_f32_16x16x32_bf16 v[106:109], v[182:185], v[190:193], v[106:109]
	v_mfma_f32_16x16x32_bf16 v[98:101], v[170:173], v[194:197], v[98:101]
	v_mfma_f32_16x16x32_bf16 v[98:101], v[174:177], v[202:205], v[98:101]
	v_mfma_f32_16x16x32_bf16 v[90:93], v[178:181], v[194:197], v[90:93]
	v_mfma_f32_16x16x32_bf16 v[90:93], v[182:185], v[202:205], v[90:93]
	v_mfma_f32_16x16x32_bf16 v[82:85], v[170:173], v[206:209], v[82:85]
	v_mfma_f32_16x16x32_bf16 v[82:85], v[174:177], v[210:213], v[82:85]
	v_mfma_f32_16x16x32_bf16 v[74:77], v[178:181], v[206:209], v[74:77]
	v_mfma_f32_16x16x32_bf16 v[74:77], v[182:185], v[210:213], v[74:77]
	v_mfma_f32_16x16x32_bf16 v[70:73], v[170:173], v[214:217], v[70:73]
	v_mfma_f32_16x16x32_bf16 v[70:73], v[174:177], v[218:221], v[70:73]
	v_mfma_f32_16x16x32_bf16 v[66:69], v[178:181], v[214:217], v[66:69]
	v_mfma_f32_16x16x32_bf16 v[66:69], v[182:185], v[218:221], v[66:69]
	s_setprio 0
	s_barrier
	s_mov_b32 m0, s87
	v_lshl_add_u64 v[160:161], v[160:161], 0, s[10:11]
	ds_read_b128 v[186:189], v146 offset:49152
	ds_read_b128 v[190:193], v146 offset:50176
	ds_read_b128 v[194:197], v146 offset:51200
	ds_read_b128 v[202:205], v146 offset:52224
	ds_read_b128 v[206:209], v146 offset:53248
	ds_read_b128 v[210:213], v146 offset:54272
	ds_read_b128 v[214:217], v146 offset:55296
	ds_read_b128 v[218:221], v146 offset:56320
	global_load_lds_dwordx4 v[160:161], off
	v_lshl_add_u64 v[160:161], v[198:199], 0, s[10:11]
	s_mov_b32 m0, s85
	s_nop 0
	global_load_lds_dwordx4 v[160:161], off
	v_lshl_add_u64 v[160:161], s[62:63], 0, v[132:133]
	s_mov_b32 m0, s86
	s_nop 0
	global_load_lds_dwordx4 v[160:161], off
	v_lshl_add_u64 v[160:161], s[62:63], 0, v[136:137]
	s_mov_b32 m0, s44
	s_nop 0
	global_load_lds_dwordx4 v[160:161], off
	v_lshl_add_u64 v[160:161], v[222:223], 0, s[10:11]
	s_mov_b32 m0, s76
	s_nop 0
	global_load_lds_dwordx4 v[160:161], off
	v_lshl_add_u64 v[160:161], v[224:225], 0, s[10:11]
	s_mov_b32 m0, s77
	s_nop 0
	global_load_lds_dwordx4 v[160:161], off
	s_waitcnt vmcnt(8)
	s_waitcnt lgkmcnt(0)
	s_barrier
	s_setprio 1
	s_waitcnt lgkmcnt(0)
	v_mfma_f32_16x16x32_bf16 v[62:65], v[148:151], v[186:189], v[62:65]
	v_mfma_f32_16x16x32_bf16 v[62:65], v[152:155], v[190:193], v[62:65]
	v_mfma_f32_16x16x32_bf16 v[58:61], v[156:159], v[186:189], v[58:61]
	v_mfma_f32_16x16x32_bf16 v[58:61], v[166:169], v[190:193], v[58:61]
	v_mfma_f32_16x16x32_bf16 v[54:57], v[148:151], v[194:197], v[54:57]
	v_mfma_f32_16x16x32_bf16 v[54:57], v[152:155], v[202:205], v[54:57]
	v_mfma_f32_16x16x32_bf16 v[46:49], v[156:159], v[194:197], v[46:49]
	v_mfma_f32_16x16x32_bf16 v[46:49], v[166:169], v[202:205], v[46:49]
	v_mfma_f32_16x16x32_bf16 v[38:41], v[148:151], v[206:209], v[38:41]
	v_mfma_f32_16x16x32_bf16 v[38:41], v[152:155], v[210:213], v[38:41]
	v_mfma_f32_16x16x32_bf16 v[30:33], v[156:159], v[206:209], v[30:33]
	v_mfma_f32_16x16x32_bf16 v[30:33], v[166:169], v[210:213], v[30:33]
	v_mfma_f32_16x16x32_bf16 v[22:25], v[148:151], v[214:217], v[22:25]
	v_mfma_f32_16x16x32_bf16 v[22:25], v[152:155], v[218:221], v[22:25]
	v_mfma_f32_16x16x32_bf16 v[14:17], v[156:159], v[214:217], v[14:17]
	v_mfma_f32_16x16x32_bf16 v[14:17], v[166:169], v[218:221], v[14:17]
	s_setprio 0
	s_setprio 1
	v_mfma_f32_16x16x32_bf16 v[50:53], v[170:173], v[186:189], v[50:53]
	v_mfma_f32_16x16x32_bf16 v[50:53], v[174:177], v[190:193], v[50:53]
	v_mfma_f32_16x16x32_bf16 v[42:45], v[178:181], v[186:189], v[42:45]
	v_mfma_f32_16x16x32_bf16 v[42:45], v[182:185], v[190:193], v[42:45]
	v_mfma_f32_16x16x32_bf16 v[34:37], v[170:173], v[194:197], v[34:37]
	v_mfma_f32_16x16x32_bf16 v[34:37], v[174:177], v[202:205], v[34:37]
	v_mfma_f32_16x16x32_bf16 v[26:29], v[178:181], v[194:197], v[26:29]
	v_mfma_f32_16x16x32_bf16 v[26:29], v[182:185], v[202:205], v[26:29]
	v_mfma_f32_16x16x32_bf16 v[18:21], v[170:173], v[206:209], v[18:21]
	v_mfma_f32_16x16x32_bf16 v[18:21], v[174:177], v[210:213], v[18:21]
	v_mfma_f32_16x16x32_bf16 v[10:13], v[178:181], v[206:209], v[10:13]
	v_mfma_f32_16x16x32_bf16 v[10:13], v[182:185], v[210:213], v[10:13]
	v_mfma_f32_16x16x32_bf16 v[6:9], v[170:173], v[214:217], v[6:9]
	v_mfma_f32_16x16x32_bf16 v[6:9], v[174:177], v[218:221], v[6:9]
	v_mfma_f32_16x16x32_bf16 v[2:5], v[178:181], v[214:217], v[2:5]
	v_mfma_f32_16x16x32_bf16 v[2:5], v[182:185], v[218:221], v[2:5]
	s_setprio 0
	s_barrier
	s_movk_i32 s44, 0x100
	s_andn2_b64 vcc, exec, s[60:61]
	s_mov_b64 s[62:63], -1
	s_mov_b64 s[60:61], 0
	s_cbranch_vccz .LBB0_722
	s_and_b64 vcc, exec, s[12:13]
	s_cbranch_vccz .LBB0_725
	s_barrier

.LBB0_1226:
	v_add_u32_e32 v3, s71, v165
	ds_read_b128 v[150:153], v3
	ds_read_b128 v[154:157], v3 offset:1024
	ds_read_b128 v[158:161], v3 offset:2048
	ds_read_b128 v[170:173], v3 offset:3072
	v_add_u32_e32 v3, s72, v165
	ds_read_b128 v[174:177], v3
	ds_read_b128 v[178:181], v3 offset:1024
	ds_read_b128 v[182:185], v3 offset:2048
	ds_read_b128 v[186:189], v3 offset:3072
	s_add_u32 s36, s52, 0xfff80080
	s_addc_u32 s37, s53, -1
	s_cmp_eq_u32 s78, 28
	s_cselect_b32 s59, s21, s37
	s_cselect_b32 s58, s44, s36
	s_cselect_b32 s57, s19, s77
	s_cselect_b32 s56, s55, s76
	v_lshl_add_u64 v[4:5], s[52:53], 0, v[142:143]
	s_add_i32 m0, s63, 0xc000
	ds_read_b128 v[190:193], v169
	ds_read_b128 v[194:197], v169 offset:1024
	ds_read_b128 v[202:205], v169 offset:2048
	ds_read_b128 v[206:209], v169 offset:3072
	ds_read_b128 v[210:213], v169 offset:4096
	ds_read_b128 v[214:217], v169 offset:5120
	ds_read_b128 v[218:221], v169 offset:6144
	ds_read_b128 v[222:225], v169 offset:7168
	global_load_lds_dwordx4 v[4:5], off
	v_lshl_add_u64 v[4:5], s[52:53], 0, v[144:145]
	s_add_i32 m0, s63, 0xe000
	s_nop 0
	global_load_lds_dwordx4 v[4:5], off
	s_waitcnt vmcnt(8)
	s_waitcnt lgkmcnt(0)
	s_barrier
	s_setprio 1
	s_waitcnt lgkmcnt(0)
	v_mfma_f32_16x16x32_bf16 v[130:133], v[150:153], v[190:193], v[130:133]
	v_mfma_f32_16x16x32_bf16 v[130:133], v[154:157], v[194:197], v[130:133]
	v_mfma_f32_16x16x32_bf16 v[126:129], v[158:161], v[190:193], v[126:129]
	v_mfma_f32_16x16x32_bf16 v[126:129], v[170:173], v[194:197], v[126:129]
	v_mfma_f32_16x16x32_bf16 v[122:125], v[150:153], v[202:205], v[122:125]
	v_mfma_f32_16x16x32_bf16 v[122:125], v[154:157], v[206:209], v[122:125]
	v_mfma_f32_16x16x32_bf16 v[118:121], v[158:161], v[202:205], v[118:121]
	v_mfma_f32_16x16x32_bf16 v[118:121], v[170:173], v[206:209], v[118:121]
	v_mfma_f32_16x16x32_bf16 v[114:117], v[150:153], v[210:213], v[114:117]
	v_mfma_f32_16x16x32_bf16 v[114:117], v[154:157], v[214:217], v[114:117]
	v_mfma_f32_16x16x32_bf16 v[110:113], v[158:161], v[210:213], v[110:113]
	v_mfma_f32_16x16x32_bf16 v[110:113], v[170:173], v[214:217], v[110:113]
	v_mfma_f32_16x16x32_bf16 v[106:109], v[150:153], v[218:221], v[106:109]
	v_mfma_f32_16x16x32_bf16 v[106:109], v[154:157], v[222:225], v[106:109]
	v_mfma_f32_16x16x32_bf16 v[102:105], v[158:161], v[218:221], v[102:105]
	v_mfma_f32_16x16x32_bf16 v[102:105], v[170:173], v[222:225], v[102:105]
	s_setprio 0
	s_setprio 1
	v_mfma_f32_16x16x32_bf16 v[98:101], v[174:177], v[190:193], v[98:101]
	v_mfma_f32_16x16x32_bf16 v[98:101], v[178:181], v[194:197], v[98:101]
	v_mfma_f32_16x16x32_bf16 v[94:97], v[182:185], v[190:193], v[94:97]
	v_mfma_f32_16x16x32_bf16 v[94:97], v[186:189], v[194:197], v[94:97]
	v_mfma_f32_16x16x32_bf16 v[90:93], v[174:177], v[202:205], v[90:93]
	v_mfma_f32_16x16x32_bf16 v[90:93], v[178:181], v[206:209], v[90:93]
	v_mfma_f32_16x16x32_bf16 v[86:89], v[182:185], v[202:205], v[86:89]
	v_mfma_f32_16x16x32_bf16 v[86:89], v[186:189], v[206:209], v[86:89]
	v_mfma_f32_16x16x32_bf16 v[82:85], v[174:177], v[210:213], v[82:85]
	v_mfma_f32_16x16x32_bf16 v[82:85], v[178:181], v[214:217], v[82:85]
	v_mfma_f32_16x16x32_bf16 v[78:81], v[182:185], v[210:213], v[78:81]
	v_mfma_f32_16x16x32_bf16 v[78:81], v[186:189], v[214:217], v[78:81]
	v_mfma_f32_16x16x32_bf16 v[74:77], v[174:177], v[218:221], v[74:77]
	v_mfma_f32_16x16x32_bf16 v[74:77], v[178:181], v[222:225], v[74:77]
	v_mfma_f32_16x16x32_bf16 v[70:73], v[182:185], v[218:221], v[70:73]
	v_mfma_f32_16x16x32_bf16 v[70:73], v[186:189], v[222:225], v[70:73]
	s_setprio 0
	s_barrier
	s_add_i32 s36, s71, s43
	v_lshl_add_u64 v[166:167], s[56:57], 0, v[138:139]
	s_mov_b32 m0, s36
	ds_read_b128 v[190:193], v169 offset:16384
	ds_read_b128 v[194:197], v169 offset:17408
	ds_read_b128 v[202:205], v169 offset:18432
	ds_read_b128 v[206:209], v169 offset:19456
	ds_read_b128 v[210:213], v169 offset:20480
	ds_read_b128 v[214:217], v169 offset:21504
	ds_read_b128 v[218:221], v169 offset:22528
	ds_read_b128 v[222:225], v169 offset:23552
	global_load_lds_dwordx4 v[166:167], off
	s_add_i32 m0, s36, 0x2000
	s_add_u32 s80, s56, 0x80000
	v_lshl_add_u64 v[198:199], s[56:57], 0, v[134:135]
	s_addc_u32 s81, s57, 0
	s_add_i32 s36, s72, s43
	global_load_lds_dwordx4 v[198:199], off
	v_lshl_add_u64 v[4:5], s[80:81], 0, v[138:139]
	s_mov_b32 m0, s36
	v_lshl_add_u64 v[226:227], s[58:59], 0, v[140:141]
	global_load_lds_dwordx4 v[4:5], off
	v_lshl_add_u64 v[4:5], s[80:81], 0, v[134:135]
	s_add_i32 m0, s36, 0x2000
	v_lshl_add_u64 v[228:229], s[58:59], 0, v[136:137]
	global_load_lds_dwordx4 v[4:5], off
	s_mov_b32 m0, s63
	s_nop 0
	global_load_lds_dwordx4 v[226:227], off
	s_mov_b32 m0, s64
	s_nop 0
	global_load_lds_dwordx4 v[228:229], off
	s_waitcnt vmcnt(8)
	s_waitcnt lgkmcnt(0)
	s_barrier
	s_setprio 1
	s_waitcnt lgkmcnt(0)
	v_mfma_f32_16x16x32_bf16 v[66:69], v[150:153], v[190:193], v[66:69]
	v_mfma_f32_16x16x32_bf16 v[66:69], v[154:157], v[194:197], v[66:69]
	v_mfma_f32_16x16x32_bf16 v[62:65], v[158:161], v[190:193], v[62:65]
	v_mfma_f32_16x16x32_bf16 v[62:65], v[170:173], v[194:197], v[62:65]
	v_mfma_f32_16x16x32_bf16 v[58:61], v[150:153], v[202:205], v[58:61]
	v_mfma_f32_16x16x32_bf16 v[58:61], v[154:157], v[206:209], v[58:61]
	v_mfma_f32_16x16x32_bf16 v[54:57], v[158:161], v[202:205], v[54:57]
	v_mfma_f32_16x16x32_bf16 v[54:57], v[170:173], v[206:209], v[54:57]
	v_mfma_f32_16x16x32_bf16 v[50:53], v[150:153], v[210:213], v[50:53]
	v_mfma_f32_16x16x32_bf16 v[50:53], v[154:157], v[214:217], v[50:53]
	v_mfma_f32_16x16x32_bf16 v[46:49], v[158:161], v[210:213], v[46:49]
	v_mfma_f32_16x16x32_bf16 v[46:49], v[170:173], v[214:217], v[46:49]
	v_mfma_f32_16x16x32_bf16 v[42:45], v[150:153], v[218:221], v[42:45]
	v_mfma_f32_16x16x32_bf16 v[42:45], v[154:157], v[222:225], v[42:45]
	v_mfma_f32_16x16x32_bf16 v[38:41], v[158:161], v[218:221], v[38:41]
	v_mfma_f32_16x16x32_bf16 v[38:41], v[170:173], v[222:225], v[38:41]
	s_setprio 0
	s_setprio 1
	v_mfma_f32_16x16x32_bf16 v[34:37], v[174:177], v[190:193], v[34:37]
	v_mfma_f32_16x16x32_bf16 v[30:33], v[182:185], v[190:193], v[30:33]
	v_mfma_f32_16x16x32_bf16 v[26:29], v[174:177], v[202:205], v[26:29]
	v_mfma_f32_16x16x32_bf16 v[22:25], v[182:185], v[202:205], v[22:25]
	v_mfma_f32_16x16x32_bf16 v[18:21], v[174:177], v[210:213], v[18:21]
	v_mfma_f32_16x16x32_bf16 v[14:17], v[182:185], v[210:213], v[14:17]
	v_mfma_f32_16x16x32_bf16 v[10:13], v[174:177], v[218:221], v[10:13]
	v_mfma_f32_16x16x32_bf16 v[4:7], v[182:185], v[218:221], v[6:9]
	v_mfma_f32_16x16x32_bf16 v[34:37], v[178:181], v[194:197], v[34:37]
	v_mfma_f32_16x16x32_bf16 v[30:33], v[186:189], v[194:197], v[30:33]
	v_mfma_f32_16x16x32_bf16 v[26:29], v[178:181], v[206:209], v[26:29]
	v_mfma_f32_16x16x32_bf16 v[22:25], v[186:189], v[206:209], v[22:25]
	v_mfma_f32_16x16x32_bf16 v[18:21], v[178:181], v[214:217], v[18:21]
	v_mfma_f32_16x16x32_bf16 v[14:17], v[186:189], v[214:217], v[14:17]
	v_mfma_f32_16x16x32_bf16 v[10:13], v[178:181], v[222:225], v[10:13]
	v_mfma_f32_16x16x32_bf16 v[4:7], v[186:189], v[222:225], v[4:7]
	s_setprio 0
	s_barrier
	s_add_i32 s36, 0, 0x18000
	v_add_u32_e32 v3, s36, v165
	s_add_i32 s37, 0, 0x1c000
	ds_read_b128 v[150:153], v3
	ds_read_b128 v[154:157], v3 offset:1024
	ds_read_b128 v[158:161], v3 offset:2048
	ds_read_b128 v[170:173], v3 offset:3072
	v_add_u32_e32 v3, s37, v165
	ds_read_b128 v[174:177], v3
	ds_read_b128 v[178:181], v3 offset:1024
	ds_read_b128 v[182:185], v3 offset:2048
	ds_read_b128 v[186:189], v3 offset:3072
	s_add_u32 s58, s58, 0x80000
	s_addc_u32 s59, s59, 0
	s_mov_b32 m0, s65
	v_lshl_add_u64 v[8:9], s[58:59], 0, v[140:141]
	ds_read_b128 v[190:193], v169 offset:32768
	ds_read_b128 v[194:197], v169 offset:33792
	ds_read_b128 v[202:205], v169 offset:34816
	ds_read_b128 v[206:209], v169 offset:35840
	ds_read_b128 v[210:213], v169 offset:36864
	ds_read_b128 v[214:217], v169 offset:37888
	ds_read_b128 v[218:221], v169 offset:38912
	ds_read_b128 v[222:225], v169 offset:39936
	global_load_lds_dwordx4 v[8:9], off
	v_lshl_add_u64 v[8:9], s[58:59], 0, v[136:137]
	s_mov_b32 m0, s66
	s_nop 0
	global_load_lds_dwordx4 v[8:9], off
	s_waitcnt vmcnt(8)
	s_waitcnt lgkmcnt(0)
	s_barrier
	s_setprio 1
	s_waitcnt lgkmcnt(0)
	v_mfma_f32_16x16x32_bf16 v[130:133], v[150:153], v[190:193], v[130:133]
	v_mfma_f32_16x16x32_bf16 v[130:133], v[154:157], v[194:197], v[130:133]
	v_mfma_f32_16x16x32_bf16 v[126:129], v[158:161], v[190:193], v[126:129]
	v_mfma_f32_16x16x32_bf16 v[126:129], v[170:173], v[194:197], v[126:129]
	v_mfma_f32_16x16x32_bf16 v[122:125], v[150:153], v[202:205], v[122:125]
	v_mfma_f32_16x16x32_bf16 v[122:125], v[154:157], v[206:209], v[122:125]
	v_mfma_f32_16x16x32_bf16 v[118:121], v[158:161], v[202:205], v[118:121]
	v_mfma_f32_16x16x32_bf16 v[118:121], v[170:173], v[206:209], v[118:121]
	v_mfma_f32_16x16x32_bf16 v[114:117], v[150:153], v[210:213], v[114:117]
	v_mfma_f32_16x16x32_bf16 v[114:117], v[154:157], v[214:217], v[114:117]
	v_mfma_f32_16x16x32_bf16 v[110:113], v[158:161], v[210:213], v[110:113]
	v_mfma_f32_16x16x32_bf16 v[110:113], v[170:173], v[214:217], v[110:113]
	v_mfma_f32_16x16x32_bf16 v[106:109], v[150:153], v[218:221], v[106:109]
	v_mfma_f32_16x16x32_bf16 v[106:109], v[154:157], v[222:225], v[106:109]
	v_mfma_f32_16x16x32_bf16 v[102:105], v[158:161], v[218:221], v[102:105]
	v_mfma_f32_16x16x32_bf16 v[102:105], v[170:173], v[222:225], v[102:105]
	s_setprio 0
	s_setprio 1
	v_mfma_f32_16x16x32_bf16 v[98:101], v[174:177], v[190:193], v[98:101]
	v_mfma_f32_16x16x32_bf16 v[98:101], v[178:181], v[194:197], v[98:101]
	v_mfma_f32_16x16x32_bf16 v[94:97], v[182:185], v[190:193], v[94:97]
	v_mfma_f32_16x16x32_bf16 v[94:97], v[186:189], v[194:197], v[94:97]
	v_mfma_f32_16x16x32_bf16 v[90:93], v[174:177], v[202:205], v[90:93]
	v_mfma_f32_16x16x32_bf16 v[90:93], v[178:181], v[206:209], v[90:93]
	v_mfma_f32_16x16x32_bf16 v[86:89], v[182:185], v[202:205], v[86:89]
	v_mfma_f32_16x16x32_bf16 v[86:89], v[186:189], v[206:209], v[86:89]
	v_mfma_f32_16x16x32_bf16 v[82:85], v[174:177], v[210:213], v[82:85]
	v_mfma_f32_16x16x32_bf16 v[82:85], v[178:181], v[214:217], v[82:85]
	v_mfma_f32_16x16x32_bf16 v[78:81], v[182:185], v[210:213], v[78:81]
	v_mfma_f32_16x16x32_bf16 v[78:81], v[186:189], v[214:217], v[78:81]
	v_mfma_f32_16x16x32_bf16 v[74:77], v[174:177], v[218:221], v[74:77]
	v_mfma_f32_16x16x32_bf16 v[74:77], v[178:181], v[222:225], v[74:77]
	v_mfma_f32_16x16x32_bf16 v[70:73], v[182:185], v[218:221], v[70:73]
	v_mfma_f32_16x16x32_bf16 v[70:73], v[186:189], v[222:225], v[70:73]
	s_setprio 0
	s_barrier
	s_add_i32 s36, s36, s43
	v_lshl_add_u64 v[8:9], v[166:167], 0, s[10:11]
	s_mov_b32 m0, s36
	ds_read_b128 v[190:193], v169 offset:49152
	ds_read_b128 v[194:197], v169 offset:50176
	ds_read_b128 v[202:205], v169 offset:51200
	ds_read_b128 v[206:209], v169 offset:52224
	ds_read_b128 v[210:213], v169 offset:53248
	ds_read_b128 v[214:217], v169 offset:54272
	ds_read_b128 v[218:221], v169 offset:55296
	ds_read_b128 v[222:225], v169 offset:56320
	global_load_lds_dwordx4 v[8:9], off
	s_add_i32 m0, s36, 0x2000
	s_add_u32 s56, s56, 0x80080
	v_lshl_add_u64 v[8:9], v[198:199], 0, s[10:11]
	s_addc_u32 s57, s57, 0
	s_add_i32 s36, s37, s43
	global_load_lds_dwordx4 v[8:9], off
	v_lshl_add_u64 v[8:9], s[56:57], 0, v[138:139]
	s_mov_b32 m0, s36
	s_nop 0
	global_load_lds_dwordx4 v[8:9], off
	v_lshl_add_u64 v[8:9], s[56:57], 0, v[134:135]
	s_add_i32 m0, s36, 0x2000
	s_nop 0
	global_load_lds_dwordx4 v[8:9], off
	v_lshl_add_u64 v[8:9], v[226:227], 0, s[10:11]
	s_mov_b32 m0, s69
	s_nop 0
	global_load_lds_dwordx4 v[8:9], off
	v_lshl_add_u64 v[8:9], v[228:229], 0, s[10:11]
	s_mov_b32 m0, s70
	s_nop 0
	global_load_lds_dwordx4 v[8:9], off
	s_waitcnt vmcnt(8)
	s_waitcnt lgkmcnt(0)
	s_barrier
	s_setprio 1
	s_waitcnt lgkmcnt(0)
	v_mfma_f32_16x16x32_bf16 v[66:69], v[150:153], v[190:193], v[66:69]
	v_mfma_f32_16x16x32_bf16 v[66:69], v[154:157], v[194:197], v[66:69]
	v_mfma_f32_16x16x32_bf16 v[62:65], v[158:161], v[190:193], v[62:65]
	v_mfma_f32_16x16x32_bf16 v[62:65], v[170:173], v[194:197], v[62:65]
	v_mfma_f32_16x16x32_bf16 v[58:61], v[150:153], v[202:205], v[58:61]
	v_mfma_f32_16x16x32_bf16 v[58:61], v[154:157], v[206:209], v[58:61]
	v_mfma_f32_16x16x32_bf16 v[54:57], v[158:161], v[202:205], v[54:57]
	v_mfma_f32_16x16x32_bf16 v[54:57], v[170:173], v[206:209], v[54:57]
	v_mfma_f32_16x16x32_bf16 v[50:53], v[150:153], v[210:213], v[50:53]
	v_mfma_f32_16x16x32_bf16 v[50:53], v[154:157], v[214:217], v[50:53]
	v_mfma_f32_16x16x32_bf16 v[46:49], v[158:161], v[210:213], v[46:49]
	v_mfma_f32_16x16x32_bf16 v[46:49], v[170:173], v[214:217], v[46:49]
	v_mfma_f32_16x16x32_bf16 v[42:45], v[150:153], v[218:221], v[42:45]
	v_mfma_f32_16x16x32_bf16 v[42:45], v[154:157], v[222:225], v[42:45]
	v_mfma_f32_16x16x32_bf16 v[38:41], v[158:161], v[218:221], v[38:41]
	v_mfma_f32_16x16x32_bf16 v[38:41], v[170:173], v[222:225], v[38:41]
	s_setprio 0
	s_setprio 1
	v_mfma_f32_16x16x32_bf16 v[34:37], v[174:177], v[190:193], v[34:37]
	v_mfma_f32_16x16x32_bf16 v[30:33], v[182:185], v[190:193], v[30:33]
	v_mfma_f32_16x16x32_bf16 v[26:29], v[174:177], v[202:205], v[26:29]
	v_mfma_f32_16x16x32_bf16 v[22:25], v[182:185], v[202:205], v[22:25]
	v_mfma_f32_16x16x32_bf16 v[18:21], v[174:177], v[210:213], v[18:21]
	v_mfma_f32_16x16x32_bf16 v[14:17], v[182:185], v[210:213], v[14:17]
	v_mfma_f32_16x16x32_bf16 v[8:11], v[174:177], v[218:221], v[10:13]
	v_mfma_f32_16x16x32_bf16 v[4:7], v[182:185], v[218:221], v[4:7]
	v_mfma_f32_16x16x32_bf16 v[34:37], v[178:181], v[194:197], v[34:37]
	v_mfma_f32_16x16x32_bf16 v[30:33], v[186:189], v[194:197], v[30:33]
	v_mfma_f32_16x16x32_bf16 v[26:29], v[178:181], v[206:209], v[26:29]
	v_mfma_f32_16x16x32_bf16 v[22:25], v[186:189], v[206:209], v[22:25]
	v_mfma_f32_16x16x32_bf16 v[18:21], v[178:181], v[214:217], v[18:21]
	v_mfma_f32_16x16x32_bf16 v[14:17], v[186:189], v[214:217], v[14:17]
	v_mfma_f32_16x16x32_bf16 v[10:13], v[178:181], v[222:225], v[8:11]
	v_mfma_f32_16x16x32_bf16 v[6:9], v[186:189], v[222:225], v[4:7]
	s_setprio 0
	s_barrier
	s_add_i32 s78, s78, 2
	s_add_u32 s52, s52, 0x100
	s_addc_u32 s53, s53, 0
	s_add_u32 s76, s76, 0x100
	s_addc_u32 s77, s77, 0
	s_cmp_gt_u32 s78, 29
	s_cbranch_scc0 .LBB0_1226
	s_and_b64 vcc, exec, s[12:13]
	s_cbranch_vccz .LBB0_1229
	s_barrier

.LBB0_1397:
	ds_read_b128 v[146:149], v154
	ds_read_b128 v[158:161], v154 offset:1024
	ds_read_b128 v[166:169], v154 offset:2048
	ds_read_b128 v[170:173], v154 offset:3072
	ds_read_b128 v[174:177], v155
	ds_read_b128 v[178:181], v155 offset:1024
	ds_read_b128 v[182:185], v155 offset:2048
	ds_read_b128 v[186:189], v155 offset:3072
	s_add_i32 s93, s44, 2
	s_add_u32 s36, s62, 0xfff00080
	s_addc_u32 s37, s63, -1
	s_cmp_eq_u32 s59, s44
	s_cselect_b32 s67, s38, s37
	s_cselect_b32 s66, s39, s36
	s_cselect_b32 s65, s51, s92
	s_cselect_b32 s64, s53, s61
	v_lshl_add_u64 v[150:151], s[62:63], 0, v[140:141]
	s_add_i32 m0, s72, 0xc000
	ds_read_b128 v[190:193], v156
	ds_read_b128 v[194:197], v156 offset:1024
	ds_read_b128 v[202:205], v156 offset:2048
	ds_read_b128 v[206:209], v156 offset:3072
	ds_read_b128 v[210:213], v156 offset:4096
	ds_read_b128 v[214:217], v156 offset:5120
	ds_read_b128 v[218:221], v156 offset:6144
	ds_read_b128 v[222:225], v156 offset:7168
	global_load_lds_dwordx4 v[150:151], off
	v_lshl_add_u64 v[150:151], s[62:63], 0, v[142:143]
	s_add_i32 m0, s72, 0xe000
	s_nop 0
	global_load_lds_dwordx4 v[150:151], off
	s_waitcnt vmcnt(8)
	s_waitcnt lgkmcnt(0)
	s_barrier
	s_setprio 1
	s_waitcnt lgkmcnt(0)
	v_mfma_f32_16x16x32_bf16 v[126:129], v[146:149], v[190:193], v[126:129]
	v_mfma_f32_16x16x32_bf16 v[126:129], v[158:161], v[194:197], v[126:129]
	v_mfma_f32_16x16x32_bf16 v[122:125], v[166:169], v[190:193], v[122:125]
	v_mfma_f32_16x16x32_bf16 v[122:125], v[170:173], v[194:197], v[122:125]
	v_mfma_f32_16x16x32_bf16 v[110:113], v[146:149], v[202:205], v[110:113]
	v_mfma_f32_16x16x32_bf16 v[110:113], v[158:161], v[206:209], v[110:113]
	v_mfma_f32_16x16x32_bf16 v[106:109], v[166:169], v[202:205], v[106:109]
	v_mfma_f32_16x16x32_bf16 v[106:109], v[170:173], v[206:209], v[106:109]
	v_mfma_f32_16x16x32_bf16 v[94:97], v[146:149], v[210:213], v[94:97]
	v_mfma_f32_16x16x32_bf16 v[94:97], v[158:161], v[214:217], v[94:97]
	v_mfma_f32_16x16x32_bf16 v[90:93], v[166:169], v[210:213], v[90:93]
	v_mfma_f32_16x16x32_bf16 v[90:93], v[170:173], v[214:217], v[90:93]
	v_mfma_f32_16x16x32_bf16 v[78:81], v[146:149], v[218:221], v[78:81]
	v_mfma_f32_16x16x32_bf16 v[78:81], v[158:161], v[222:225], v[78:81]
	v_mfma_f32_16x16x32_bf16 v[74:77], v[166:169], v[218:221], v[74:77]
	v_mfma_f32_16x16x32_bf16 v[74:77], v[170:173], v[222:225], v[74:77]
	s_setprio 0
	s_setprio 1
	v_mfma_f32_16x16x32_bf16 v[118:121], v[174:177], v[190:193], v[118:121]
	v_mfma_f32_16x16x32_bf16 v[118:121], v[178:181], v[194:197], v[118:121]
	v_mfma_f32_16x16x32_bf16 v[114:117], v[182:185], v[190:193], v[114:117]
	v_mfma_f32_16x16x32_bf16 v[114:117], v[186:189], v[194:197], v[114:117]
	v_mfma_f32_16x16x32_bf16 v[102:105], v[174:177], v[202:205], v[102:105]
	v_mfma_f32_16x16x32_bf16 v[102:105], v[178:181], v[206:209], v[102:105]
	v_mfma_f32_16x16x32_bf16 v[98:101], v[182:185], v[202:205], v[98:101]
	v_mfma_f32_16x16x32_bf16 v[98:101], v[186:189], v[206:209], v[98:101]
	v_mfma_f32_16x16x32_bf16 v[86:89], v[174:177], v[210:213], v[86:89]
	v_mfma_f32_16x16x32_bf16 v[86:89], v[178:181], v[214:217], v[86:89]
	v_mfma_f32_16x16x32_bf16 v[82:85], v[182:185], v[210:213], v[82:85]
	v_mfma_f32_16x16x32_bf16 v[82:85], v[186:189], v[214:217], v[82:85]
	v_mfma_f32_16x16x32_bf16 v[70:73], v[174:177], v[218:221], v[70:73]
	v_mfma_f32_16x16x32_bf16 v[70:73], v[178:181], v[222:225], v[70:73]
	v_mfma_f32_16x16x32_bf16 v[66:69], v[182:185], v[218:221], v[66:69]
	v_mfma_f32_16x16x32_bf16 v[66:69], v[186:189], v[222:225], v[66:69]
	s_setprio 0
	s_barrier
	s_add_i32 s36, s82, s69
	v_lshl_add_u64 v[150:151], s[64:65], 0, v[132:133]
	s_mov_b32 m0, s36
	ds_read_b128 v[190:193], v156 offset:16384
	ds_read_b128 v[194:197], v156 offset:17408
	ds_read_b128 v[202:205], v156 offset:18432
	ds_read_b128 v[206:209], v156 offset:19456
	ds_read_b128 v[210:213], v156 offset:20480
	ds_read_b128 v[214:217], v156 offset:21504
	ds_read_b128 v[218:221], v156 offset:22528
	ds_read_b128 v[222:225], v156 offset:23552
	global_load_lds_dwordx4 v[150:151], off
	s_add_i32 m0, s36, 0x2000
	s_add_u32 s94, s64, 0x100000
	v_lshl_add_u64 v[198:199], s[64:65], 0, v[136:137]
	s_addc_u32 s95, s65, 0
	s_add_i32 s36, s83, s69
	global_load_lds_dwordx4 v[198:199], off
	v_lshl_add_u64 v[226:227], s[94:95], 0, v[132:133]
	s_mov_b32 m0, s36
	v_lshl_add_u64 v[228:229], s[66:67], 0, v[134:135]
	global_load_lds_dwordx4 v[226:227], off
	v_lshl_add_u64 v[226:227], s[94:95], 0, v[136:137]
	s_add_i32 m0, s36, 0x2000
	s_nop 0
	global_load_lds_dwordx4 v[226:227], off
	v_lshl_add_u64 v[226:227], s[66:67], 0, v[130:131]
	s_mov_b32 m0, s72
	s_nop 0
	global_load_lds_dwordx4 v[226:227], off
	s_mov_b32 m0, s73
	s_nop 0
	global_load_lds_dwordx4 v[228:229], off
	s_waitcnt vmcnt(8)
	s_waitcnt lgkmcnt(0)
	s_barrier
	s_setprio 1
	s_waitcnt lgkmcnt(0)
	v_mfma_f32_16x16x32_bf16 v[62:65], v[146:149], v[190:193], v[62:65]
	v_mfma_f32_16x16x32_bf16 v[62:65], v[158:161], v[194:197], v[62:65]
	v_mfma_f32_16x16x32_bf16 v[58:61], v[166:169], v[190:193], v[58:61]
	v_mfma_f32_16x16x32_bf16 v[58:61], v[170:173], v[194:197], v[58:61]
	v_mfma_f32_16x16x32_bf16 v[46:49], v[146:149], v[202:205], v[46:49]
	v_mfma_f32_16x16x32_bf16 v[46:49], v[158:161], v[206:209], v[46:49]
	v_mfma_f32_16x16x32_bf16 v[42:45], v[166:169], v[202:205], v[42:45]
	v_mfma_f32_16x16x32_bf16 v[42:45], v[170:173], v[206:209], v[42:45]
	v_mfma_f32_16x16x32_bf16 v[30:33], v[146:149], v[210:213], v[30:33]
	v_mfma_f32_16x16x32_bf16 v[30:33], v[158:161], v[214:217], v[30:33]
	v_mfma_f32_16x16x32_bf16 v[26:29], v[166:169], v[210:213], v[26:29]
	v_mfma_f32_16x16x32_bf16 v[26:29], v[170:173], v[214:217], v[26:29]
	v_mfma_f32_16x16x32_bf16 v[14:17], v[146:149], v[218:221], v[14:17]
	v_mfma_f32_16x16x32_bf16 v[14:17], v[158:161], v[222:225], v[14:17]
	v_mfma_f32_16x16x32_bf16 v[10:13], v[166:169], v[218:221], v[10:13]
	v_mfma_f32_16x16x32_bf16 v[10:13], v[170:173], v[222:225], v[10:13]
	s_setprio 0
	s_setprio 1
	v_mfma_f32_16x16x32_bf16 v[54:57], v[174:177], v[190:193], v[54:57]
	v_mfma_f32_16x16x32_bf16 v[54:57], v[178:181], v[194:197], v[54:57]
	v_mfma_f32_16x16x32_bf16 v[50:53], v[182:185], v[190:193], v[50:53]
	v_mfma_f32_16x16x32_bf16 v[50:53], v[186:189], v[194:197], v[50:53]
	v_mfma_f32_16x16x32_bf16 v[38:41], v[174:177], v[202:205], v[38:41]
	v_mfma_f32_16x16x32_bf16 v[38:41], v[178:181], v[206:209], v[38:41]
	v_mfma_f32_16x16x32_bf16 v[34:37], v[182:185], v[202:205], v[34:37]
	v_mfma_f32_16x16x32_bf16 v[34:37], v[186:189], v[206:209], v[34:37]
	v_mfma_f32_16x16x32_bf16 v[22:25], v[174:177], v[210:213], v[22:25]
	v_mfma_f32_16x16x32_bf16 v[22:25], v[178:181], v[214:217], v[22:25]
	v_mfma_f32_16x16x32_bf16 v[18:21], v[182:185], v[210:213], v[18:21]
	v_mfma_f32_16x16x32_bf16 v[18:21], v[186:189], v[214:217], v[18:21]
	v_mfma_f32_16x16x32_bf16 v[6:9], v[174:177], v[218:221], v[6:9]
	v_mfma_f32_16x16x32_bf16 v[6:9], v[178:181], v[222:225], v[6:9]
	v_mfma_f32_16x16x32_bf16 v[2:5], v[182:185], v[218:221], v[2:5]
	v_mfma_f32_16x16x32_bf16 v[2:5], v[186:189], v[222:225], v[2:5]
	s_setprio 0
	s_barrier
	s_add_i32 s36, 0, 0x18000
	v_add_u32_e32 v138, s36, v152
	s_add_i32 s37, 0, 0x1c000
	ds_read_b128 v[146:149], v138
	ds_read_b128 v[158:161], v138 offset:1024
	ds_read_b128 v[166:169], v138 offset:2048
	ds_read_b128 v[170:173], v138 offset:3072
	v_add_u32_e32 v138, s37, v152
	ds_read_b128 v[174:177], v138
	ds_read_b128 v[178:181], v138 offset:1024
	ds_read_b128 v[182:185], v138 offset:2048
	ds_read_b128 v[186:189], v138 offset:3072
	s_add_u32 s66, s66, 0x100000
	s_addc_u32 s67, s67, 0
	s_mov_b32 m0, s74
	v_lshl_add_u64 v[230:231], s[66:67], 0, v[130:131]
	ds_read_b128 v[190:193], v156 offset:32768
	ds_read_b128 v[194:197], v156 offset:33792
	ds_read_b128 v[202:205], v156 offset:34816
	ds_read_b128 v[206:209], v156 offset:35840
	ds_read_b128 v[210:213], v156 offset:36864
	ds_read_b128 v[214:217], v156 offset:37888
	ds_read_b128 v[218:221], v156 offset:38912
	ds_read_b128 v[222:225], v156 offset:39936
	global_load_lds_dwordx4 v[230:231], off
	v_lshl_add_u64 v[230:231], s[66:67], 0, v[134:135]
	s_mov_b32 m0, s75
	s_nop 0
	global_load_lds_dwordx4 v[230:231], off
	s_waitcnt vmcnt(8)
	s_waitcnt lgkmcnt(0)
	s_barrier
	s_setprio 1
	s_waitcnt lgkmcnt(0)
	v_mfma_f32_16x16x32_bf16 v[126:129], v[146:149], v[190:193], v[126:129]
	v_mfma_f32_16x16x32_bf16 v[126:129], v[158:161], v[194:197], v[126:129]
	v_mfma_f32_16x16x32_bf16 v[122:125], v[166:169], v[190:193], v[122:125]
	v_mfma_f32_16x16x32_bf16 v[122:125], v[170:173], v[194:197], v[122:125]
	v_mfma_f32_16x16x32_bf16 v[110:113], v[146:149], v[202:205], v[110:113]
	v_mfma_f32_16x16x32_bf16 v[110:113], v[158:161], v[206:209], v[110:113]
	v_mfma_f32_16x16x32_bf16 v[106:109], v[166:169], v[202:205], v[106:109]
	v_mfma_f32_16x16x32_bf16 v[106:109], v[170:173], v[206:209], v[106:109]
	v_mfma_f32_16x16x32_bf16 v[94:97], v[146:149], v[210:213], v[94:97]
	v_mfma_f32_16x16x32_bf16 v[94:97], v[158:161], v[214:217], v[94:97]
	v_mfma_f32_16x16x32_bf16 v[90:93], v[166:169], v[210:213], v[90:93]
	v_mfma_f32_16x16x32_bf16 v[90:93], v[170:173], v[214:217], v[90:93]
	v_mfma_f32_16x16x32_bf16 v[78:81], v[146:149], v[218:221], v[78:81]
	v_mfma_f32_16x16x32_bf16 v[78:81], v[158:161], v[222:225], v[78:81]
	v_mfma_f32_16x16x32_bf16 v[74:77], v[166:169], v[218:221], v[74:77]
	v_mfma_f32_16x16x32_bf16 v[74:77], v[170:173], v[222:225], v[74:77]
	s_setprio 0
	s_setprio 1
	v_mfma_f32_16x16x32_bf16 v[118:121], v[174:177], v[190:193], v[118:121]
	v_mfma_f32_16x16x32_bf16 v[118:121], v[178:181], v[194:197], v[118:121]
	v_mfma_f32_16x16x32_bf16 v[114:117], v[182:185], v[190:193], v[114:117]
	v_mfma_f32_16x16x32_bf16 v[114:117], v[186:189], v[194:197], v[114:117]
	v_mfma_f32_16x16x32_bf16 v[102:105], v[174:177], v[202:205], v[102:105]
	v_mfma_f32_16x16x32_bf16 v[102:105], v[178:181], v[206:209], v[102:105]
	v_mfma_f32_16x16x32_bf16 v[98:101], v[182:185], v[202:205], v[98:101]
	v_mfma_f32_16x16x32_bf16 v[98:101], v[186:189], v[206:209], v[98:101]
	v_mfma_f32_16x16x32_bf16 v[86:89], v[174:177], v[210:213], v[86:89]
	v_mfma_f32_16x16x32_bf16 v[86:89], v[178:181], v[214:217], v[86:89]
	v_mfma_f32_16x16x32_bf16 v[82:85], v[182:185], v[210:213], v[82:85]
	v_mfma_f32_16x16x32_bf16 v[82:85], v[186:189], v[214:217], v[82:85]
	v_mfma_f32_16x16x32_bf16 v[70:73], v[174:177], v[218:221], v[70:73]
	v_mfma_f32_16x16x32_bf16 v[70:73], v[178:181], v[222:225], v[70:73]
	v_mfma_f32_16x16x32_bf16 v[66:69], v[182:185], v[218:221], v[66:69]
	v_mfma_f32_16x16x32_bf16 v[66:69], v[186:189], v[222:225], v[66:69]
	s_setprio 0
	s_barrier
	s_add_i32 s36, s36, s69
	v_lshl_add_u64 v[150:151], v[150:151], 0, s[16:17]
	s_mov_b32 m0, s36
	ds_read_b128 v[190:193], v156 offset:49152
	ds_read_b128 v[194:197], v156 offset:50176
	ds_read_b128 v[202:205], v156 offset:51200
	ds_read_b128 v[206:209], v156 offset:52224
	ds_read_b128 v[210:213], v156 offset:53248
	ds_read_b128 v[214:217], v156 offset:54272
	ds_read_b128 v[218:221], v156 offset:55296
	ds_read_b128 v[222:225], v156 offset:56320
	global_load_lds_dwordx4 v[150:151], off
	s_add_i32 m0, s36, 0x2000
	s_add_u32 s64, s64, 0x100080
	v_lshl_add_u64 v[150:151], v[198:199], 0, s[16:17]
	s_addc_u32 s65, s65, 0
	s_add_i32 s36, s37, s69
	global_load_lds_dwordx4 v[150:151], off
	v_lshl_add_u64 v[150:151], s[64:65], 0, v[132:133]
	s_mov_b32 m0, s36
	s_nop 0
	global_load_lds_dwordx4 v[150:151], off
	v_lshl_add_u64 v[150:151], s[64:65], 0, v[136:137]
	s_add_i32 m0, s36, 0x2000
	s_nop 0
	global_load_lds_dwordx4 v[150:151], off
	v_lshl_add_u64 v[150:151], v[226:227], 0, s[16:17]
	s_mov_b32 m0, s78
	s_nop 0
	global_load_lds_dwordx4 v[150:151], off
	v_lshl_add_u64 v[150:151], v[228:229], 0, s[16:17]
	s_mov_b32 m0, s79
	s_nop 0
	global_load_lds_dwordx4 v[150:151], off
	s_waitcnt vmcnt(8)
	s_waitcnt lgkmcnt(0)
	s_barrier
	s_setprio 1
	s_waitcnt lgkmcnt(0)
	v_mfma_f32_16x16x32_bf16 v[62:65], v[146:149], v[190:193], v[62:65]
	v_mfma_f32_16x16x32_bf16 v[62:65], v[158:161], v[194:197], v[62:65]
	v_mfma_f32_16x16x32_bf16 v[58:61], v[166:169], v[190:193], v[58:61]
	v_mfma_f32_16x16x32_bf16 v[58:61], v[170:173], v[194:197], v[58:61]
	v_mfma_f32_16x16x32_bf16 v[46:49], v[146:149], v[202:205], v[46:49]
	v_mfma_f32_16x16x32_bf16 v[46:49], v[158:161], v[206:209], v[46:49]
	v_mfma_f32_16x16x32_bf16 v[42:45], v[166:169], v[202:205], v[42:45]
	v_mfma_f32_16x16x32_bf16 v[42:45], v[170:173], v[206:209], v[42:45]
	v_mfma_f32_16x16x32_bf16 v[30:33], v[146:149], v[210:213], v[30:33]
	v_mfma_f32_16x16x32_bf16 v[30:33], v[158:161], v[214:217], v[30:33]
	v_mfma_f32_16x16x32_bf16 v[26:29], v[166:169], v[210:213], v[26:29]
	v_mfma_f32_16x16x32_bf16 v[26:29], v[170:173], v[214:217], v[26:29]
	v_mfma_f32_16x16x32_bf16 v[14:17], v[146:149], v[218:221], v[14:17]
	v_mfma_f32_16x16x32_bf16 v[14:17], v[158:161], v[222:225], v[14:17]
	v_mfma_f32_16x16x32_bf16 v[10:13], v[166:169], v[218:221], v[10:13]
	v_mfma_f32_16x16x32_bf16 v[10:13], v[170:173], v[222:225], v[10:13]
	s_setprio 0
	s_setprio 1
	v_mfma_f32_16x16x32_bf16 v[54:57], v[174:177], v[190:193], v[54:57]
	v_mfma_f32_16x16x32_bf16 v[54:57], v[178:181], v[194:197], v[54:57]
	v_mfma_f32_16x16x32_bf16 v[50:53], v[182:185], v[190:193], v[50:53]
	v_mfma_f32_16x16x32_bf16 v[50:53], v[186:189], v[194:197], v[50:53]
	v_mfma_f32_16x16x32_bf16 v[38:41], v[174:177], v[202:205], v[38:41]
	v_mfma_f32_16x16x32_bf16 v[38:41], v[178:181], v[206:209], v[38:41]
	v_mfma_f32_16x16x32_bf16 v[34:37], v[182:185], v[202:205], v[34:37]
	v_mfma_f32_16x16x32_bf16 v[34:37], v[186:189], v[206:209], v[34:37]
	v_mfma_f32_16x16x32_bf16 v[22:25], v[174:177], v[210:213], v[22:25]
	v_mfma_f32_16x16x32_bf16 v[22:25], v[178:181], v[214:217], v[22:25]
	v_mfma_f32_16x16x32_bf16 v[18:21], v[182:185], v[210:213], v[18:21]
	v_mfma_f32_16x16x32_bf16 v[18:21], v[186:189], v[214:217], v[18:21]
	v_mfma_f32_16x16x32_bf16 v[6:9], v[174:177], v[218:221], v[6:9]
	v_mfma_f32_16x16x32_bf16 v[6:9], v[178:181], v[222:225], v[6:9]
	v_mfma_f32_16x16x32_bf16 v[2:5], v[182:185], v[218:221], v[2:5]
	v_mfma_f32_16x16x32_bf16 v[2:5], v[186:189], v[222:225], v[2:5]
	s_setprio 0
	s_barrier
	s_add_u32 s62, s62, 0x100
	s_addc_u32 s63, s63, 0
	s_add_u32 s61, s61, 0x100
	s_addc_u32 s92, s92, 0
	s_cmp_ge_i32 s93, s11
	s_mov_b32 s44, s93
	s_cbranch_scc0 .LBB0_1397
	s_and_b64 vcc, exec, s[18:19]
	s_cbranch_vccz .LBB0_1400

.LBB0_1631:
	ds_read_b128 v[166:169], v158
	ds_read_b128 v[170:173], v158 offset:1024
	ds_read_b128 v[174:177], v158 offset:2048
	ds_read_b128 v[178:181], v158 offset:3072
	ds_read_b128 v[182:185], v159
	ds_read_b128 v[186:189], v159 offset:1024
	ds_read_b128 v[190:193], v159 offset:2048
	ds_read_b128 v[194:197], v159 offset:3072
	s_add_u32 s36, s54, 0xfff00080
	s_addc_u32 s37, s55, -1
	s_cmp_eq_u32 s78, 60
	s_cselect_b32 s59, s21, s37
	s_cselect_b32 s58, s74, s36
	s_cselect_b32 s57, s19, s77
	s_cselect_b32 s56, s75, s76
	v_lshl_add_u64 v[198:199], s[54:55], 0, v[140:141]
	s_add_i32 m0, s53, 0xc000
	ds_read_b128 v[202:205], v160
	ds_read_b128 v[206:209], v160 offset:1024
	ds_read_b128 v[210:213], v160 offset:2048
	ds_read_b128 v[214:217], v160 offset:3072
	ds_read_b128 v[218:221], v160 offset:4096
	ds_read_b128 v[222:225], v160 offset:5120
	ds_read_b128 v[226:229], v160 offset:6144
	ds_read_b128 v[230:233], v160 offset:7168
	global_load_lds_dwordx4 v[198:199], off
	v_lshl_add_u64 v[198:199], s[54:55], 0, v[142:143]
	s_add_i32 m0, s53, 0xe000
	s_nop 0
	global_load_lds_dwordx4 v[198:199], off
	s_waitcnt vmcnt(8)
	s_waitcnt lgkmcnt(0)
	s_barrier
	s_setprio 1
	s_waitcnt lgkmcnt(0)
	v_mfma_f32_16x16x32_bf16 v[126:129], v[166:169], v[202:205], v[126:129]
	v_mfma_f32_16x16x32_bf16 v[126:129], v[170:173], v[206:209], v[126:129]
	v_mfma_f32_16x16x32_bf16 v[122:125], v[174:177], v[202:205], v[122:125]
	v_mfma_f32_16x16x32_bf16 v[122:125], v[178:181], v[206:209], v[122:125]
	v_mfma_f32_16x16x32_bf16 v[118:121], v[166:169], v[210:213], v[118:121]
	v_mfma_f32_16x16x32_bf16 v[118:121], v[170:173], v[214:217], v[118:121]
	v_mfma_f32_16x16x32_bf16 v[110:113], v[174:177], v[210:213], v[110:113]
	v_mfma_f32_16x16x32_bf16 v[110:113], v[178:181], v[214:217], v[110:113]
	v_mfma_f32_16x16x32_bf16 v[102:105], v[166:169], v[218:221], v[102:105]
	v_mfma_f32_16x16x32_bf16 v[102:105], v[170:173], v[222:225], v[102:105]
	v_mfma_f32_16x16x32_bf16 v[94:97], v[174:177], v[218:221], v[94:97]
	v_mfma_f32_16x16x32_bf16 v[94:97], v[178:181], v[222:225], v[94:97]
	v_mfma_f32_16x16x32_bf16 v[86:89], v[166:169], v[226:229], v[86:89]
	v_mfma_f32_16x16x32_bf16 v[86:89], v[170:173], v[230:233], v[86:89]
	v_mfma_f32_16x16x32_bf16 v[78:81], v[174:177], v[226:229], v[78:81]
	v_mfma_f32_16x16x32_bf16 v[78:81], v[178:181], v[230:233], v[78:81]
	s_setprio 0
	s_setprio 1
	v_mfma_f32_16x16x32_bf16 v[114:117], v[182:185], v[202:205], v[114:117]
	v_mfma_f32_16x16x32_bf16 v[114:117], v[186:189], v[206:209], v[114:117]
	v_mfma_f32_16x16x32_bf16 v[106:109], v[190:193], v[202:205], v[106:109]
	v_mfma_f32_16x16x32_bf16 v[106:109], v[194:197], v[206:209], v[106:109]
	v_mfma_f32_16x16x32_bf16 v[98:101], v[182:185], v[210:213], v[98:101]
	v_mfma_f32_16x16x32_bf16 v[98:101], v[186:189], v[214:217], v[98:101]
	v_mfma_f32_16x16x32_bf16 v[90:93], v[190:193], v[210:213], v[90:93]
	v_mfma_f32_16x16x32_bf16 v[90:93], v[194:197], v[214:217], v[90:93]
	v_mfma_f32_16x16x32_bf16 v[82:85], v[182:185], v[218:221], v[82:85]
	v_mfma_f32_16x16x32_bf16 v[82:85], v[186:189], v[222:225], v[82:85]
	v_mfma_f32_16x16x32_bf16 v[74:77], v[190:193], v[218:221], v[74:77]
	v_mfma_f32_16x16x32_bf16 v[74:77], v[194:197], v[222:225], v[74:77]
	v_mfma_f32_16x16x32_bf16 v[70:73], v[182:185], v[226:229], v[70:73]
	v_mfma_f32_16x16x32_bf16 v[70:73], v[186:189], v[230:233], v[70:73]
	v_mfma_f32_16x16x32_bf16 v[66:69], v[190:193], v[226:229], v[66:69]
	v_mfma_f32_16x16x32_bf16 v[66:69], v[194:197], v[230:233], v[66:69]
	s_setprio 0
	s_barrier
	s_add_i32 s36, s68, s38
	v_lshl_add_u64 v[198:199], s[56:57], 0, v[136:137]
	s_mov_b32 m0, s36
	ds_read_b128 v[202:205], v160 offset:16384
	ds_read_b128 v[206:209], v160 offset:17408
	ds_read_b128 v[210:213], v160 offset:18432
	ds_read_b128 v[214:217], v160 offset:19456
	ds_read_b128 v[218:221], v160 offset:20480
	ds_read_b128 v[222:225], v160 offset:21504
	ds_read_b128 v[226:229], v160 offset:22528
	ds_read_b128 v[230:233], v160 offset:23552
	global_load_lds_dwordx4 v[198:199], off
	s_add_i32 m0, s36, 0x2000
	s_add_u32 s80, s56, 0x100000
	v_lshl_add_u64 v[234:235], s[56:57], 0, v[132:133]
	s_addc_u32 s81, s57, 0
	s_add_i32 s36, s69, s38
	global_load_lds_dwordx4 v[234:235], off
	v_lshl_add_u64 v[236:237], s[80:81], 0, v[136:137]
	s_mov_b32 m0, s36
	v_lshl_add_u64 v[238:239], s[58:59], 0, v[134:135]
	global_load_lds_dwordx4 v[236:237], off
	v_lshl_add_u64 v[236:237], s[80:81], 0, v[132:133]
	s_add_i32 m0, s36, 0x2000
	s_nop 0
	global_load_lds_dwordx4 v[236:237], off
	v_lshl_add_u64 v[236:237], s[58:59], 0, v[138:139]
	s_mov_b32 m0, s53
	s_nop 0
	global_load_lds_dwordx4 v[236:237], off
	s_mov_b32 m0, s61
	s_nop 0
	global_load_lds_dwordx4 v[238:239], off
	s_waitcnt vmcnt(8)
	s_waitcnt lgkmcnt(0)
	s_barrier
	s_setprio 1
	s_waitcnt lgkmcnt(0)
	v_mfma_f32_16x16x32_bf16 v[62:65], v[166:169], v[202:205], v[62:65]
	v_mfma_f32_16x16x32_bf16 v[62:65], v[170:173], v[206:209], v[62:65]
	v_mfma_f32_16x16x32_bf16 v[58:61], v[174:177], v[202:205], v[58:61]
	v_mfma_f32_16x16x32_bf16 v[58:61], v[178:181], v[206:209], v[58:61]
	v_mfma_f32_16x16x32_bf16 v[54:57], v[166:169], v[210:213], v[54:57]
	v_mfma_f32_16x16x32_bf16 v[54:57], v[170:173], v[214:217], v[54:57]
	v_mfma_f32_16x16x32_bf16 v[46:49], v[174:177], v[210:213], v[46:49]
	v_mfma_f32_16x16x32_bf16 v[46:49], v[178:181], v[214:217], v[46:49]
	v_mfma_f32_16x16x32_bf16 v[38:41], v[166:169], v[218:221], v[38:41]
	v_mfma_f32_16x16x32_bf16 v[38:41], v[170:173], v[222:225], v[38:41]
	v_mfma_f32_16x16x32_bf16 v[30:33], v[174:177], v[218:221], v[30:33]
	v_mfma_f32_16x16x32_bf16 v[30:33], v[178:181], v[222:225], v[30:33]
	v_mfma_f32_16x16x32_bf16 v[22:25], v[166:169], v[226:229], v[22:25]
	v_mfma_f32_16x16x32_bf16 v[22:25], v[170:173], v[230:233], v[22:25]
	v_mfma_f32_16x16x32_bf16 v[14:17], v[174:177], v[226:229], v[14:17]
	v_mfma_f32_16x16x32_bf16 v[14:17], v[178:181], v[230:233], v[14:17]
	s_setprio 0
	s_setprio 1
	v_mfma_f32_16x16x32_bf16 v[50:53], v[182:185], v[202:205], v[50:53]
	v_mfma_f32_16x16x32_bf16 v[50:53], v[186:189], v[206:209], v[50:53]
	v_mfma_f32_16x16x32_bf16 v[42:45], v[190:193], v[202:205], v[42:45]
	v_mfma_f32_16x16x32_bf16 v[42:45], v[194:197], v[206:209], v[42:45]
	v_mfma_f32_16x16x32_bf16 v[34:37], v[182:185], v[210:213], v[34:37]
	v_mfma_f32_16x16x32_bf16 v[34:37], v[186:189], v[214:217], v[34:37]
	v_mfma_f32_16x16x32_bf16 v[26:29], v[190:193], v[210:213], v[26:29]
	v_mfma_f32_16x16x32_bf16 v[26:29], v[194:197], v[214:217], v[26:29]
	v_mfma_f32_16x16x32_bf16 v[18:21], v[182:185], v[218:221], v[18:21]
	v_mfma_f32_16x16x32_bf16 v[18:21], v[186:189], v[222:225], v[18:21]
	v_mfma_f32_16x16x32_bf16 v[10:13], v[190:193], v[218:221], v[10:13]
	v_mfma_f32_16x16x32_bf16 v[10:13], v[194:197], v[222:225], v[10:13]
	v_mfma_f32_16x16x32_bf16 v[6:9], v[182:185], v[226:229], v[6:9]
	v_mfma_f32_16x16x32_bf16 v[6:9], v[186:189], v[230:233], v[6:9]
	v_mfma_f32_16x16x32_bf16 v[2:5], v[190:193], v[226:229], v[2:5]
	v_mfma_f32_16x16x32_bf16 v[2:5], v[194:197], v[230:233], v[2:5]
	s_setprio 0
	s_barrier
	s_add_i32 s36, 0, 0x18000
	v_add_u32_e32 v161, s36, v156
	s_add_i32 s37, 0, 0x1c000
	ds_read_b128 v[166:169], v161
	ds_read_b128 v[170:173], v161 offset:1024
	ds_read_b128 v[174:177], v161 offset:2048
	ds_read_b128 v[178:181], v161 offset:3072
	v_add_u32_e32 v161, s37, v156
	ds_read_b128 v[182:185], v161
	ds_read_b128 v[186:189], v161 offset:1024
	ds_read_b128 v[190:193], v161 offset:2048
	ds_read_b128 v[194:197], v161 offset:3072
	s_add_u32 s58, s58, 0x100000
	s_addc_u32 s59, s59, 0
	s_mov_b32 m0, s62
	v_lshl_add_u64 v[240:241], s[58:59], 0, v[138:139]
	ds_read_b128 v[202:205], v160 offset:32768
	ds_read_b128 v[206:209], v160 offset:33792
	ds_read_b128 v[210:213], v160 offset:34816
	ds_read_b128 v[214:217], v160 offset:35840
	ds_read_b128 v[218:221], v160 offset:36864
	ds_read_b128 v[222:225], v160 offset:37888
	ds_read_b128 v[226:229], v160 offset:38912
	ds_read_b128 v[230:233], v160 offset:39936
	global_load_lds_dwordx4 v[240:241], off
	v_lshl_add_u64 v[240:241], s[58:59], 0, v[134:135]
	s_mov_b32 m0, s63
	s_nop 0
	global_load_lds_dwordx4 v[240:241], off
	s_waitcnt vmcnt(8)
	s_waitcnt lgkmcnt(0)
	s_barrier
	s_setprio 1
	s_waitcnt lgkmcnt(0)
	v_mfma_f32_16x16x32_bf16 v[126:129], v[166:169], v[202:205], v[126:129]
	v_mfma_f32_16x16x32_bf16 v[126:129], v[170:173], v[206:209], v[126:129]
	v_mfma_f32_16x16x32_bf16 v[122:125], v[174:177], v[202:205], v[122:125]
	v_mfma_f32_16x16x32_bf16 v[122:125], v[178:181], v[206:209], v[122:125]
	v_mfma_f32_16x16x32_bf16 v[118:121], v[166:169], v[210:213], v[118:121]
	v_mfma_f32_16x16x32_bf16 v[118:121], v[170:173], v[214:217], v[118:121]
	v_mfma_f32_16x16x32_bf16 v[110:113], v[174:177], v[210:213], v[110:113]
	v_mfma_f32_16x16x32_bf16 v[110:113], v[178:181], v[214:217], v[110:113]
	v_mfma_f32_16x16x32_bf16 v[102:105], v[166:169], v[218:221], v[102:105]
	v_mfma_f32_16x16x32_bf16 v[102:105], v[170:173], v[222:225], v[102:105]
	v_mfma_f32_16x16x32_bf16 v[94:97], v[174:177], v[218:221], v[94:97]
	v_mfma_f32_16x16x32_bf16 v[94:97], v[178:181], v[222:225], v[94:97]
	v_mfma_f32_16x16x32_bf16 v[86:89], v[166:169], v[226:229], v[86:89]
	v_mfma_f32_16x16x32_bf16 v[86:89], v[170:173], v[230:233], v[86:89]
	v_mfma_f32_16x16x32_bf16 v[78:81], v[174:177], v[226:229], v[78:81]
	v_mfma_f32_16x16x32_bf16 v[78:81], v[178:181], v[230:233], v[78:81]
	s_setprio 0
	s_setprio 1
	v_mfma_f32_16x16x32_bf16 v[114:117], v[182:185], v[202:205], v[114:117]
	v_mfma_f32_16x16x32_bf16 v[114:117], v[186:189], v[206:209], v[114:117]
	v_mfma_f32_16x16x32_bf16 v[106:109], v[190:193], v[202:205], v[106:109]
	v_mfma_f32_16x16x32_bf16 v[106:109], v[194:197], v[206:209], v[106:109]
	v_mfma_f32_16x16x32_bf16 v[98:101], v[182:185], v[210:213], v[98:101]
	v_mfma_f32_16x16x32_bf16 v[98:101], v[186:189], v[214:217], v[98:101]
	v_mfma_f32_16x16x32_bf16 v[90:93], v[190:193], v[210:213], v[90:93]
	v_mfma_f32_16x16x32_bf16 v[90:93], v[194:197], v[214:217], v[90:93]
	v_mfma_f32_16x16x32_bf16 v[82:85], v[182:185], v[218:221], v[82:85]
	v_mfma_f32_16x16x32_bf16 v[82:85], v[186:189], v[222:225], v[82:85]
	v_mfma_f32_16x16x32_bf16 v[74:77], v[190:193], v[218:221], v[74:77]
	v_mfma_f32_16x16x32_bf16 v[74:77], v[194:197], v[222:225], v[74:77]
	v_mfma_f32_16x16x32_bf16 v[70:73], v[182:185], v[226:229], v[70:73]
	v_mfma_f32_16x16x32_bf16 v[70:73], v[186:189], v[230:233], v[70:73]
	v_mfma_f32_16x16x32_bf16 v[66:69], v[190:193], v[226:229], v[66:69]
	v_mfma_f32_16x16x32_bf16 v[66:69], v[194:197], v[230:233], v[66:69]
	s_setprio 0
	s_barrier
	s_add_i32 s36, s36, s38
	v_lshl_add_u64 v[198:199], v[198:199], 0, s[14:15]
	s_mov_b32 m0, s36
	ds_read_b128 v[202:205], v160 offset:49152
	ds_read_b128 v[206:209], v160 offset:50176
	ds_read_b128 v[210:213], v160 offset:51200
	ds_read_b128 v[214:217], v160 offset:52224
	ds_read_b128 v[218:221], v160 offset:53248
	ds_read_b128 v[222:225], v160 offset:54272
	ds_read_b128 v[226:229], v160 offset:55296
	ds_read_b128 v[230:233], v160 offset:56320
	global_load_lds_dwordx4 v[198:199], off
	s_add_i32 m0, s36, 0x2000
	s_add_u32 s56, s56, 0x100080
	v_lshl_add_u64 v[198:199], v[234:235], 0, s[14:15]
	s_addc_u32 s57, s57, 0
	s_add_i32 s36, s37, s38
	global_load_lds_dwordx4 v[198:199], off
	v_lshl_add_u64 v[198:199], s[56:57], 0, v[136:137]
	s_mov_b32 m0, s36
	s_nop 0
	global_load_lds_dwordx4 v[198:199], off
	v_lshl_add_u64 v[198:199], s[56:57], 0, v[132:133]
	s_add_i32 m0, s36, 0x2000
	s_nop 0
	global_load_lds_dwordx4 v[198:199], off
	v_lshl_add_u64 v[198:199], v[236:237], 0, s[14:15]
	s_mov_b32 m0, s65
	s_nop 0
	global_load_lds_dwordx4 v[198:199], off
	v_lshl_add_u64 v[198:199], v[238:239], 0, s[14:15]
	s_mov_b32 m0, s66
	s_nop 0
	global_load_lds_dwordx4 v[198:199], off
	s_waitcnt vmcnt(8)
	s_waitcnt lgkmcnt(0)
	s_barrier
	s_setprio 1
	s_waitcnt lgkmcnt(0)
	v_mfma_f32_16x16x32_bf16 v[62:65], v[166:169], v[202:205], v[62:65]
	v_mfma_f32_16x16x32_bf16 v[62:65], v[170:173], v[206:209], v[62:65]
	v_mfma_f32_16x16x32_bf16 v[58:61], v[174:177], v[202:205], v[58:61]
	v_mfma_f32_16x16x32_bf16 v[58:61], v[178:181], v[206:209], v[58:61]
	v_mfma_f32_16x16x32_bf16 v[54:57], v[166:169], v[210:213], v[54:57]
	v_mfma_f32_16x16x32_bf16 v[54:57], v[170:173], v[214:217], v[54:57]
	v_mfma_f32_16x16x32_bf16 v[46:49], v[174:177], v[210:213], v[46:49]
	v_mfma_f32_16x16x32_bf16 v[46:49], v[178:181], v[214:217], v[46:49]
	v_mfma_f32_16x16x32_bf16 v[38:41], v[166:169], v[218:221], v[38:41]
	v_mfma_f32_16x16x32_bf16 v[38:41], v[170:173], v[222:225], v[38:41]
	v_mfma_f32_16x16x32_bf16 v[30:33], v[174:177], v[218:221], v[30:33]
	v_mfma_f32_16x16x32_bf16 v[30:33], v[178:181], v[222:225], v[30:33]
	v_mfma_f32_16x16x32_bf16 v[22:25], v[166:169], v[226:229], v[22:25]
	v_mfma_f32_16x16x32_bf16 v[22:25], v[170:173], v[230:233], v[22:25]
	v_mfma_f32_16x16x32_bf16 v[14:17], v[174:177], v[226:229], v[14:17]
	v_mfma_f32_16x16x32_bf16 v[14:17], v[178:181], v[230:233], v[14:17]
	s_setprio 0
	s_setprio 1
	v_mfma_f32_16x16x32_bf16 v[50:53], v[182:185], v[202:205], v[50:53]
	v_mfma_f32_16x16x32_bf16 v[50:53], v[186:189], v[206:209], v[50:53]
	v_mfma_f32_16x16x32_bf16 v[42:45], v[190:193], v[202:205], v[42:45]
	v_mfma_f32_16x16x32_bf16 v[42:45], v[194:197], v[206:209], v[42:45]
	v_mfma_f32_16x16x32_bf16 v[34:37], v[182:185], v[210:213], v[34:37]
	v_mfma_f32_16x16x32_bf16 v[34:37], v[186:189], v[214:217], v[34:37]
	v_mfma_f32_16x16x32_bf16 v[26:29], v[190:193], v[210:213], v[26:29]
	v_mfma_f32_16x16x32_bf16 v[26:29], v[194:197], v[214:217], v[26:29]
	v_mfma_f32_16x16x32_bf16 v[18:21], v[182:185], v[218:221], v[18:21]
	v_mfma_f32_16x16x32_bf16 v[18:21], v[186:189], v[222:225], v[18:21]
	v_mfma_f32_16x16x32_bf16 v[10:13], v[190:193], v[218:221], v[10:13]
	v_mfma_f32_16x16x32_bf16 v[10:13], v[194:197], v[222:225], v[10:13]
	v_mfma_f32_16x16x32_bf16 v[6:9], v[182:185], v[226:229], v[6:9]
	v_mfma_f32_16x16x32_bf16 v[6:9], v[186:189], v[230:233], v[6:9]
	v_mfma_f32_16x16x32_bf16 v[2:5], v[190:193], v[226:229], v[2:5]
	v_mfma_f32_16x16x32_bf16 v[2:5], v[194:197], v[230:233], v[2:5]
	s_setprio 0
	s_barrier
	s_add_i32 s78, s78, 2
	s_add_u32 s54, s54, 0x100
	s_addc_u32 s55, s55, 0
	s_add_u32 s76, s76, 0x100
	s_addc_u32 s77, s77, 0
	s_cmp_gt_u32 s78, 61
	s_cbranch_scc0 .LBB0_1631
	s_and_b64 vcc, exec, s[16:17]
	s_cbranch_vccz .LBB0_1634
	s_barrier

.LBB0_1649:
	s_add_u32 s36, s56, s44
	s_addc_u32 s37, s57, 0
	s_add_u32 s64, s36, 0x100
	s_addc_u32 s65, s37, 0
	s_and_b64 s[62:63], s[60:61], exec
	s_cselect_b32 s65, s21, s65
	s_cselect_b32 s64, s87, s64
	s_add_u32 s44, s54, s44
	s_addc_u32 s62, s55, 0
	s_add_u32 s44, s44, 0x100
	s_addc_u32 s62, s62, 0
	s_and_b64 s[60:61], s[60:61], exec
	s_cselect_b32 s67, s19, s62
	s_cselect_b32 s66, s89, s44
	s_add_u32 s70, s36, 0x10080
	s_addc_u32 s71, s37, 0
	s_add_i32 vcc_lo, s84, s39
	ds_read_b128 v[158:161], v147
	ds_read_b128 v[166:169], v147 offset:1024
	ds_read_b128 v[170:173], v147 offset:2048
	ds_read_b128 v[174:177], v147 offset:3072
	ds_read_b128 v[178:181], v155
	ds_read_b128 v[182:185], v155 offset:1024
	ds_read_b128 v[186:189], v155 offset:2048
	ds_read_b128 v[190:193], v155 offset:3072
	s_add_i32 m0, s53, 0xc000
	s_add_i32 vcc_hi, s53, 0xe000
	s_add_i32 s95, vcc_lo, 0x2000
	s_add_u32 s68, s66, 0x10000
	s_addc_u32 s69, s67, 0
	s_add_i32 s97, s85, s39
	s_add_i32 s96, s97, 0x2000
	s_add_i32 s94, 0, 0x18000
	s_add_i32 s93, 0, 0x1c000
	s_add_u32 s62, s64, 0x10000
	s_addc_u32 s63, s65, 0
	s_add_i32 s92, s94, s39
	s_add_i32 s90, s92, 0x2000
	s_add_u32 s60, s66, 0x10080
	s_addc_u32 s61, s67, 0
	s_add_i32 s91, s93, s39
	s_add_i32 s44, s91, 0x2000
	v_lshl_add_u64 v[198:199], s[70:71], 0, v[138:139]
	ds_read_b128 v[194:197], v156
	ds_read_b128 v[202:205], v156 offset:1024
	ds_read_b128 v[206:209], v156 offset:2048
	ds_read_b128 v[210:213], v156 offset:3072
	ds_read_b128 v[214:217], v156 offset:4096
	ds_read_b128 v[218:221], v156 offset:5120
	ds_read_b128 v[222:225], v156 offset:6144
	ds_read_b128 v[226:229], v156 offset:7168
	global_load_lds_dwordx4 v[198:199], off
	v_lshl_add_u64 v[198:199], s[70:71], 0, v[134:135]
	s_mov_b32 m0, vcc_hi
	s_nop 0
	global_load_lds_dwordx4 v[198:199], off
	s_waitcnt vmcnt(8)
	s_waitcnt lgkmcnt(0)
	s_barrier
	s_setprio 1
	s_waitcnt lgkmcnt(0)
	v_mfma_f32_16x16x32_bf16 v[126:129], v[158:161], v[194:197], v[126:129]
	v_mfma_f32_16x16x32_bf16 v[126:129], v[166:169], v[202:205], v[126:129]
	v_mfma_f32_16x16x32_bf16 v[122:125], v[170:173], v[194:197], v[122:125]
	v_mfma_f32_16x16x32_bf16 v[122:125], v[174:177], v[202:205], v[122:125]
	v_mfma_f32_16x16x32_bf16 v[118:121], v[158:161], v[206:209], v[118:121]
	v_mfma_f32_16x16x32_bf16 v[118:121], v[166:169], v[210:213], v[118:121]
	v_mfma_f32_16x16x32_bf16 v[110:113], v[170:173], v[206:209], v[110:113]
	v_mfma_f32_16x16x32_bf16 v[110:113], v[174:177], v[210:213], v[110:113]
	v_mfma_f32_16x16x32_bf16 v[102:105], v[158:161], v[214:217], v[102:105]
	v_mfma_f32_16x16x32_bf16 v[102:105], v[166:169], v[218:221], v[102:105]
	v_mfma_f32_16x16x32_bf16 v[94:97], v[170:173], v[214:217], v[94:97]
	v_mfma_f32_16x16x32_bf16 v[94:97], v[174:177], v[218:221], v[94:97]
	v_mfma_f32_16x16x32_bf16 v[86:89], v[158:161], v[222:225], v[86:89]
	v_mfma_f32_16x16x32_bf16 v[86:89], v[166:169], v[226:229], v[86:89]
	v_mfma_f32_16x16x32_bf16 v[78:81], v[170:173], v[222:225], v[78:81]
	v_mfma_f32_16x16x32_bf16 v[78:81], v[174:177], v[226:229], v[78:81]
	s_setprio 0
	s_setprio 1
	v_mfma_f32_16x16x32_bf16 v[114:117], v[178:181], v[194:197], v[114:117]
	v_mfma_f32_16x16x32_bf16 v[114:117], v[182:185], v[202:205], v[114:117]
	v_mfma_f32_16x16x32_bf16 v[106:109], v[186:189], v[194:197], v[106:109]
	v_mfma_f32_16x16x32_bf16 v[106:109], v[190:193], v[202:205], v[106:109]
	v_mfma_f32_16x16x32_bf16 v[98:101], v[178:181], v[206:209], v[98:101]
	v_mfma_f32_16x16x32_bf16 v[98:101], v[182:185], v[210:213], v[98:101]
	v_mfma_f32_16x16x32_bf16 v[90:93], v[186:189], v[206:209], v[90:93]
	v_mfma_f32_16x16x32_bf16 v[90:93], v[190:193], v[210:213], v[90:93]
	v_mfma_f32_16x16x32_bf16 v[82:85], v[178:181], v[214:217], v[82:85]
	v_mfma_f32_16x16x32_bf16 v[82:85], v[182:185], v[218:221], v[82:85]
	v_mfma_f32_16x16x32_bf16 v[74:77], v[186:189], v[214:217], v[74:77]
	v_mfma_f32_16x16x32_bf16 v[74:77], v[190:193], v[218:221], v[74:77]
	v_mfma_f32_16x16x32_bf16 v[70:73], v[178:181], v[222:225], v[70:73]
	v_mfma_f32_16x16x32_bf16 v[70:73], v[182:185], v[226:229], v[70:73]
	v_mfma_f32_16x16x32_bf16 v[66:69], v[186:189], v[222:225], v[66:69]
	v_mfma_f32_16x16x32_bf16 v[66:69], v[190:193], v[226:229], v[66:69]
	s_setprio 0
	s_barrier
	s_mov_b32 m0, vcc_lo
	v_lshl_add_u64 v[198:199], s[66:67], 0, v[136:137]
	ds_read_b128 v[194:197], v156 offset:16384
	ds_read_b128 v[202:205], v156 offset:17408
	ds_read_b128 v[206:209], v156 offset:18432
	ds_read_b128 v[210:213], v156 offset:19456
	ds_read_b128 v[214:217], v156 offset:20480
	ds_read_b128 v[218:221], v156 offset:21504
	ds_read_b128 v[222:225], v156 offset:22528
	ds_read_b128 v[226:229], v156 offset:23552
	global_load_lds_dwordx4 v[198:199], off
	v_lshl_add_u64 v[230:231], s[66:67], 0, v[132:133]
	s_mov_b32 m0, s95
	v_lshl_add_u64 v[232:233], s[68:69], 0, v[136:137]
	global_load_lds_dwordx4 v[230:231], off
	s_mov_b32 m0, s97
	v_lshl_add_u64 v[234:235], s[64:65], 0, v[134:135]
	global_load_lds_dwordx4 v[232:233], off
	v_lshl_add_u64 v[232:233], s[68:69], 0, v[132:133]
	s_mov_b32 m0, s96
	s_nop 0
	global_load_lds_dwordx4 v[232:233], off
	v_lshl_add_u64 v[232:233], s[64:65], 0, v[138:139]
	s_mov_b32 m0, s53
	s_nop 0
	global_load_lds_dwordx4 v[232:233], off
	s_mov_b32 m0, s75
	s_nop 0
	global_load_lds_dwordx4 v[234:235], off
	s_waitcnt vmcnt(8)
	s_waitcnt lgkmcnt(0)
	s_barrier
	s_setprio 1
	s_waitcnt lgkmcnt(0)
	v_mfma_f32_16x16x32_bf16 v[62:65], v[158:161], v[194:197], v[62:65]
	v_mfma_f32_16x16x32_bf16 v[62:65], v[166:169], v[202:205], v[62:65]
	v_mfma_f32_16x16x32_bf16 v[58:61], v[170:173], v[194:197], v[58:61]
	v_mfma_f32_16x16x32_bf16 v[58:61], v[174:177], v[202:205], v[58:61]
	v_mfma_f32_16x16x32_bf16 v[54:57], v[158:161], v[206:209], v[54:57]
	v_mfma_f32_16x16x32_bf16 v[54:57], v[166:169], v[210:213], v[54:57]
	v_mfma_f32_16x16x32_bf16 v[46:49], v[170:173], v[206:209], v[46:49]
	v_mfma_f32_16x16x32_bf16 v[46:49], v[174:177], v[210:213], v[46:49]
	v_mfma_f32_16x16x32_bf16 v[38:41], v[158:161], v[214:217], v[38:41]
	v_mfma_f32_16x16x32_bf16 v[38:41], v[166:169], v[218:221], v[38:41]
	v_mfma_f32_16x16x32_bf16 v[30:33], v[170:173], v[214:217], v[30:33]
	v_mfma_f32_16x16x32_bf16 v[30:33], v[174:177], v[218:221], v[30:33]
	v_mfma_f32_16x16x32_bf16 v[22:25], v[158:161], v[222:225], v[22:25]
	v_mfma_f32_16x16x32_bf16 v[22:25], v[166:169], v[226:229], v[22:25]
	v_mfma_f32_16x16x32_bf16 v[14:17], v[170:173], v[222:225], v[14:17]
	v_mfma_f32_16x16x32_bf16 v[14:17], v[174:177], v[226:229], v[14:17]
	s_setprio 0
	s_setprio 1
	v_mfma_f32_16x16x32_bf16 v[50:53], v[178:181], v[194:197], v[50:53]
	v_mfma_f32_16x16x32_bf16 v[50:53], v[182:185], v[202:205], v[50:53]
	v_mfma_f32_16x16x32_bf16 v[42:45], v[186:189], v[194:197], v[42:45]
	v_mfma_f32_16x16x32_bf16 v[42:45], v[190:193], v[202:205], v[42:45]
	v_mfma_f32_16x16x32_bf16 v[34:37], v[178:181], v[206:209], v[34:37]
	v_mfma_f32_16x16x32_bf16 v[34:37], v[182:185], v[210:213], v[34:37]
	v_mfma_f32_16x16x32_bf16 v[26:29], v[186:189], v[206:209], v[26:29]
	v_mfma_f32_16x16x32_bf16 v[26:29], v[190:193], v[210:213], v[26:29]
	v_mfma_f32_16x16x32_bf16 v[18:21], v[178:181], v[214:217], v[18:21]
	v_mfma_f32_16x16x32_bf16 v[18:21], v[182:185], v[218:221], v[18:21]
	v_mfma_f32_16x16x32_bf16 v[10:13], v[186:189], v[214:217], v[10:13]
	v_mfma_f32_16x16x32_bf16 v[10:13], v[190:193], v[218:221], v[10:13]
	v_mfma_f32_16x16x32_bf16 v[6:9], v[178:181], v[222:225], v[6:9]
	v_mfma_f32_16x16x32_bf16 v[6:9], v[182:185], v[226:229], v[6:9]
	v_mfma_f32_16x16x32_bf16 v[2:5], v[186:189], v[222:225], v[2:5]
	v_mfma_f32_16x16x32_bf16 v[2:5], v[190:193], v[226:229], v[2:5]
	s_setprio 0
	s_barrier
	v_add_u32_e32 v157, s94, v145
	ds_read_b128 v[158:161], v157
	ds_read_b128 v[166:169], v157 offset:1024
	ds_read_b128 v[170:173], v157 offset:2048
	ds_read_b128 v[174:177], v157 offset:3072
	v_add_u32_e32 v157, s93, v145
	ds_read_b128 v[178:181], v157
	ds_read_b128 v[182:185], v157 offset:1024
	ds_read_b128 v[186:189], v157 offset:2048
	ds_read_b128 v[190:193], v157 offset:3072
	s_mov_b32 m0, s76
	v_lshl_add_u64 v[236:237], s[62:63], 0, v[138:139]
	ds_read_b128 v[194:197], v156 offset:32768
	ds_read_b128 v[202:205], v156 offset:33792
	ds_read_b128 v[206:209], v156 offset:34816
	ds_read_b128 v[210:213], v156 offset:35840
	ds_read_b128 v[214:217], v156 offset:36864
	ds_read_b128 v[218:221], v156 offset:37888
	ds_read_b128 v[222:225], v156 offset:38912
	ds_read_b128 v[226:229], v156 offset:39936
	global_load_lds_dwordx4 v[236:237], off
	v_lshl_add_u64 v[236:237], s[62:63], 0, v[134:135]
	s_mov_b32 m0, s77
	s_nop 0
	global_load_lds_dwordx4 v[236:237], off
	s_waitcnt vmcnt(8)
	s_waitcnt lgkmcnt(0)
	s_barrier
	s_setprio 1
	s_waitcnt lgkmcnt(0)
	v_mfma_f32_16x16x32_bf16 v[126:129], v[158:161], v[194:197], v[126:129]
	v_mfma_f32_16x16x32_bf16 v[126:129], v[166:169], v[202:205], v[126:129]
	v_mfma_f32_16x16x32_bf16 v[122:125], v[170:173], v[194:197], v[122:125]
	v_mfma_f32_16x16x32_bf16 v[122:125], v[174:177], v[202:205], v[122:125]
	v_mfma_f32_16x16x32_bf16 v[118:121], v[158:161], v[206:209], v[118:121]
	v_mfma_f32_16x16x32_bf16 v[118:121], v[166:169], v[210:213], v[118:121]
	v_mfma_f32_16x16x32_bf16 v[110:113], v[170:173], v[206:209], v[110:113]
	v_mfma_f32_16x16x32_bf16 v[110:113], v[174:177], v[210:213], v[110:113]
	v_mfma_f32_16x16x32_bf16 v[102:105], v[158:161], v[214:217], v[102:105]
	v_mfma_f32_16x16x32_bf16 v[102:105], v[166:169], v[218:221], v[102:105]
	v_mfma_f32_16x16x32_bf16 v[94:97], v[170:173], v[214:217], v[94:97]
	v_mfma_f32_16x16x32_bf16 v[94:97], v[174:177], v[218:221], v[94:97]
	v_mfma_f32_16x16x32_bf16 v[86:89], v[158:161], v[222:225], v[86:89]
	v_mfma_f32_16x16x32_bf16 v[86:89], v[166:169], v[226:229], v[86:89]
	v_mfma_f32_16x16x32_bf16 v[78:81], v[170:173], v[222:225], v[78:81]
	v_mfma_f32_16x16x32_bf16 v[78:81], v[174:177], v[226:229], v[78:81]
	s_setprio 0
	s_setprio 1
	v_mfma_f32_16x16x32_bf16 v[114:117], v[178:181], v[194:197], v[114:117]
	v_mfma_f32_16x16x32_bf16 v[114:117], v[182:185], v[202:205], v[114:117]
	v_mfma_f32_16x16x32_bf16 v[106:109], v[186:189], v[194:197], v[106:109]
	v_mfma_f32_16x16x32_bf16 v[106:109], v[190:193], v[202:205], v[106:109]
	v_mfma_f32_16x16x32_bf16 v[98:101], v[178:181], v[206:209], v[98:101]
	v_mfma_f32_16x16x32_bf16 v[98:101], v[182:185], v[210:213], v[98:101]
	v_mfma_f32_16x16x32_bf16 v[90:93], v[186:189], v[206:209], v[90:93]
	v_mfma_f32_16x16x32_bf16 v[90:93], v[190:193], v[210:213], v[90:93]
	v_mfma_f32_16x16x32_bf16 v[82:85], v[178:181], v[214:217], v[82:85]
	v_mfma_f32_16x16x32_bf16 v[82:85], v[182:185], v[218:221], v[82:85]
	v_mfma_f32_16x16x32_bf16 v[74:77], v[186:189], v[214:217], v[74:77]
	v_mfma_f32_16x16x32_bf16 v[74:77], v[190:193], v[218:221], v[74:77]
	v_mfma_f32_16x16x32_bf16 v[70:73], v[178:181], v[222:225], v[70:73]
	v_mfma_f32_16x16x32_bf16 v[70:73], v[182:185], v[226:229], v[70:73]
	v_mfma_f32_16x16x32_bf16 v[66:69], v[186:189], v[222:225], v[66:69]
	v_mfma_f32_16x16x32_bf16 v[66:69], v[190:193], v[226:229], v[66:69]
	s_setprio 0
	s_barrier
	s_mov_b32 m0, s92
	v_lshl_add_u64 v[198:199], v[198:199], 0, s[14:15]
	ds_read_b128 v[194:197], v156 offset:49152
	ds_read_b128 v[202:205], v156 offset:50176
	ds_read_b128 v[206:209], v156 offset:51200
	ds_read_b128 v[210:213], v156 offset:52224
	ds_read_b128 v[214:217], v156 offset:53248
	ds_read_b128 v[218:221], v156 offset:54272
	ds_read_b128 v[222:225], v156 offset:55296
	ds_read_b128 v[226:229], v156 offset:56320
	global_load_lds_dwordx4 v[198:199], off
	v_lshl_add_u64 v[198:199], v[230:231], 0, s[14:15]
	s_mov_b32 m0, s90
	s_nop 0
	global_load_lds_dwordx4 v[198:199], off
	v_lshl_add_u64 v[198:199], s[60:61], 0, v[136:137]
	s_mov_b32 m0, s91
	s_nop 0
	global_load_lds_dwordx4 v[198:199], off
	v_lshl_add_u64 v[198:199], s[60:61], 0, v[132:133]
	s_mov_b32 m0, s44
	s_nop 0
	global_load_lds_dwordx4 v[198:199], off
	v_lshl_add_u64 v[198:199], v[232:233], 0, s[14:15]
	s_mov_b32 m0, s80
	s_nop 0
	global_load_lds_dwordx4 v[198:199], off
	v_lshl_add_u64 v[198:199], v[234:235], 0, s[14:15]
	s_mov_b32 m0, s81
	s_nop 0
	global_load_lds_dwordx4 v[198:199], off
	s_waitcnt vmcnt(8)
	s_waitcnt lgkmcnt(0)
	s_barrier
	s_setprio 1
	s_waitcnt lgkmcnt(0)
	v_mfma_f32_16x16x32_bf16 v[62:65], v[158:161], v[194:197], v[62:65]
	v_mfma_f32_16x16x32_bf16 v[62:65], v[166:169], v[202:205], v[62:65]
	v_mfma_f32_16x16x32_bf16 v[58:61], v[170:173], v[194:197], v[58:61]
	v_mfma_f32_16x16x32_bf16 v[58:61], v[174:177], v[202:205], v[58:61]
	v_mfma_f32_16x16x32_bf16 v[54:57], v[158:161], v[206:209], v[54:57]
	v_mfma_f32_16x16x32_bf16 v[54:57], v[166:169], v[210:213], v[54:57]
	v_mfma_f32_16x16x32_bf16 v[46:49], v[170:173], v[206:209], v[46:49]
	v_mfma_f32_16x16x32_bf16 v[46:49], v[174:177], v[210:213], v[46:49]
	v_mfma_f32_16x16x32_bf16 v[38:41], v[158:161], v[214:217], v[38:41]
	v_mfma_f32_16x16x32_bf16 v[38:41], v[166:169], v[218:221], v[38:41]
	v_mfma_f32_16x16x32_bf16 v[30:33], v[170:173], v[214:217], v[30:33]
	v_mfma_f32_16x16x32_bf16 v[30:33], v[174:177], v[218:221], v[30:33]
	v_mfma_f32_16x16x32_bf16 v[22:25], v[158:161], v[222:225], v[22:25]
	v_mfma_f32_16x16x32_bf16 v[22:25], v[166:169], v[226:229], v[22:25]
	v_mfma_f32_16x16x32_bf16 v[14:17], v[170:173], v[222:225], v[14:17]
	v_mfma_f32_16x16x32_bf16 v[14:17], v[174:177], v[226:229], v[14:17]
	s_setprio 0
	s_setprio 1
	v_mfma_f32_16x16x32_bf16 v[50:53], v[178:181], v[194:197], v[50:53]
	v_mfma_f32_16x16x32_bf16 v[50:53], v[182:185], v[202:205], v[50:53]
	v_mfma_f32_16x16x32_bf16 v[42:45], v[186:189], v[194:197], v[42:45]
	v_mfma_f32_16x16x32_bf16 v[42:45], v[190:193], v[202:205], v[42:45]
	v_mfma_f32_16x16x32_bf16 v[34:37], v[178:181], v[206:209], v[34:37]
	v_mfma_f32_16x16x32_bf16 v[34:37], v[182:185], v[210:213], v[34:37]
	v_mfma_f32_16x16x32_bf16 v[26:29], v[186:189], v[206:209], v[26:29]
	v_mfma_f32_16x16x32_bf16 v[26:29], v[190:193], v[210:213], v[26:29]
	v_mfma_f32_16x16x32_bf16 v[18:21], v[178:181], v[214:217], v[18:21]
	v_mfma_f32_16x16x32_bf16 v[18:21], v[182:185], v[218:221], v[18:21]
	v_mfma_f32_16x16x32_bf16 v[10:13], v[186:189], v[214:217], v[10:13]
	v_mfma_f32_16x16x32_bf16 v[10:13], v[190:193], v[218:221], v[10:13]
	v_mfma_f32_16x16x32_bf16 v[6:9], v[178:181], v[222:225], v[6:9]
	v_mfma_f32_16x16x32_bf16 v[6:9], v[182:185], v[226:229], v[6:9]
	v_mfma_f32_16x16x32_bf16 v[2:5], v[186:189], v[222:225], v[2:5]
	v_mfma_f32_16x16x32_bf16 v[2:5], v[190:193], v[226:229], v[2:5]
	s_setprio 0
	s_barrier
	s_movk_i32 s44, 0x100
	s_andn2_b64 vcc, exec, s[58:59]
	s_mov_b64 s[60:61], -1
	s_mov_b64 s[58:59], 0
	s_cbranch_vccz .LBB0_1649
	s_and_b64 vcc, exec, s[16:17]
	s_cbranch_vccz .LBB0_1652
	s_barrier

.LBB0_1667:
	s_add_u32 s36, s56, s44
	s_addc_u32 s37, s57, 0
	s_add_u32 s64, s36, 0x100
	s_addc_u32 s65, s37, 0
	s_and_b64 s[62:63], s[60:61], exec
	s_cselect_b32 s65, s21, s65
	s_cselect_b32 s64, s86, s64
	s_add_u32 s44, s54, s44
	s_addc_u32 s62, s55, 0
	s_add_u32 s44, s44, 0x100
	s_addc_u32 s62, s62, 0
	s_and_b64 s[60:61], s[60:61], exec
	s_cselect_b32 s67, s19, s62
	s_cselect_b32 s66, s87, s44
	s_add_u32 s70, s36, 0x10080
	s_addc_u32 s71, s37, 0
	s_add_i32 s97, s82, s38
	ds_read_b128 v[150:153], v146
	ds_read_b128 v[154:157], v146 offset:1024
	ds_read_b128 v[158:161], v146 offset:2048
	ds_read_b128 v[166:169], v146 offset:3072
	ds_read_b128 v[170:173], v147
	ds_read_b128 v[174:177], v147 offset:1024
	ds_read_b128 v[178:181], v147 offset:2048
	ds_read_b128 v[182:185], v147 offset:3072
	s_add_i32 m0, s53, 0xc000
	s_add_i32 vcc_lo, s53, 0xe000
	s_add_i32 s94, s97, 0x2000
	s_add_u32 s68, s66, 0x10000
	s_addc_u32 s69, s67, 0
	s_add_i32 s96, s83, s38
	s_add_i32 s95, s96, 0x2000
	s_add_i32 s93, 0, 0x18000
	s_add_i32 s92, 0, 0x1c000
	s_add_u32 s62, s64, 0x10000
	s_addc_u32 s63, s65, 0
	s_add_i32 s91, s93, s38
	s_add_i32 s89, s91, 0x2000
	s_add_u32 s60, s66, 0x10080
	s_addc_u32 s61, s67, 0
	s_add_i32 s90, s92, s38
	s_add_i32 s44, s90, 0x2000
	v_lshl_add_u64 v[198:199], s[70:71], 0, v[138:139]
	ds_read_b128 v[186:189], v148
	ds_read_b128 v[190:193], v148 offset:1024
	ds_read_b128 v[194:197], v148 offset:2048
	ds_read_b128 v[202:205], v148 offset:3072
	ds_read_b128 v[206:209], v148 offset:4096
	ds_read_b128 v[210:213], v148 offset:5120
	ds_read_b128 v[214:217], v148 offset:6144
	ds_read_b128 v[218:221], v148 offset:7168
	global_load_lds_dwordx4 v[198:199], off
	v_lshl_add_u64 v[198:199], s[70:71], 0, v[134:135]
	s_mov_b32 m0, vcc_lo
	s_nop 0
	global_load_lds_dwordx4 v[198:199], off
	s_waitcnt vmcnt(8)
	s_waitcnt lgkmcnt(0)
	s_barrier
	s_setprio 1
	s_waitcnt lgkmcnt(0)
	v_mfma_f32_16x16x32_bf16 v[126:129], v[150:153], v[186:189], v[126:129]
	v_mfma_f32_16x16x32_bf16 v[126:129], v[154:157], v[190:193], v[126:129]
	v_mfma_f32_16x16x32_bf16 v[122:125], v[158:161], v[186:189], v[122:125]
	v_mfma_f32_16x16x32_bf16 v[122:125], v[166:169], v[190:193], v[122:125]
	v_mfma_f32_16x16x32_bf16 v[118:121], v[150:153], v[194:197], v[118:121]
	v_mfma_f32_16x16x32_bf16 v[118:121], v[154:157], v[202:205], v[118:121]
	v_mfma_f32_16x16x32_bf16 v[110:113], v[158:161], v[194:197], v[110:113]
	v_mfma_f32_16x16x32_bf16 v[110:113], v[166:169], v[202:205], v[110:113]
	v_mfma_f32_16x16x32_bf16 v[102:105], v[150:153], v[206:209], v[102:105]
	v_mfma_f32_16x16x32_bf16 v[102:105], v[154:157], v[210:213], v[102:105]
	v_mfma_f32_16x16x32_bf16 v[94:97], v[158:161], v[206:209], v[94:97]
	v_mfma_f32_16x16x32_bf16 v[94:97], v[166:169], v[210:213], v[94:97]
	v_mfma_f32_16x16x32_bf16 v[86:89], v[150:153], v[214:217], v[86:89]
	v_mfma_f32_16x16x32_bf16 v[86:89], v[154:157], v[218:221], v[86:89]
	v_mfma_f32_16x16x32_bf16 v[78:81], v[158:161], v[214:217], v[78:81]
	v_mfma_f32_16x16x32_bf16 v[78:81], v[166:169], v[218:221], v[78:81]
	s_setprio 0
	s_setprio 1
	v_mfma_f32_16x16x32_bf16 v[114:117], v[170:173], v[186:189], v[114:117]
	v_mfma_f32_16x16x32_bf16 v[114:117], v[174:177], v[190:193], v[114:117]
	v_mfma_f32_16x16x32_bf16 v[106:109], v[178:181], v[186:189], v[106:109]
	v_mfma_f32_16x16x32_bf16 v[106:109], v[182:185], v[190:193], v[106:109]
	v_mfma_f32_16x16x32_bf16 v[98:101], v[170:173], v[194:197], v[98:101]
	v_mfma_f32_16x16x32_bf16 v[98:101], v[174:177], v[202:205], v[98:101]
	v_mfma_f32_16x16x32_bf16 v[90:93], v[178:181], v[194:197], v[90:93]
	v_mfma_f32_16x16x32_bf16 v[90:93], v[182:185], v[202:205], v[90:93]
	v_mfma_f32_16x16x32_bf16 v[82:85], v[170:173], v[206:209], v[82:85]
	v_mfma_f32_16x16x32_bf16 v[82:85], v[174:177], v[210:213], v[82:85]
	v_mfma_f32_16x16x32_bf16 v[74:77], v[178:181], v[206:209], v[74:77]
	v_mfma_f32_16x16x32_bf16 v[74:77], v[182:185], v[210:213], v[74:77]
	v_mfma_f32_16x16x32_bf16 v[70:73], v[170:173], v[214:217], v[70:73]
	v_mfma_f32_16x16x32_bf16 v[70:73], v[174:177], v[218:221], v[70:73]
	v_mfma_f32_16x16x32_bf16 v[66:69], v[178:181], v[214:217], v[66:69]
	v_mfma_f32_16x16x32_bf16 v[66:69], v[182:185], v[218:221], v[66:69]
	s_setprio 0
	s_barrier
	s_mov_b32 m0, s97
	v_lshl_add_u64 v[198:199], s[66:67], 0, v[136:137]
	ds_read_b128 v[186:189], v148 offset:16384
	ds_read_b128 v[190:193], v148 offset:17408
	ds_read_b128 v[194:197], v148 offset:18432
	ds_read_b128 v[202:205], v148 offset:19456
	ds_read_b128 v[206:209], v148 offset:20480
	ds_read_b128 v[210:213], v148 offset:21504
	ds_read_b128 v[214:217], v148 offset:22528
	ds_read_b128 v[218:221], v148 offset:23552
	global_load_lds_dwordx4 v[198:199], off
	v_lshl_add_u64 v[222:223], s[66:67], 0, v[132:133]
	s_mov_b32 m0, s94
	v_lshl_add_u64 v[224:225], s[68:69], 0, v[136:137]
	global_load_lds_dwordx4 v[222:223], off
	s_mov_b32 m0, s96
	v_lshl_add_u64 v[226:227], s[64:65], 0, v[134:135]
	global_load_lds_dwordx4 v[224:225], off
	v_lshl_add_u64 v[224:225], s[68:69], 0, v[132:133]
	s_mov_b32 m0, s95
	s_nop 0
	global_load_lds_dwordx4 v[224:225], off
	v_lshl_add_u64 v[224:225], s[64:65], 0, v[138:139]
	s_mov_b32 m0, s53
	s_nop 0
	global_load_lds_dwordx4 v[224:225], off
	s_mov_b32 m0, s75
	s_nop 0
	global_load_lds_dwordx4 v[226:227], off
	s_waitcnt vmcnt(8)
	s_waitcnt lgkmcnt(0)
	s_barrier
	s_setprio 1
	s_waitcnt lgkmcnt(0)
	v_mfma_f32_16x16x32_bf16 v[62:65], v[150:153], v[186:189], v[62:65]
	v_mfma_f32_16x16x32_bf16 v[62:65], v[154:157], v[190:193], v[62:65]
	v_mfma_f32_16x16x32_bf16 v[58:61], v[158:161], v[186:189], v[58:61]
	v_mfma_f32_16x16x32_bf16 v[58:61], v[166:169], v[190:193], v[58:61]
	v_mfma_f32_16x16x32_bf16 v[54:57], v[150:153], v[194:197], v[54:57]
	v_mfma_f32_16x16x32_bf16 v[54:57], v[154:157], v[202:205], v[54:57]
	v_mfma_f32_16x16x32_bf16 v[46:49], v[158:161], v[194:197], v[46:49]
	v_mfma_f32_16x16x32_bf16 v[46:49], v[166:169], v[202:205], v[46:49]
	v_mfma_f32_16x16x32_bf16 v[38:41], v[150:153], v[206:209], v[38:41]
	v_mfma_f32_16x16x32_bf16 v[38:41], v[154:157], v[210:213], v[38:41]
	v_mfma_f32_16x16x32_bf16 v[30:33], v[158:161], v[206:209], v[30:33]
	v_mfma_f32_16x16x32_bf16 v[30:33], v[166:169], v[210:213], v[30:33]
	v_mfma_f32_16x16x32_bf16 v[22:25], v[150:153], v[214:217], v[22:25]
	v_mfma_f32_16x16x32_bf16 v[22:25], v[154:157], v[218:221], v[22:25]
	v_mfma_f32_16x16x32_bf16 v[14:17], v[158:161], v[214:217], v[14:17]
	v_mfma_f32_16x16x32_bf16 v[14:17], v[166:169], v[218:221], v[14:17]
	s_setprio 0
	s_setprio 1
	v_mfma_f32_16x16x32_bf16 v[50:53], v[170:173], v[186:189], v[50:53]
	v_mfma_f32_16x16x32_bf16 v[50:53], v[174:177], v[190:193], v[50:53]
	v_mfma_f32_16x16x32_bf16 v[42:45], v[178:181], v[186:189], v[42:45]
	v_mfma_f32_16x16x32_bf16 v[42:45], v[182:185], v[190:193], v[42:45]
	v_mfma_f32_16x16x32_bf16 v[34:37], v[170:173], v[194:197], v[34:37]
	v_mfma_f32_16x16x32_bf16 v[34:37], v[174:177], v[202:205], v[34:37]
	v_mfma_f32_16x16x32_bf16 v[26:29], v[178:181], v[194:197], v[26:29]
	v_mfma_f32_16x16x32_bf16 v[26:29], v[182:185], v[202:205], v[26:29]
	v_mfma_f32_16x16x32_bf16 v[18:21], v[170:173], v[206:209], v[18:21]
	v_mfma_f32_16x16x32_bf16 v[18:21], v[174:177], v[210:213], v[18:21]
	v_mfma_f32_16x16x32_bf16 v[10:13], v[178:181], v[206:209], v[10:13]
	v_mfma_f32_16x16x32_bf16 v[10:13], v[182:185], v[210:213], v[10:13]
	v_mfma_f32_16x16x32_bf16 v[6:9], v[170:173], v[214:217], v[6:9]
	v_mfma_f32_16x16x32_bf16 v[6:9], v[174:177], v[218:221], v[6:9]
	v_mfma_f32_16x16x32_bf16 v[2:5], v[178:181], v[214:217], v[2:5]
	v_mfma_f32_16x16x32_bf16 v[2:5], v[182:185], v[218:221], v[2:5]
	s_setprio 0
	s_barrier
	v_add_u32_e32 v149, s93, v145
	ds_read_b128 v[150:153], v149
	ds_read_b128 v[154:157], v149 offset:1024
	ds_read_b128 v[158:161], v149 offset:2048
	ds_read_b128 v[166:169], v149 offset:3072
	v_add_u32_e32 v149, s92, v145
	ds_read_b128 v[170:173], v149
	ds_read_b128 v[174:177], v149 offset:1024
	ds_read_b128 v[178:181], v149 offset:2048
	ds_read_b128 v[182:185], v149 offset:3072
	s_mov_b32 m0, s76
	v_lshl_add_u64 v[228:229], s[62:63], 0, v[138:139]
	ds_read_b128 v[186:189], v148 offset:32768
	ds_read_b128 v[190:193], v148 offset:33792
	ds_read_b128 v[194:197], v148 offset:34816
	ds_read_b128 v[202:205], v148 offset:35840
	ds_read_b128 v[206:209], v148 offset:36864
	ds_read_b128 v[210:213], v148 offset:37888
	ds_read_b128 v[214:217], v148 offset:38912
	ds_read_b128 v[218:221], v148 offset:39936
	global_load_lds_dwordx4 v[228:229], off
	v_lshl_add_u64 v[228:229], s[62:63], 0, v[134:135]
	s_mov_b32 m0, s77
	s_nop 0
	global_load_lds_dwordx4 v[228:229], off
	s_waitcnt vmcnt(8)
	s_waitcnt lgkmcnt(0)
	s_barrier
	s_setprio 1
	s_waitcnt lgkmcnt(0)
	v_mfma_f32_16x16x32_bf16 v[126:129], v[150:153], v[186:189], v[126:129]
	v_mfma_f32_16x16x32_bf16 v[126:129], v[154:157], v[190:193], v[126:129]
	v_mfma_f32_16x16x32_bf16 v[122:125], v[158:161], v[186:189], v[122:125]
	v_mfma_f32_16x16x32_bf16 v[122:125], v[166:169], v[190:193], v[122:125]
	v_mfma_f32_16x16x32_bf16 v[118:121], v[150:153], v[194:197], v[118:121]
	v_mfma_f32_16x16x32_bf16 v[118:121], v[154:157], v[202:205], v[118:121]
	v_mfma_f32_16x16x32_bf16 v[110:113], v[158:161], v[194:197], v[110:113]
	v_mfma_f32_16x16x32_bf16 v[110:113], v[166:169], v[202:205], v[110:113]
	v_mfma_f32_16x16x32_bf16 v[102:105], v[150:153], v[206:209], v[102:105]
	v_mfma_f32_16x16x32_bf16 v[102:105], v[154:157], v[210:213], v[102:105]
	v_mfma_f32_16x16x32_bf16 v[94:97], v[158:161], v[206:209], v[94:97]
	v_mfma_f32_16x16x32_bf16 v[94:97], v[166:169], v[210:213], v[94:97]
	v_mfma_f32_16x16x32_bf16 v[86:89], v[150:153], v[214:217], v[86:89]
	v_mfma_f32_16x16x32_bf16 v[86:89], v[154:157], v[218:221], v[86:89]
	v_mfma_f32_16x16x32_bf16 v[78:81], v[158:161], v[214:217], v[78:81]
	v_mfma_f32_16x16x32_bf16 v[78:81], v[166:169], v[218:221], v[78:81]
	s_setprio 0
	s_setprio 1
	v_mfma_f32_16x16x32_bf16 v[114:117], v[170:173], v[186:189], v[114:117]
	v_mfma_f32_16x16x32_bf16 v[114:117], v[174:177], v[190:193], v[114:117]
	v_mfma_f32_16x16x32_bf16 v[106:109], v[178:181], v[186:189], v[106:109]
	v_mfma_f32_16x16x32_bf16 v[106:109], v[182:185], v[190:193], v[106:109]
	v_mfma_f32_16x16x32_bf16 v[98:101], v[170:173], v[194:197], v[98:101]
	v_mfma_f32_16x16x32_bf16 v[98:101], v[174:177], v[202:205], v[98:101]
	v_mfma_f32_16x16x32_bf16 v[90:93], v[178:181], v[194:197], v[90:93]
	v_mfma_f32_16x16x32_bf16 v[90:93], v[182:185], v[202:205], v[90:93]
	v_mfma_f32_16x16x32_bf16 v[82:85], v[170:173], v[206:209], v[82:85]
	v_mfma_f32_16x16x32_bf16 v[82:85], v[174:177], v[210:213], v[82:85]
	v_mfma_f32_16x16x32_bf16 v[74:77], v[178:181], v[206:209], v[74:77]
	v_mfma_f32_16x16x32_bf16 v[74:77], v[182:185], v[210:213], v[74:77]
	v_mfma_f32_16x16x32_bf16 v[70:73], v[170:173], v[214:217], v[70:73]
	v_mfma_f32_16x16x32_bf16 v[70:73], v[174:177], v[218:221], v[70:73]
	v_mfma_f32_16x16x32_bf16 v[66:69], v[178:181], v[214:217], v[66:69]
	v_mfma_f32_16x16x32_bf16 v[66:69], v[182:185], v[218:221], v[66:69]
	s_setprio 0
	s_barrier
	s_mov_b32 m0, s91
	v_lshl_add_u64 v[198:199], v[198:199], 0, s[14:15]
	ds_read_b128 v[186:189], v148 offset:49152
	ds_read_b128 v[190:193], v148 offset:50176
	ds_read_b128 v[194:197], v148 offset:51200
	ds_read_b128 v[202:205], v148 offset:52224
	ds_read_b128 v[206:209], v148 offset:53248
	ds_read_b128 v[210:213], v148 offset:54272
	ds_read_b128 v[214:217], v148 offset:55296
	ds_read_b128 v[218:221], v148 offset:56320
	global_load_lds_dwordx4 v[198:199], off
	v_lshl_add_u64 v[198:199], v[222:223], 0, s[14:15]
	s_mov_b32 m0, s89
	s_nop 0
	global_load_lds_dwordx4 v[198:199], off
	v_lshl_add_u64 v[198:199], s[60:61], 0, v[136:137]
	s_mov_b32 m0, s90
	s_nop 0
	global_load_lds_dwordx4 v[198:199], off
	v_lshl_add_u64 v[198:199], s[60:61], 0, v[132:133]
	s_mov_b32 m0, s44
	s_nop 0
	global_load_lds_dwordx4 v[198:199], off
	v_lshl_add_u64 v[198:199], v[224:225], 0, s[14:15]
	s_mov_b32 m0, s79
	s_nop 0
	global_load_lds_dwordx4 v[198:199], off
	v_lshl_add_u64 v[198:199], v[226:227], 0, s[14:15]
	s_mov_b32 m0, s80
	s_nop 0
	global_load_lds_dwordx4 v[198:199], off
	s_waitcnt vmcnt(8)
	s_waitcnt lgkmcnt(0)
	s_barrier
	s_setprio 1
	s_waitcnt lgkmcnt(0)
	v_mfma_f32_16x16x32_bf16 v[62:65], v[150:153], v[186:189], v[62:65]
	v_mfma_f32_16x16x32_bf16 v[62:65], v[154:157], v[190:193], v[62:65]
	v_mfma_f32_16x16x32_bf16 v[58:61], v[158:161], v[186:189], v[58:61]
	v_mfma_f32_16x16x32_bf16 v[58:61], v[166:169], v[190:193], v[58:61]
	v_mfma_f32_16x16x32_bf16 v[54:57], v[150:153], v[194:197], v[54:57]
	v_mfma_f32_16x16x32_bf16 v[54:57], v[154:157], v[202:205], v[54:57]
	v_mfma_f32_16x16x32_bf16 v[46:49], v[158:161], v[194:197], v[46:49]
	v_mfma_f32_16x16x32_bf16 v[46:49], v[166:169], v[202:205], v[46:49]
	v_mfma_f32_16x16x32_bf16 v[38:41], v[150:153], v[206:209], v[38:41]
	v_mfma_f32_16x16x32_bf16 v[38:41], v[154:157], v[210:213], v[38:41]
	v_mfma_f32_16x16x32_bf16 v[30:33], v[158:161], v[206:209], v[30:33]
	v_mfma_f32_16x16x32_bf16 v[30:33], v[166:169], v[210:213], v[30:33]
	v_mfma_f32_16x16x32_bf16 v[22:25], v[150:153], v[214:217], v[22:25]
	v_mfma_f32_16x16x32_bf16 v[22:25], v[154:157], v[218:221], v[22:25]
	v_mfma_f32_16x16x32_bf16 v[14:17], v[158:161], v[214:217], v[14:17]
	v_mfma_f32_16x16x32_bf16 v[14:17], v[166:169], v[218:221], v[14:17]
	s_setprio 0
	s_setprio 1
	v_mfma_f32_16x16x32_bf16 v[50:53], v[170:173], v[186:189], v[50:53]
	v_mfma_f32_16x16x32_bf16 v[50:53], v[174:177], v[190:193], v[50:53]
	v_mfma_f32_16x16x32_bf16 v[42:45], v[178:181], v[186:189], v[42:45]
	v_mfma_f32_16x16x32_bf16 v[42:45], v[182:185], v[190:193], v[42:45]
	v_mfma_f32_16x16x32_bf16 v[34:37], v[170:173], v[194:197], v[34:37]
	v_mfma_f32_16x16x32_bf16 v[34:37], v[174:177], v[202:205], v[34:37]
	v_mfma_f32_16x16x32_bf16 v[26:29], v[178:181], v[194:197], v[26:29]
	v_mfma_f32_16x16x32_bf16 v[26:29], v[182:185], v[202:205], v[26:29]
	v_mfma_f32_16x16x32_bf16 v[18:21], v[170:173], v[206:209], v[18:21]
	v_mfma_f32_16x16x32_bf16 v[18:21], v[174:177], v[210:213], v[18:21]
	v_mfma_f32_16x16x32_bf16 v[10:13], v[178:181], v[206:209], v[10:13]
	v_mfma_f32_16x16x32_bf16 v[10:13], v[182:185], v[210:213], v[10:13]
	v_mfma_f32_16x16x32_bf16 v[6:9], v[170:173], v[214:217], v[6:9]
	v_mfma_f32_16x16x32_bf16 v[6:9], v[174:177], v[218:221], v[6:9]
	v_mfma_f32_16x16x32_bf16 v[2:5], v[178:181], v[214:217], v[2:5]
	v_mfma_f32_16x16x32_bf16 v[2:5], v[182:185], v[218:221], v[2:5]
	s_setprio 0
	s_barrier
	s_movk_i32 s44, 0x100
	s_andn2_b64 vcc, exec, s[58:59]
	s_mov_b64 s[60:61], -1
	s_mov_b64 s[58:59], 0
	s_cbranch_vccz .LBB0_1667
	s_and_b64 vcc, exec, s[16:17]
	s_cbranch_vccz .LBB0_1670
	s_barrier

.LBB0_1685:
	ds_read_b128 v[156:159], v153
	ds_read_b128 v[166:169], v153 offset:1024
	ds_read_b128 v[170:173], v153 offset:2048
	ds_read_b128 v[174:177], v153 offset:3072
	ds_read_b128 v[178:181], v154
	ds_read_b128 v[182:185], v154 offset:1024
	ds_read_b128 v[186:189], v154 offset:2048
	ds_read_b128 v[190:193], v154 offset:3072
	s_add_u32 s36, s56, 0xfff00080
	s_addc_u32 s37, s57, -1
	s_cmp_eq_u32 s78, 60
	s_cselect_b32 s61, s25, s37
	s_cselect_b32 s60, s74, s36
	s_cselect_b32 s59, s21, s77
	s_cselect_b32 s58, s75, s76
	v_lshl_add_u64 v[160:161], s[56:57], 0, v[140:141]
	s_add_i32 m0, s55, 0xc000
	ds_read_b128 v[194:197], v155
	ds_read_b128 v[202:205], v155 offset:1024
	ds_read_b128 v[206:209], v155 offset:2048
	ds_read_b128 v[210:213], v155 offset:3072
	ds_read_b128 v[214:217], v155 offset:4096
	ds_read_b128 v[218:221], v155 offset:5120
	ds_read_b128 v[222:225], v155 offset:6144
	ds_read_b128 v[226:229], v155 offset:7168
	global_load_lds_dwordx4 v[160:161], off
	v_lshl_add_u64 v[160:161], s[56:57], 0, v[142:143]
	s_add_i32 m0, s55, 0xe000
	s_nop 0
	global_load_lds_dwordx4 v[160:161], off
	s_waitcnt vmcnt(8)
	s_waitcnt lgkmcnt(0)
	s_barrier
	s_setprio 1
	s_waitcnt lgkmcnt(0)
	v_mfma_f32_16x16x32_bf16 v[126:129], v[156:159], v[194:197], v[126:129]
	v_mfma_f32_16x16x32_bf16 v[126:129], v[166:169], v[202:205], v[126:129]
	v_mfma_f32_16x16x32_bf16 v[122:125], v[170:173], v[194:197], v[122:125]
	v_mfma_f32_16x16x32_bf16 v[122:125], v[174:177], v[202:205], v[122:125]
	v_mfma_f32_16x16x32_bf16 v[118:121], v[156:159], v[206:209], v[118:121]
	v_mfma_f32_16x16x32_bf16 v[118:121], v[166:169], v[210:213], v[118:121]
	v_mfma_f32_16x16x32_bf16 v[110:113], v[170:173], v[206:209], v[110:113]
	v_mfma_f32_16x16x32_bf16 v[110:113], v[174:177], v[210:213], v[110:113]
	v_mfma_f32_16x16x32_bf16 v[102:105], v[156:159], v[214:217], v[102:105]
	v_mfma_f32_16x16x32_bf16 v[102:105], v[166:169], v[218:221], v[102:105]
	v_mfma_f32_16x16x32_bf16 v[94:97], v[170:173], v[214:217], v[94:97]
	v_mfma_f32_16x16x32_bf16 v[94:97], v[174:177], v[218:221], v[94:97]
	v_mfma_f32_16x16x32_bf16 v[86:89], v[156:159], v[222:225], v[86:89]
	v_mfma_f32_16x16x32_bf16 v[86:89], v[166:169], v[226:229], v[86:89]
	v_mfma_f32_16x16x32_bf16 v[78:81], v[170:173], v[222:225], v[78:81]
	v_mfma_f32_16x16x32_bf16 v[78:81], v[174:177], v[226:229], v[78:81]
	s_setprio 0
	s_setprio 1
	v_mfma_f32_16x16x32_bf16 v[114:117], v[178:181], v[194:197], v[114:117]
	v_mfma_f32_16x16x32_bf16 v[114:117], v[182:185], v[202:205], v[114:117]
	v_mfma_f32_16x16x32_bf16 v[106:109], v[186:189], v[194:197], v[106:109]
	v_mfma_f32_16x16x32_bf16 v[106:109], v[190:193], v[202:205], v[106:109]
	v_mfma_f32_16x16x32_bf16 v[98:101], v[178:181], v[206:209], v[98:101]
	v_mfma_f32_16x16x32_bf16 v[98:101], v[182:185], v[210:213], v[98:101]
	v_mfma_f32_16x16x32_bf16 v[90:93], v[186:189], v[206:209], v[90:93]
	v_mfma_f32_16x16x32_bf16 v[90:93], v[190:193], v[210:213], v[90:93]
	v_mfma_f32_16x16x32_bf16 v[82:85], v[178:181], v[214:217], v[82:85]
	v_mfma_f32_16x16x32_bf16 v[82:85], v[182:185], v[218:221], v[82:85]
	v_mfma_f32_16x16x32_bf16 v[74:77], v[186:189], v[214:217], v[74:77]
	v_mfma_f32_16x16x32_bf16 v[74:77], v[190:193], v[218:221], v[74:77]
	v_mfma_f32_16x16x32_bf16 v[70:73], v[178:181], v[222:225], v[70:73]
	v_mfma_f32_16x16x32_bf16 v[70:73], v[182:185], v[226:229], v[70:73]
	v_mfma_f32_16x16x32_bf16 v[66:69], v[186:189], v[222:225], v[66:69]
	v_mfma_f32_16x16x32_bf16 v[66:69], v[190:193], v[226:229], v[66:69]
	s_setprio 0
	s_barrier
	s_add_i32 s36, s68, s38
	v_lshl_add_u64 v[160:161], s[58:59], 0, v[136:137]
	s_mov_b32 m0, s36
	ds_read_b128 v[194:197], v155 offset:16384
	ds_read_b128 v[202:205], v155 offset:17408
	ds_read_b128 v[206:209], v155 offset:18432
	ds_read_b128 v[210:213], v155 offset:19456
	ds_read_b128 v[214:217], v155 offset:20480
	ds_read_b128 v[218:221], v155 offset:21504
	ds_read_b128 v[222:225], v155 offset:22528
	ds_read_b128 v[226:229], v155 offset:23552
	global_load_lds_dwordx4 v[160:161], off
	s_add_i32 m0, s36, 0x2000
	s_add_u32 s80, s58, 0x100000
	v_lshl_add_u64 v[198:199], s[58:59], 0, v[132:133]
	s_addc_u32 s81, s59, 0
	s_add_i32 s36, s69, s38
	global_load_lds_dwordx4 v[198:199], off
	v_lshl_add_u64 v[230:231], s[80:81], 0, v[136:137]
	s_mov_b32 m0, s36
	v_lshl_add_u64 v[232:233], s[60:61], 0, v[134:135]
	global_load_lds_dwordx4 v[230:231], off
	v_lshl_add_u64 v[230:231], s[80:81], 0, v[132:133]
	s_add_i32 m0, s36, 0x2000
	s_nop 0
	global_load_lds_dwordx4 v[230:231], off
	v_lshl_add_u64 v[230:231], s[60:61], 0, v[138:139]
	s_mov_b32 m0, s55
	s_nop 0
	global_load_lds_dwordx4 v[230:231], off
	s_mov_b32 m0, s63
	s_nop 0
	global_load_lds_dwordx4 v[232:233], off
	s_waitcnt vmcnt(8)
	s_waitcnt lgkmcnt(0)
	s_barrier
	s_setprio 1
	s_waitcnt lgkmcnt(0)
	v_mfma_f32_16x16x32_bf16 v[62:65], v[156:159], v[194:197], v[62:65]
	v_mfma_f32_16x16x32_bf16 v[62:65], v[166:169], v[202:205], v[62:65]
	v_mfma_f32_16x16x32_bf16 v[58:61], v[170:173], v[194:197], v[58:61]
	v_mfma_f32_16x16x32_bf16 v[58:61], v[174:177], v[202:205], v[58:61]
	v_mfma_f32_16x16x32_bf16 v[54:57], v[156:159], v[206:209], v[54:57]
	v_mfma_f32_16x16x32_bf16 v[54:57], v[166:169], v[210:213], v[54:57]
	v_mfma_f32_16x16x32_bf16 v[46:49], v[170:173], v[206:209], v[46:49]
	v_mfma_f32_16x16x32_bf16 v[46:49], v[174:177], v[210:213], v[46:49]
	v_mfma_f32_16x16x32_bf16 v[38:41], v[156:159], v[214:217], v[38:41]
	v_mfma_f32_16x16x32_bf16 v[38:41], v[166:169], v[218:221], v[38:41]
	v_mfma_f32_16x16x32_bf16 v[30:33], v[170:173], v[214:217], v[30:33]
	v_mfma_f32_16x16x32_bf16 v[30:33], v[174:177], v[218:221], v[30:33]
	v_mfma_f32_16x16x32_bf16 v[22:25], v[156:159], v[222:225], v[22:25]
	v_mfma_f32_16x16x32_bf16 v[22:25], v[166:169], v[226:229], v[22:25]
	v_mfma_f32_16x16x32_bf16 v[14:17], v[170:173], v[222:225], v[14:17]
	v_mfma_f32_16x16x32_bf16 v[14:17], v[174:177], v[226:229], v[14:17]
	s_setprio 0
	s_setprio 1
	v_mfma_f32_16x16x32_bf16 v[50:53], v[178:181], v[194:197], v[50:53]
	v_mfma_f32_16x16x32_bf16 v[50:53], v[182:185], v[202:205], v[50:53]
	v_mfma_f32_16x16x32_bf16 v[42:45], v[186:189], v[194:197], v[42:45]
	v_mfma_f32_16x16x32_bf16 v[42:45], v[190:193], v[202:205], v[42:45]
	v_mfma_f32_16x16x32_bf16 v[34:37], v[178:181], v[206:209], v[34:37]
	v_mfma_f32_16x16x32_bf16 v[34:37], v[182:185], v[210:213], v[34:37]
	v_mfma_f32_16x16x32_bf16 v[26:29], v[186:189], v[206:209], v[26:29]
	v_mfma_f32_16x16x32_bf16 v[26:29], v[190:193], v[210:213], v[26:29]
	v_mfma_f32_16x16x32_bf16 v[18:21], v[178:181], v[214:217], v[18:21]
	v_mfma_f32_16x16x32_bf16 v[18:21], v[182:185], v[218:221], v[18:21]
	v_mfma_f32_16x16x32_bf16 v[10:13], v[186:189], v[214:217], v[10:13]
	v_mfma_f32_16x16x32_bf16 v[10:13], v[190:193], v[218:221], v[10:13]
	v_mfma_f32_16x16x32_bf16 v[6:9], v[178:181], v[222:225], v[6:9]
	v_mfma_f32_16x16x32_bf16 v[6:9], v[182:185], v[226:229], v[6:9]
	v_mfma_f32_16x16x32_bf16 v[2:5], v[186:189], v[222:225], v[2:5]
	v_mfma_f32_16x16x32_bf16 v[2:5], v[190:193], v[226:229], v[2:5]
	s_setprio 0
	s_barrier
	s_add_i32 s36, 0, 0x18000
	v_add_u32_e32 v165, s36, v151
	s_add_i32 s37, 0, 0x1c000
	ds_read_b128 v[156:159], v165
	ds_read_b128 v[166:169], v165 offset:1024
	ds_read_b128 v[170:173], v165 offset:2048
	ds_read_b128 v[174:177], v165 offset:3072
	v_add_u32_e32 v165, s37, v151
	ds_read_b128 v[178:181], v165
	ds_read_b128 v[182:185], v165 offset:1024
	ds_read_b128 v[186:189], v165 offset:2048
	ds_read_b128 v[190:193], v165 offset:3072
	s_add_u32 s60, s60, 0x100000
	s_addc_u32 s61, s61, 0
	s_mov_b32 m0, s64
	v_lshl_add_u64 v[234:235], s[60:61], 0, v[138:139]
	ds_read_b128 v[194:197], v155 offset:32768
	ds_read_b128 v[202:205], v155 offset:33792
	ds_read_b128 v[206:209], v155 offset:34816
	ds_read_b128 v[210:213], v155 offset:35840
	ds_read_b128 v[214:217], v155 offset:36864
	ds_read_b128 v[218:221], v155 offset:37888
	ds_read_b128 v[222:225], v155 offset:38912
	ds_read_b128 v[226:229], v155 offset:39936
	global_load_lds_dwordx4 v[234:235], off
	v_lshl_add_u64 v[234:235], s[60:61], 0, v[134:135]
	s_mov_b32 m0, s65
	s_nop 0
	global_load_lds_dwordx4 v[234:235], off
	s_waitcnt vmcnt(8)
	s_waitcnt lgkmcnt(0)
	s_barrier
	s_setprio 1
	s_waitcnt lgkmcnt(0)
	v_mfma_f32_16x16x32_bf16 v[126:129], v[156:159], v[194:197], v[126:129]
	v_mfma_f32_16x16x32_bf16 v[126:129], v[166:169], v[202:205], v[126:129]
	v_mfma_f32_16x16x32_bf16 v[122:125], v[170:173], v[194:197], v[122:125]
	v_mfma_f32_16x16x32_bf16 v[122:125], v[174:177], v[202:205], v[122:125]
	v_mfma_f32_16x16x32_bf16 v[118:121], v[156:159], v[206:209], v[118:121]
	v_mfma_f32_16x16x32_bf16 v[118:121], v[166:169], v[210:213], v[118:121]
	v_mfma_f32_16x16x32_bf16 v[110:113], v[170:173], v[206:209], v[110:113]
	v_mfma_f32_16x16x32_bf16 v[110:113], v[174:177], v[210:213], v[110:113]
	v_mfma_f32_16x16x32_bf16 v[102:105], v[156:159], v[214:217], v[102:105]
	v_mfma_f32_16x16x32_bf16 v[102:105], v[166:169], v[218:221], v[102:105]
	v_mfma_f32_16x16x32_bf16 v[94:97], v[170:173], v[214:217], v[94:97]
	v_mfma_f32_16x16x32_bf16 v[94:97], v[174:177], v[218:221], v[94:97]
	v_mfma_f32_16x16x32_bf16 v[86:89], v[156:159], v[222:225], v[86:89]
	v_mfma_f32_16x16x32_bf16 v[86:89], v[166:169], v[226:229], v[86:89]
	v_mfma_f32_16x16x32_bf16 v[78:81], v[170:173], v[222:225], v[78:81]
	v_mfma_f32_16x16x32_bf16 v[78:81], v[174:177], v[226:229], v[78:81]
	s_setprio 0
	s_setprio 1
	v_mfma_f32_16x16x32_bf16 v[114:117], v[178:181], v[194:197], v[114:117]
	v_mfma_f32_16x16x32_bf16 v[114:117], v[182:185], v[202:205], v[114:117]
	v_mfma_f32_16x16x32_bf16 v[106:109], v[186:189], v[194:197], v[106:109]
	v_mfma_f32_16x16x32_bf16 v[106:109], v[190:193], v[202:205], v[106:109]
	v_mfma_f32_16x16x32_bf16 v[98:101], v[178:181], v[206:209], v[98:101]
	v_mfma_f32_16x16x32_bf16 v[98:101], v[182:185], v[210:213], v[98:101]
	v_mfma_f32_16x16x32_bf16 v[90:93], v[186:189], v[206:209], v[90:93]
	v_mfma_f32_16x16x32_bf16 v[90:93], v[190:193], v[210:213], v[90:93]
	v_mfma_f32_16x16x32_bf16 v[82:85], v[178:181], v[214:217], v[82:85]
	v_mfma_f32_16x16x32_bf16 v[82:85], v[182:185], v[218:221], v[82:85]
	v_mfma_f32_16x16x32_bf16 v[74:77], v[186:189], v[214:217], v[74:77]
	v_mfma_f32_16x16x32_bf16 v[74:77], v[190:193], v[218:221], v[74:77]
	v_mfma_f32_16x16x32_bf16 v[70:73], v[178:181], v[222:225], v[70:73]
	v_mfma_f32_16x16x32_bf16 v[70:73], v[182:185], v[226:229], v[70:73]
	v_mfma_f32_16x16x32_bf16 v[66:69], v[186:189], v[222:225], v[66:69]
	v_mfma_f32_16x16x32_bf16 v[66:69], v[190:193], v[226:229], v[66:69]
	s_setprio 0
	s_barrier
	s_add_i32 s36, s36, s38
	v_lshl_add_u64 v[160:161], v[160:161], 0, s[16:17]
	s_mov_b32 m0, s36
	ds_read_b128 v[194:197], v155 offset:49152
	ds_read_b128 v[202:205], v155 offset:50176
	ds_read_b128 v[206:209], v155 offset:51200
	ds_read_b128 v[210:213], v155 offset:52224
	ds_read_b128 v[214:217], v155 offset:53248
	ds_read_b128 v[218:221], v155 offset:54272
	ds_read_b128 v[222:225], v155 offset:55296
	ds_read_b128 v[226:229], v155 offset:56320
	global_load_lds_dwordx4 v[160:161], off
	s_add_i32 m0, s36, 0x2000
	s_add_u32 s58, s58, 0x100080
	v_lshl_add_u64 v[160:161], v[198:199], 0, s[16:17]
	s_addc_u32 s59, s59, 0
	s_add_i32 s36, s37, s38
	global_load_lds_dwordx4 v[160:161], off
	v_lshl_add_u64 v[160:161], s[58:59], 0, v[136:137]
	s_mov_b32 m0, s36
	s_nop 0
	global_load_lds_dwordx4 v[160:161], off
	v_lshl_add_u64 v[160:161], s[58:59], 0, v[132:133]
	s_add_i32 m0, s36, 0x2000
	s_nop 0
	global_load_lds_dwordx4 v[160:161], off
	v_lshl_add_u64 v[160:161], v[230:231], 0, s[16:17]
	s_mov_b32 m0, s66
	s_nop 0
	global_load_lds_dwordx4 v[160:161], off
	v_lshl_add_u64 v[160:161], v[232:233], 0, s[16:17]
	s_mov_b32 m0, s67
	s_nop 0
	global_load_lds_dwordx4 v[160:161], off
	s_waitcnt vmcnt(8)
	s_waitcnt lgkmcnt(0)
	s_barrier
	s_setprio 1
	s_waitcnt lgkmcnt(0)
	v_mfma_f32_16x16x32_bf16 v[62:65], v[156:159], v[194:197], v[62:65]
	v_mfma_f32_16x16x32_bf16 v[62:65], v[166:169], v[202:205], v[62:65]
	v_mfma_f32_16x16x32_bf16 v[58:61], v[170:173], v[194:197], v[58:61]
	v_mfma_f32_16x16x32_bf16 v[58:61], v[174:177], v[202:205], v[58:61]
	v_mfma_f32_16x16x32_bf16 v[54:57], v[156:159], v[206:209], v[54:57]
	v_mfma_f32_16x16x32_bf16 v[54:57], v[166:169], v[210:213], v[54:57]
	v_mfma_f32_16x16x32_bf16 v[46:49], v[170:173], v[206:209], v[46:49]
	v_mfma_f32_16x16x32_bf16 v[46:49], v[174:177], v[210:213], v[46:49]
	v_mfma_f32_16x16x32_bf16 v[38:41], v[156:159], v[214:217], v[38:41]
	v_mfma_f32_16x16x32_bf16 v[38:41], v[166:169], v[218:221], v[38:41]
	v_mfma_f32_16x16x32_bf16 v[30:33], v[170:173], v[214:217], v[30:33]
	v_mfma_f32_16x16x32_bf16 v[30:33], v[174:177], v[218:221], v[30:33]
	v_mfma_f32_16x16x32_bf16 v[22:25], v[156:159], v[222:225], v[22:25]
	v_mfma_f32_16x16x32_bf16 v[22:25], v[166:169], v[226:229], v[22:25]
	v_mfma_f32_16x16x32_bf16 v[14:17], v[170:173], v[222:225], v[14:17]
	v_mfma_f32_16x16x32_bf16 v[14:17], v[174:177], v[226:229], v[14:17]
	s_setprio 0
	s_setprio 1
	v_mfma_f32_16x16x32_bf16 v[50:53], v[178:181], v[194:197], v[50:53]
	v_mfma_f32_16x16x32_bf16 v[50:53], v[182:185], v[202:205], v[50:53]
	v_mfma_f32_16x16x32_bf16 v[42:45], v[186:189], v[194:197], v[42:45]
	v_mfma_f32_16x16x32_bf16 v[42:45], v[190:193], v[202:205], v[42:45]
	v_mfma_f32_16x16x32_bf16 v[34:37], v[178:181], v[206:209], v[34:37]
	v_mfma_f32_16x16x32_bf16 v[34:37], v[182:185], v[210:213], v[34:37]
	v_mfma_f32_16x16x32_bf16 v[26:29], v[186:189], v[206:209], v[26:29]
	v_mfma_f32_16x16x32_bf16 v[26:29], v[190:193], v[210:213], v[26:29]
	v_mfma_f32_16x16x32_bf16 v[18:21], v[178:181], v[214:217], v[18:21]
	v_mfma_f32_16x16x32_bf16 v[18:21], v[182:185], v[218:221], v[18:21]
	v_mfma_f32_16x16x32_bf16 v[10:13], v[186:189], v[214:217], v[10:13]
	v_mfma_f32_16x16x32_bf16 v[10:13], v[190:193], v[218:221], v[10:13]
	v_mfma_f32_16x16x32_bf16 v[6:9], v[178:181], v[222:225], v[6:9]
	v_mfma_f32_16x16x32_bf16 v[6:9], v[182:185], v[226:229], v[6:9]
	v_mfma_f32_16x16x32_bf16 v[2:5], v[186:189], v[222:225], v[2:5]
	v_mfma_f32_16x16x32_bf16 v[2:5], v[190:193], v[226:229], v[2:5]
	s_setprio 0
	s_barrier
	s_add_i32 s78, s78, 2
	s_add_u32 s56, s56, 0x100
	s_addc_u32 s57, s57, 0
	s_add_u32 s76, s76, 0x100
	s_addc_u32 s77, s77, 0
	s_cmp_gt_u32 s78, 61
	s_cbranch_scc0 .LBB0_1685
	s_and_b64 vcc, exec, s[18:19]
	s_cbranch_vccz .LBB0_1688
	s_barrier

.LBB0_1701:
	s_add_u32 s36, s56, s44
	s_addc_u32 s37, s57, 0
	s_add_u32 s64, s36, 0x100
	s_addc_u32 s65, s37, 0
	s_and_b64 s[62:63], s[60:61], exec
	s_cselect_b32 s65, s21, s65
	s_cselect_b32 s64, s86, s64
	s_add_u32 s44, s54, s44
	s_addc_u32 s62, s55, 0
	s_add_u32 s44, s44, 0x100
	s_addc_u32 s62, s62, 0
	s_and_b64 s[60:61], s[60:61], exec
	s_cselect_b32 s67, s25, s62
	s_cselect_b32 s66, s87, s44
	s_add_u32 s70, s36, 0x10080
	s_addc_u32 s71, s37, 0
	s_add_i32 s97, s81, s39
	ds_read_b128 v[152:155], v147
	ds_read_b128 v[156:159], v147 offset:1024
	ds_read_b128 v[166:169], v147 offset:2048
	ds_read_b128 v[170:173], v147 offset:3072
	ds_read_b128 v[174:177], v150
	ds_read_b128 v[178:181], v150 offset:1024
	ds_read_b128 v[182:185], v150 offset:2048
	ds_read_b128 v[186:189], v150 offset:3072
	s_add_i32 m0, s74, 0xc000
	s_add_i32 vcc_lo, s74, 0xe000
	s_add_i32 s94, s97, 0x2000
	s_add_u32 s68, s66, 0x10000
	s_addc_u32 s69, s67, 0
	s_add_i32 s96, s82, s39
	s_add_i32 s95, s96, 0x2000
	s_add_i32 s93, 0, 0x18000
	s_add_i32 s92, 0, 0x1c000
	s_add_u32 s62, s64, 0x10000
	s_addc_u32 s63, s65, 0
	s_add_i32 s91, s93, s39
	s_add_i32 s89, s91, 0x2000
	s_add_u32 s60, s66, 0x10080
	s_addc_u32 s61, s67, 0
	s_add_i32 s90, s92, s39
	s_add_i32 s44, s90, 0x2000
	v_lshl_add_u64 v[160:161], s[70:71], 0, v[138:139]
	ds_read_b128 v[190:193], v151
	ds_read_b128 v[194:197], v151 offset:1024
	ds_read_b128 v[202:205], v151 offset:2048
	ds_read_b128 v[206:209], v151 offset:3072
	ds_read_b128 v[210:213], v151 offset:4096
	ds_read_b128 v[214:217], v151 offset:5120
	ds_read_b128 v[218:221], v151 offset:6144
	ds_read_b128 v[222:225], v151 offset:7168
	global_load_lds_dwordx4 v[160:161], off
	v_lshl_add_u64 v[160:161], s[70:71], 0, v[134:135]
	s_mov_b32 m0, vcc_lo
	s_nop 0
	global_load_lds_dwordx4 v[160:161], off
	s_waitcnt vmcnt(8)
	s_waitcnt lgkmcnt(0)
	s_barrier
	s_setprio 1
	s_waitcnt lgkmcnt(0)
	v_mfma_f32_16x16x32_bf16 v[126:129], v[152:155], v[190:193], v[126:129]
	v_mfma_f32_16x16x32_bf16 v[126:129], v[156:159], v[194:197], v[126:129]
	v_mfma_f32_16x16x32_bf16 v[122:125], v[166:169], v[190:193], v[122:125]
	v_mfma_f32_16x16x32_bf16 v[122:125], v[170:173], v[194:197], v[122:125]
	v_mfma_f32_16x16x32_bf16 v[118:121], v[152:155], v[202:205], v[118:121]
	v_mfma_f32_16x16x32_bf16 v[118:121], v[156:159], v[206:209], v[118:121]
	v_mfma_f32_16x16x32_bf16 v[110:113], v[166:169], v[202:205], v[110:113]
	v_mfma_f32_16x16x32_bf16 v[110:113], v[170:173], v[206:209], v[110:113]
	v_mfma_f32_16x16x32_bf16 v[102:105], v[152:155], v[210:213], v[102:105]
	v_mfma_f32_16x16x32_bf16 v[102:105], v[156:159], v[214:217], v[102:105]
	v_mfma_f32_16x16x32_bf16 v[94:97], v[166:169], v[210:213], v[94:97]
	v_mfma_f32_16x16x32_bf16 v[94:97], v[170:173], v[214:217], v[94:97]
	v_mfma_f32_16x16x32_bf16 v[86:89], v[152:155], v[218:221], v[86:89]
	v_mfma_f32_16x16x32_bf16 v[86:89], v[156:159], v[222:225], v[86:89]
	v_mfma_f32_16x16x32_bf16 v[78:81], v[166:169], v[218:221], v[78:81]
	v_mfma_f32_16x16x32_bf16 v[78:81], v[170:173], v[222:225], v[78:81]
	s_setprio 0
	s_setprio 1
	v_mfma_f32_16x16x32_bf16 v[114:117], v[174:177], v[190:193], v[114:117]
	v_mfma_f32_16x16x32_bf16 v[114:117], v[178:181], v[194:197], v[114:117]
	v_mfma_f32_16x16x32_bf16 v[106:109], v[182:185], v[190:193], v[106:109]
	v_mfma_f32_16x16x32_bf16 v[106:109], v[186:189], v[194:197], v[106:109]
	v_mfma_f32_16x16x32_bf16 v[98:101], v[174:177], v[202:205], v[98:101]
	v_mfma_f32_16x16x32_bf16 v[98:101], v[178:181], v[206:209], v[98:101]
	v_mfma_f32_16x16x32_bf16 v[90:93], v[182:185], v[202:205], v[90:93]
	v_mfma_f32_16x16x32_bf16 v[90:93], v[186:189], v[206:209], v[90:93]
	v_mfma_f32_16x16x32_bf16 v[82:85], v[174:177], v[210:213], v[82:85]
	v_mfma_f32_16x16x32_bf16 v[82:85], v[178:181], v[214:217], v[82:85]
	v_mfma_f32_16x16x32_bf16 v[74:77], v[182:185], v[210:213], v[74:77]
	v_mfma_f32_16x16x32_bf16 v[74:77], v[186:189], v[214:217], v[74:77]
	v_mfma_f32_16x16x32_bf16 v[70:73], v[174:177], v[218:221], v[70:73]
	v_mfma_f32_16x16x32_bf16 v[70:73], v[178:181], v[222:225], v[70:73]
	v_mfma_f32_16x16x32_bf16 v[66:69], v[182:185], v[218:221], v[66:69]
	v_mfma_f32_16x16x32_bf16 v[66:69], v[186:189], v[222:225], v[66:69]
	s_setprio 0
	s_barrier
	s_mov_b32 m0, s97
	v_lshl_add_u64 v[160:161], s[66:67], 0, v[136:137]
	ds_read_b128 v[190:193], v151 offset:16384
	ds_read_b128 v[194:197], v151 offset:17408
	ds_read_b128 v[202:205], v151 offset:18432
	ds_read_b128 v[206:209], v151 offset:19456
	ds_read_b128 v[210:213], v151 offset:20480
	ds_read_b128 v[214:217], v151 offset:21504
	ds_read_b128 v[218:221], v151 offset:22528
	ds_read_b128 v[222:225], v151 offset:23552
	global_load_lds_dwordx4 v[160:161], off
	v_lshl_add_u64 v[198:199], s[66:67], 0, v[132:133]
	s_mov_b32 m0, s94
	v_lshl_add_u64 v[226:227], s[68:69], 0, v[136:137]
	global_load_lds_dwordx4 v[198:199], off
	s_mov_b32 m0, s96
	v_lshl_add_u64 v[228:229], s[64:65], 0, v[134:135]
	global_load_lds_dwordx4 v[226:227], off
	v_lshl_add_u64 v[226:227], s[68:69], 0, v[132:133]
	s_mov_b32 m0, s95
	s_nop 0
	global_load_lds_dwordx4 v[226:227], off
	v_lshl_add_u64 v[226:227], s[64:65], 0, v[138:139]
	s_mov_b32 m0, s74
	s_nop 0
	global_load_lds_dwordx4 v[226:227], off
	s_mov_b32 m0, s75
	s_nop 0
	global_load_lds_dwordx4 v[228:229], off
	s_waitcnt vmcnt(8)
	s_waitcnt lgkmcnt(0)
	s_barrier
	s_setprio 1
	s_waitcnt lgkmcnt(0)
	v_mfma_f32_16x16x32_bf16 v[62:65], v[152:155], v[190:193], v[62:65]
	v_mfma_f32_16x16x32_bf16 v[62:65], v[156:159], v[194:197], v[62:65]
	v_mfma_f32_16x16x32_bf16 v[58:61], v[166:169], v[190:193], v[58:61]
	v_mfma_f32_16x16x32_bf16 v[58:61], v[170:173], v[194:197], v[58:61]
	v_mfma_f32_16x16x32_bf16 v[54:57], v[152:155], v[202:205], v[54:57]
	v_mfma_f32_16x16x32_bf16 v[54:57], v[156:159], v[206:209], v[54:57]
	v_mfma_f32_16x16x32_bf16 v[46:49], v[166:169], v[202:205], v[46:49]
	v_mfma_f32_16x16x32_bf16 v[46:49], v[170:173], v[206:209], v[46:49]
	v_mfma_f32_16x16x32_bf16 v[38:41], v[152:155], v[210:213], v[38:41]
	v_mfma_f32_16x16x32_bf16 v[38:41], v[156:159], v[214:217], v[38:41]
	v_mfma_f32_16x16x32_bf16 v[30:33], v[166:169], v[210:213], v[30:33]
	v_mfma_f32_16x16x32_bf16 v[30:33], v[170:173], v[214:217], v[30:33]
	v_mfma_f32_16x16x32_bf16 v[22:25], v[152:155], v[218:221], v[22:25]
	v_mfma_f32_16x16x32_bf16 v[22:25], v[156:159], v[222:225], v[22:25]
	v_mfma_f32_16x16x32_bf16 v[14:17], v[166:169], v[218:221], v[14:17]
	v_mfma_f32_16x16x32_bf16 v[14:17], v[170:173], v[222:225], v[14:17]
	s_setprio 0
	s_setprio 1
	v_mfma_f32_16x16x32_bf16 v[50:53], v[174:177], v[190:193], v[50:53]
	v_mfma_f32_16x16x32_bf16 v[50:53], v[178:181], v[194:197], v[50:53]
	v_mfma_f32_16x16x32_bf16 v[42:45], v[182:185], v[190:193], v[42:45]
	v_mfma_f32_16x16x32_bf16 v[42:45], v[186:189], v[194:197], v[42:45]
	v_mfma_f32_16x16x32_bf16 v[34:37], v[174:177], v[202:205], v[34:37]
	v_mfma_f32_16x16x32_bf16 v[34:37], v[178:181], v[206:209], v[34:37]
	v_mfma_f32_16x16x32_bf16 v[26:29], v[182:185], v[202:205], v[26:29]
	v_mfma_f32_16x16x32_bf16 v[26:29], v[186:189], v[206:209], v[26:29]
	v_mfma_f32_16x16x32_bf16 v[18:21], v[174:177], v[210:213], v[18:21]
	v_mfma_f32_16x16x32_bf16 v[18:21], v[178:181], v[214:217], v[18:21]
	v_mfma_f32_16x16x32_bf16 v[10:13], v[182:185], v[210:213], v[10:13]
	v_mfma_f32_16x16x32_bf16 v[10:13], v[186:189], v[214:217], v[10:13]
	v_mfma_f32_16x16x32_bf16 v[6:9], v[174:177], v[218:221], v[6:9]
	v_mfma_f32_16x16x32_bf16 v[6:9], v[178:181], v[222:225], v[6:9]
	v_mfma_f32_16x16x32_bf16 v[2:5], v[182:185], v[218:221], v[2:5]
	v_mfma_f32_16x16x32_bf16 v[2:5], v[186:189], v[222:225], v[2:5]
	s_setprio 0
	s_barrier
	v_add_u32_e32 v165, s93, v145
	ds_read_b128 v[152:155], v165
	ds_read_b128 v[156:159], v165 offset:1024
	ds_read_b128 v[166:169], v165 offset:2048
	ds_read_b128 v[170:173], v165 offset:3072
	v_add_u32_e32 v165, s92, v145
	ds_read_b128 v[174:177], v165
	ds_read_b128 v[178:181], v165 offset:1024
	ds_read_b128 v[182:185], v165 offset:2048
	ds_read_b128 v[186:189], v165 offset:3072
	s_mov_b32 m0, s76
	v_lshl_add_u64 v[230:231], s[62:63], 0, v[138:139]
	ds_read_b128 v[190:193], v151 offset:32768
	ds_read_b128 v[194:197], v151 offset:33792
	ds_read_b128 v[202:205], v151 offset:34816
	ds_read_b128 v[206:209], v151 offset:35840
	ds_read_b128 v[210:213], v151 offset:36864
	ds_read_b128 v[214:217], v151 offset:37888
	ds_read_b128 v[218:221], v151 offset:38912
	ds_read_b128 v[222:225], v151 offset:39936
	global_load_lds_dwordx4 v[230:231], off
	v_lshl_add_u64 v[230:231], s[62:63], 0, v[134:135]
	s_mov_b32 m0, s77
	s_nop 0
	global_load_lds_dwordx4 v[230:231], off
	s_waitcnt vmcnt(8)
	s_waitcnt lgkmcnt(0)
	s_barrier
	s_setprio 1
	s_waitcnt lgkmcnt(0)
	v_mfma_f32_16x16x32_bf16 v[126:129], v[152:155], v[190:193], v[126:129]
	v_mfma_f32_16x16x32_bf16 v[126:129], v[156:159], v[194:197], v[126:129]
	v_mfma_f32_16x16x32_bf16 v[122:125], v[166:169], v[190:193], v[122:125]
	v_mfma_f32_16x16x32_bf16 v[122:125], v[170:173], v[194:197], v[122:125]
	v_mfma_f32_16x16x32_bf16 v[118:121], v[152:155], v[202:205], v[118:121]
	v_mfma_f32_16x16x32_bf16 v[118:121], v[156:159], v[206:209], v[118:121]
	v_mfma_f32_16x16x32_bf16 v[110:113], v[166:169], v[202:205], v[110:113]
	v_mfma_f32_16x16x32_bf16 v[110:113], v[170:173], v[206:209], v[110:113]
	v_mfma_f32_16x16x32_bf16 v[102:105], v[152:155], v[210:213], v[102:105]
	v_mfma_f32_16x16x32_bf16 v[102:105], v[156:159], v[214:217], v[102:105]
	v_mfma_f32_16x16x32_bf16 v[94:97], v[166:169], v[210:213], v[94:97]
	v_mfma_f32_16x16x32_bf16 v[94:97], v[170:173], v[214:217], v[94:97]
	v_mfma_f32_16x16x32_bf16 v[86:89], v[152:155], v[218:221], v[86:89]
	v_mfma_f32_16x16x32_bf16 v[86:89], v[156:159], v[222:225], v[86:89]
	v_mfma_f32_16x16x32_bf16 v[78:81], v[166:169], v[218:221], v[78:81]
	v_mfma_f32_16x16x32_bf16 v[78:81], v[170:173], v[222:225], v[78:81]
	s_setprio 0
	s_setprio 1
	v_mfma_f32_16x16x32_bf16 v[114:117], v[174:177], v[190:193], v[114:117]
	v_mfma_f32_16x16x32_bf16 v[114:117], v[178:181], v[194:197], v[114:117]
	v_mfma_f32_16x16x32_bf16 v[106:109], v[182:185], v[190:193], v[106:109]
	v_mfma_f32_16x16x32_bf16 v[106:109], v[186:189], v[194:197], v[106:109]
	v_mfma_f32_16x16x32_bf16 v[98:101], v[174:177], v[202:205], v[98:101]
	v_mfma_f32_16x16x32_bf16 v[98:101], v[178:181], v[206:209], v[98:101]
	v_mfma_f32_16x16x32_bf16 v[90:93], v[182:185], v[202:205], v[90:93]
	v_mfma_f32_16x16x32_bf16 v[90:93], v[186:189], v[206:209], v[90:93]
	v_mfma_f32_16x16x32_bf16 v[82:85], v[174:177], v[210:213], v[82:85]
	v_mfma_f32_16x16x32_bf16 v[82:85], v[178:181], v[214:217], v[82:85]
	v_mfma_f32_16x16x32_bf16 v[74:77], v[182:185], v[210:213], v[74:77]
	v_mfma_f32_16x16x32_bf16 v[74:77], v[186:189], v[214:217], v[74:77]
	v_mfma_f32_16x16x32_bf16 v[70:73], v[174:177], v[218:221], v[70:73]
	v_mfma_f32_16x16x32_bf16 v[70:73], v[178:181], v[222:225], v[70:73]
	v_mfma_f32_16x16x32_bf16 v[66:69], v[182:185], v[218:221], v[66:69]
	v_mfma_f32_16x16x32_bf16 v[66:69], v[186:189], v[222:225], v[66:69]
	s_setprio 0
	s_barrier
	s_mov_b32 m0, s91
	v_lshl_add_u64 v[160:161], v[160:161], 0, s[14:15]
	ds_read_b128 v[190:193], v151 offset:49152
	ds_read_b128 v[194:197], v151 offset:50176
	ds_read_b128 v[202:205], v151 offset:51200
	ds_read_b128 v[206:209], v151 offset:52224
	ds_read_b128 v[210:213], v151 offset:53248
	ds_read_b128 v[214:217], v151 offset:54272
	ds_read_b128 v[218:221], v151 offset:55296
	ds_read_b128 v[222:225], v151 offset:56320
	global_load_lds_dwordx4 v[160:161], off
	v_lshl_add_u64 v[160:161], v[198:199], 0, s[14:15]
	s_mov_b32 m0, s89
	s_nop 0
	global_load_lds_dwordx4 v[160:161], off
	v_lshl_add_u64 v[160:161], s[60:61], 0, v[136:137]
	s_mov_b32 m0, s90
	s_nop 0
	global_load_lds_dwordx4 v[160:161], off
	v_lshl_add_u64 v[160:161], s[60:61], 0, v[132:133]
	s_mov_b32 m0, s44
	s_nop 0
	global_load_lds_dwordx4 v[160:161], off
	v_lshl_add_u64 v[160:161], v[226:227], 0, s[14:15]
	s_mov_b32 m0, s79
	s_nop 0
	global_load_lds_dwordx4 v[160:161], off
	v_lshl_add_u64 v[160:161], v[228:229], 0, s[14:15]
	s_mov_b32 m0, s80
	s_nop 0
	global_load_lds_dwordx4 v[160:161], off
	s_waitcnt vmcnt(8)
	s_waitcnt lgkmcnt(0)
	s_barrier
	s_setprio 1
	s_waitcnt lgkmcnt(0)
	v_mfma_f32_16x16x32_bf16 v[62:65], v[152:155], v[190:193], v[62:65]
	v_mfma_f32_16x16x32_bf16 v[62:65], v[156:159], v[194:197], v[62:65]
	v_mfma_f32_16x16x32_bf16 v[58:61], v[166:169], v[190:193], v[58:61]
	v_mfma_f32_16x16x32_bf16 v[58:61], v[170:173], v[194:197], v[58:61]
	v_mfma_f32_16x16x32_bf16 v[54:57], v[152:155], v[202:205], v[54:57]
	v_mfma_f32_16x16x32_bf16 v[54:57], v[156:159], v[206:209], v[54:57]
	v_mfma_f32_16x16x32_bf16 v[46:49], v[166:169], v[202:205], v[46:49]
	v_mfma_f32_16x16x32_bf16 v[46:49], v[170:173], v[206:209], v[46:49]
	v_mfma_f32_16x16x32_bf16 v[38:41], v[152:155], v[210:213], v[38:41]
	v_mfma_f32_16x16x32_bf16 v[38:41], v[156:159], v[214:217], v[38:41]
	v_mfma_f32_16x16x32_bf16 v[30:33], v[166:169], v[210:213], v[30:33]
	v_mfma_f32_16x16x32_bf16 v[30:33], v[170:173], v[214:217], v[30:33]
	v_mfma_f32_16x16x32_bf16 v[22:25], v[152:155], v[218:221], v[22:25]
	v_mfma_f32_16x16x32_bf16 v[22:25], v[156:159], v[222:225], v[22:25]
	v_mfma_f32_16x16x32_bf16 v[14:17], v[166:169], v[218:221], v[14:17]
	v_mfma_f32_16x16x32_bf16 v[14:17], v[170:173], v[222:225], v[14:17]
	s_setprio 0
	s_setprio 1
	v_mfma_f32_16x16x32_bf16 v[50:53], v[174:177], v[190:193], v[50:53]
	v_mfma_f32_16x16x32_bf16 v[50:53], v[178:181], v[194:197], v[50:53]
	v_mfma_f32_16x16x32_bf16 v[42:45], v[182:185], v[190:193], v[42:45]
	v_mfma_f32_16x16x32_bf16 v[42:45], v[186:189], v[194:197], v[42:45]
	v_mfma_f32_16x16x32_bf16 v[34:37], v[174:177], v[202:205], v[34:37]
	v_mfma_f32_16x16x32_bf16 v[34:37], v[178:181], v[206:209], v[34:37]
	v_mfma_f32_16x16x32_bf16 v[26:29], v[182:185], v[202:205], v[26:29]
	v_mfma_f32_16x16x32_bf16 v[26:29], v[186:189], v[206:209], v[26:29]
	v_mfma_f32_16x16x32_bf16 v[18:21], v[174:177], v[210:213], v[18:21]
	v_mfma_f32_16x16x32_bf16 v[18:21], v[178:181], v[214:217], v[18:21]
	v_mfma_f32_16x16x32_bf16 v[10:13], v[182:185], v[210:213], v[10:13]
	v_mfma_f32_16x16x32_bf16 v[10:13], v[186:189], v[214:217], v[10:13]
	v_mfma_f32_16x16x32_bf16 v[6:9], v[174:177], v[218:221], v[6:9]
	v_mfma_f32_16x16x32_bf16 v[6:9], v[178:181], v[222:225], v[6:9]
	v_mfma_f32_16x16x32_bf16 v[2:5], v[182:185], v[218:221], v[2:5]
	v_mfma_f32_16x16x32_bf16 v[2:5], v[186:189], v[222:225], v[2:5]
	s_setprio 0
	s_barrier
	s_movk_i32 s44, 0x100
	s_andn2_b64 vcc, exec, s[58:59]
	s_mov_b64 s[60:61], -1
	s_mov_b64 s[58:59], 0
	s_cbranch_vccz .LBB0_1701
	s_and_b64 vcc, exec, s[16:17]
	s_cbranch_vccz .LBB0_1704
	s_barrier

.LBB0_1902:
	ds_read_b128 v[148:151], v156
	ds_read_b128 v[166:169], v156 offset:1024
	ds_read_b128 v[170:173], v156 offset:2048
	ds_read_b128 v[174:177], v156 offset:3072
	ds_read_b128 v[178:181], v157
	ds_read_b128 v[182:185], v157 offset:1024
	ds_read_b128 v[186:189], v157 offset:2048
	ds_read_b128 v[190:193], v157 offset:3072
	s_add_i32 s92, s58, 2
	s_add_u32 s36, s56, 0xffd50080
	s_addc_u32 s37, s57, -1
	s_cmp_eq_u32 s89, s58
	s_cselect_b32 s58, s54, s90
	s_cselect_b32 s61, s53, s37
	s_cselect_b32 s60, s52, s36
	s_cselect_b32 s59, s55, s91
	v_lshl_add_u64 v[152:153], s[56:57], 0, v[142:143]
	s_add_i32 m0, s67, 0xc000
	ds_read_b128 v[194:197], v158
	ds_read_b128 v[202:205], v158 offset:1024
	ds_read_b128 v[206:209], v158 offset:2048
	ds_read_b128 v[210:213], v158 offset:3072
	ds_read_b128 v[214:217], v158 offset:4096
	ds_read_b128 v[218:221], v158 offset:5120
	ds_read_b128 v[222:225], v158 offset:6144
	ds_read_b128 v[226:229], v158 offset:7168
	global_load_lds_dwordx4 v[152:153], off
	v_lshl_add_u64 v[152:153], s[56:57], 0, v[144:145]
	s_add_i32 m0, s67, 0xe000
	s_nop 0
	global_load_lds_dwordx4 v[152:153], off
	s_waitcnt vmcnt(8)
	s_waitcnt lgkmcnt(0)
	s_barrier
	s_setprio 1
	s_waitcnt lgkmcnt(0)
	v_mfma_f32_16x16x32_bf16 v[126:129], v[148:151], v[194:197], v[126:129]
	v_mfma_f32_16x16x32_bf16 v[126:129], v[166:169], v[202:205], v[126:129]
	v_mfma_f32_16x16x32_bf16 v[122:125], v[170:173], v[194:197], v[122:125]
	v_mfma_f32_16x16x32_bf16 v[122:125], v[174:177], v[202:205], v[122:125]
	v_mfma_f32_16x16x32_bf16 v[110:113], v[148:151], v[206:209], v[110:113]
	v_mfma_f32_16x16x32_bf16 v[110:113], v[166:169], v[210:213], v[110:113]
	v_mfma_f32_16x16x32_bf16 v[106:109], v[170:173], v[206:209], v[106:109]
	v_mfma_f32_16x16x32_bf16 v[106:109], v[174:177], v[210:213], v[106:109]
	v_mfma_f32_16x16x32_bf16 v[94:97], v[148:151], v[214:217], v[94:97]
	v_mfma_f32_16x16x32_bf16 v[94:97], v[166:169], v[218:221], v[94:97]
	v_mfma_f32_16x16x32_bf16 v[90:93], v[170:173], v[214:217], v[90:93]
	v_mfma_f32_16x16x32_bf16 v[90:93], v[174:177], v[218:221], v[90:93]
	v_mfma_f32_16x16x32_bf16 v[78:81], v[148:151], v[222:225], v[78:81]
	v_mfma_f32_16x16x32_bf16 v[78:81], v[166:169], v[226:229], v[78:81]
	v_mfma_f32_16x16x32_bf16 v[74:77], v[170:173], v[222:225], v[74:77]
	v_mfma_f32_16x16x32_bf16 v[74:77], v[174:177], v[226:229], v[74:77]
	s_setprio 0
	s_setprio 1
	v_mfma_f32_16x16x32_bf16 v[118:121], v[178:181], v[194:197], v[118:121]
	v_mfma_f32_16x16x32_bf16 v[118:121], v[182:185], v[202:205], v[118:121]
	v_mfma_f32_16x16x32_bf16 v[114:117], v[186:189], v[194:197], v[114:117]
	v_mfma_f32_16x16x32_bf16 v[114:117], v[190:193], v[202:205], v[114:117]
	v_mfma_f32_16x16x32_bf16 v[102:105], v[178:181], v[206:209], v[102:105]
	v_mfma_f32_16x16x32_bf16 v[102:105], v[182:185], v[210:213], v[102:105]
	v_mfma_f32_16x16x32_bf16 v[98:101], v[186:189], v[206:209], v[98:101]
	v_mfma_f32_16x16x32_bf16 v[98:101], v[190:193], v[210:213], v[98:101]
	v_mfma_f32_16x16x32_bf16 v[86:89], v[178:181], v[214:217], v[86:89]
	v_mfma_f32_16x16x32_bf16 v[86:89], v[182:185], v[218:221], v[86:89]
	v_mfma_f32_16x16x32_bf16 v[82:85], v[186:189], v[214:217], v[82:85]
	v_mfma_f32_16x16x32_bf16 v[82:85], v[190:193], v[218:221], v[82:85]
	v_mfma_f32_16x16x32_bf16 v[70:73], v[178:181], v[222:225], v[70:73]
	v_mfma_f32_16x16x32_bf16 v[70:73], v[182:185], v[226:229], v[70:73]
	v_mfma_f32_16x16x32_bf16 v[66:69], v[186:189], v[222:225], v[66:69]
	v_mfma_f32_16x16x32_bf16 v[66:69], v[190:193], v[226:229], v[66:69]
	s_setprio 0
	s_barrier
	s_add_i32 s36, s77, s64
	v_lshl_add_u64 v[152:153], s[58:59], 0, v[134:135]
	s_mov_b32 m0, s36
	ds_read_b128 v[194:197], v158 offset:16384
	ds_read_b128 v[202:205], v158 offset:17408
	ds_read_b128 v[206:209], v158 offset:18432
	ds_read_b128 v[210:213], v158 offset:19456
	ds_read_b128 v[214:217], v158 offset:20480
	ds_read_b128 v[218:221], v158 offset:21504
	ds_read_b128 v[222:225], v158 offset:22528
	ds_read_b128 v[226:229], v158 offset:23552
	global_load_lds_dwordx4 v[152:153], off
	s_add_i32 m0, s36, 0x2000
	s_add_u32 s94, s58, 0x2b0000
	v_lshl_add_u64 v[160:161], s[58:59], 0, v[138:139]
	s_addc_u32 s95, s59, 0
	s_add_i32 s36, s78, s64
	global_load_lds_dwordx4 v[160:161], off
	v_lshl_add_u64 v[198:199], s[94:95], 0, v[134:135]
	s_mov_b32 m0, s36
	v_lshl_add_u64 v[230:231], s[60:61], 0, v[136:137]
	global_load_lds_dwordx4 v[198:199], off
	v_lshl_add_u64 v[198:199], s[94:95], 0, v[138:139]
	s_add_i32 m0, s36, 0x2000
	s_nop 0
	global_load_lds_dwordx4 v[198:199], off
	v_lshl_add_u64 v[198:199], s[60:61], 0, v[132:133]
	s_mov_b32 m0, s67
	s_nop 0
	global_load_lds_dwordx4 v[198:199], off
	s_mov_b32 m0, s68
	s_nop 0
	global_load_lds_dwordx4 v[230:231], off
	s_waitcnt vmcnt(8)
	s_waitcnt lgkmcnt(0)
	s_barrier
	s_setprio 1
	s_waitcnt lgkmcnt(0)
	v_mfma_f32_16x16x32_bf16 v[62:65], v[148:151], v[194:197], v[62:65]
	v_mfma_f32_16x16x32_bf16 v[62:65], v[166:169], v[202:205], v[62:65]
	v_mfma_f32_16x16x32_bf16 v[58:61], v[170:173], v[194:197], v[58:61]
	v_mfma_f32_16x16x32_bf16 v[58:61], v[174:177], v[202:205], v[58:61]
	v_mfma_f32_16x16x32_bf16 v[46:49], v[148:151], v[206:209], v[46:49]
	v_mfma_f32_16x16x32_bf16 v[46:49], v[166:169], v[210:213], v[46:49]
	v_mfma_f32_16x16x32_bf16 v[42:45], v[170:173], v[206:209], v[42:45]
	v_mfma_f32_16x16x32_bf16 v[42:45], v[174:177], v[210:213], v[42:45]
	v_mfma_f32_16x16x32_bf16 v[30:33], v[148:151], v[214:217], v[30:33]
	v_mfma_f32_16x16x32_bf16 v[30:33], v[166:169], v[218:221], v[30:33]
	v_mfma_f32_16x16x32_bf16 v[26:29], v[170:173], v[214:217], v[26:29]
	v_mfma_f32_16x16x32_bf16 v[26:29], v[174:177], v[218:221], v[26:29]
	v_mfma_f32_16x16x32_bf16 v[14:17], v[148:151], v[222:225], v[14:17]
	v_mfma_f32_16x16x32_bf16 v[14:17], v[166:169], v[226:229], v[14:17]
	v_mfma_f32_16x16x32_bf16 v[10:13], v[170:173], v[222:225], v[10:13]
	v_mfma_f32_16x16x32_bf16 v[10:13], v[174:177], v[226:229], v[10:13]
	s_setprio 0
	s_setprio 1
	v_mfma_f32_16x16x32_bf16 v[54:57], v[178:181], v[194:197], v[54:57]
	v_mfma_f32_16x16x32_bf16 v[54:57], v[182:185], v[202:205], v[54:57]
	v_mfma_f32_16x16x32_bf16 v[50:53], v[186:189], v[194:197], v[50:53]
	v_mfma_f32_16x16x32_bf16 v[50:53], v[190:193], v[202:205], v[50:53]
	v_mfma_f32_16x16x32_bf16 v[38:41], v[178:181], v[206:209], v[38:41]
	v_mfma_f32_16x16x32_bf16 v[38:41], v[182:185], v[210:213], v[38:41]
	v_mfma_f32_16x16x32_bf16 v[34:37], v[186:189], v[206:209], v[34:37]
	v_mfma_f32_16x16x32_bf16 v[34:37], v[190:193], v[210:213], v[34:37]
	v_mfma_f32_16x16x32_bf16 v[22:25], v[178:181], v[214:217], v[22:25]
	v_mfma_f32_16x16x32_bf16 v[22:25], v[182:185], v[218:221], v[22:25]
	v_mfma_f32_16x16x32_bf16 v[18:21], v[186:189], v[214:217], v[18:21]
	v_mfma_f32_16x16x32_bf16 v[18:21], v[190:193], v[218:221], v[18:21]
	v_mfma_f32_16x16x32_bf16 v[6:9], v[178:181], v[222:225], v[6:9]
	v_mfma_f32_16x16x32_bf16 v[6:9], v[182:185], v[226:229], v[6:9]
	v_mfma_f32_16x16x32_bf16 v[2:5], v[186:189], v[222:225], v[2:5]
	v_mfma_f32_16x16x32_bf16 v[2:5], v[190:193], v[226:229], v[2:5]
	s_setprio 0
	s_barrier
	s_add_i32 s36, 0, 0x18000
	v_add_u32_e32 v140, s36, v154
	s_add_i32 s37, 0, 0x1c000
	ds_read_b128 v[148:151], v140
	ds_read_b128 v[166:169], v140 offset:1024
	ds_read_b128 v[170:173], v140 offset:2048
	ds_read_b128 v[174:177], v140 offset:3072
	v_add_u32_e32 v140, s37, v154
	ds_read_b128 v[178:181], v140
	ds_read_b128 v[182:185], v140 offset:1024
	ds_read_b128 v[186:189], v140 offset:2048
	ds_read_b128 v[190:193], v140 offset:3072
	s_add_u32 s60, s60, 0x2b0000
	s_addc_u32 s61, s61, 0
	s_mov_b32 m0, s69
	v_lshl_add_u64 v[232:233], s[60:61], 0, v[132:133]
	ds_read_b128 v[194:197], v158 offset:32768
	ds_read_b128 v[202:205], v158 offset:33792
	ds_read_b128 v[206:209], v158 offset:34816
	ds_read_b128 v[210:213], v158 offset:35840
	ds_read_b128 v[214:217], v158 offset:36864
	ds_read_b128 v[218:221], v158 offset:37888
	ds_read_b128 v[222:225], v158 offset:38912
	ds_read_b128 v[226:229], v158 offset:39936
	global_load_lds_dwordx4 v[232:233], off
	v_lshl_add_u64 v[232:233], s[60:61], 0, v[136:137]
	s_mov_b32 m0, s70
	s_nop 0
	global_load_lds_dwordx4 v[232:233], off
	s_waitcnt vmcnt(8)
	s_waitcnt lgkmcnt(0)
	s_barrier
	s_setprio 1
	s_waitcnt lgkmcnt(0)
	v_mfma_f32_16x16x32_bf16 v[126:129], v[148:151], v[194:197], v[126:129]
	v_mfma_f32_16x16x32_bf16 v[126:129], v[166:169], v[202:205], v[126:129]
	v_mfma_f32_16x16x32_bf16 v[122:125], v[170:173], v[194:197], v[122:125]
	v_mfma_f32_16x16x32_bf16 v[122:125], v[174:177], v[202:205], v[122:125]
	v_mfma_f32_16x16x32_bf16 v[110:113], v[148:151], v[206:209], v[110:113]
	v_mfma_f32_16x16x32_bf16 v[110:113], v[166:169], v[210:213], v[110:113]
	v_mfma_f32_16x16x32_bf16 v[106:109], v[170:173], v[206:209], v[106:109]
	v_mfma_f32_16x16x32_bf16 v[106:109], v[174:177], v[210:213], v[106:109]
	v_mfma_f32_16x16x32_bf16 v[94:97], v[148:151], v[214:217], v[94:97]
	v_mfma_f32_16x16x32_bf16 v[94:97], v[166:169], v[218:221], v[94:97]
	v_mfma_f32_16x16x32_bf16 v[90:93], v[170:173], v[214:217], v[90:93]
	v_mfma_f32_16x16x32_bf16 v[90:93], v[174:177], v[218:221], v[90:93]
	v_mfma_f32_16x16x32_bf16 v[78:81], v[148:151], v[222:225], v[78:81]
	v_mfma_f32_16x16x32_bf16 v[78:81], v[166:169], v[226:229], v[78:81]
	v_mfma_f32_16x16x32_bf16 v[74:77], v[170:173], v[222:225], v[74:77]
	v_mfma_f32_16x16x32_bf16 v[74:77], v[174:177], v[226:229], v[74:77]
	s_setprio 0
	s_setprio 1
	v_mfma_f32_16x16x32_bf16 v[118:121], v[178:181], v[194:197], v[118:121]
	v_mfma_f32_16x16x32_bf16 v[118:121], v[182:185], v[202:205], v[118:121]
	v_mfma_f32_16x16x32_bf16 v[114:117], v[186:189], v[194:197], v[114:117]
	v_mfma_f32_16x16x32_bf16 v[114:117], v[190:193], v[202:205], v[114:117]
	v_mfma_f32_16x16x32_bf16 v[102:105], v[178:181], v[206:209], v[102:105]
	v_mfma_f32_16x16x32_bf16 v[102:105], v[182:185], v[210:213], v[102:105]
	v_mfma_f32_16x16x32_bf16 v[98:101], v[186:189], v[206:209], v[98:101]
	v_mfma_f32_16x16x32_bf16 v[98:101], v[190:193], v[210:213], v[98:101]
	v_mfma_f32_16x16x32_bf16 v[86:89], v[178:181], v[214:217], v[86:89]
	v_mfma_f32_16x16x32_bf16 v[86:89], v[182:185], v[218:221], v[86:89]
	v_mfma_f32_16x16x32_bf16 v[82:85], v[186:189], v[214:217], v[82:85]
	v_mfma_f32_16x16x32_bf16 v[82:85], v[190:193], v[218:221], v[82:85]
	v_mfma_f32_16x16x32_bf16 v[70:73], v[178:181], v[222:225], v[70:73]
	v_mfma_f32_16x16x32_bf16 v[70:73], v[182:185], v[226:229], v[70:73]
	v_mfma_f32_16x16x32_bf16 v[66:69], v[186:189], v[222:225], v[66:69]
	v_mfma_f32_16x16x32_bf16 v[66:69], v[190:193], v[226:229], v[66:69]
	s_setprio 0
	s_barrier
	s_add_i32 s36, s36, s64
	v_lshl_add_u64 v[152:153], v[152:153], 0, s[20:21]
	s_mov_b32 m0, s36
	ds_read_b128 v[194:197], v158 offset:49152
	ds_read_b128 v[202:205], v158 offset:50176
	ds_read_b128 v[206:209], v158 offset:51200
	ds_read_b128 v[210:213], v158 offset:52224
	ds_read_b128 v[214:217], v158 offset:53248
	ds_read_b128 v[218:221], v158 offset:54272
	ds_read_b128 v[222:225], v158 offset:55296
	ds_read_b128 v[226:229], v158 offset:56320
	global_load_lds_dwordx4 v[152:153], off
	s_add_i32 m0, s36, 0x2000
	s_add_u32 s58, s58, 0x2b0080
	v_lshl_add_u64 v[152:153], v[160:161], 0, s[20:21]
	s_addc_u32 s59, s59, 0
	s_add_i32 s36, s37, s64
	global_load_lds_dwordx4 v[152:153], off
	v_lshl_add_u64 v[152:153], s[58:59], 0, v[134:135]
	s_mov_b32 m0, s36
	s_nop 0
	global_load_lds_dwordx4 v[152:153], off
	v_lshl_add_u64 v[152:153], s[58:59], 0, v[138:139]
	s_add_i32 m0, s36, 0x2000
	s_nop 0
	global_load_lds_dwordx4 v[152:153], off
	v_lshl_add_u64 v[152:153], v[198:199], 0, s[20:21]
	s_mov_b32 m0, s73
	s_nop 0
	global_load_lds_dwordx4 v[152:153], off
	v_lshl_add_u64 v[152:153], v[230:231], 0, s[20:21]
	s_mov_b32 m0, s74
	s_nop 0
	global_load_lds_dwordx4 v[152:153], off
	s_waitcnt vmcnt(8)
	s_waitcnt lgkmcnt(0)
	s_barrier
	s_setprio 1
	s_waitcnt lgkmcnt(0)
	v_mfma_f32_16x16x32_bf16 v[62:65], v[148:151], v[194:197], v[62:65]
	v_mfma_f32_16x16x32_bf16 v[62:65], v[166:169], v[202:205], v[62:65]
	v_mfma_f32_16x16x32_bf16 v[58:61], v[170:173], v[194:197], v[58:61]
	v_mfma_f32_16x16x32_bf16 v[58:61], v[174:177], v[202:205], v[58:61]
	v_mfma_f32_16x16x32_bf16 v[46:49], v[148:151], v[206:209], v[46:49]
	v_mfma_f32_16x16x32_bf16 v[46:49], v[166:169], v[210:213], v[46:49]
	v_mfma_f32_16x16x32_bf16 v[42:45], v[170:173], v[206:209], v[42:45]
	v_mfma_f32_16x16x32_bf16 v[42:45], v[174:177], v[210:213], v[42:45]
	v_mfma_f32_16x16x32_bf16 v[30:33], v[148:151], v[214:217], v[30:33]
	v_mfma_f32_16x16x32_bf16 v[30:33], v[166:169], v[218:221], v[30:33]
	v_mfma_f32_16x16x32_bf16 v[26:29], v[170:173], v[214:217], v[26:29]
	v_mfma_f32_16x16x32_bf16 v[26:29], v[174:177], v[218:221], v[26:29]
	v_mfma_f32_16x16x32_bf16 v[14:17], v[148:151], v[222:225], v[14:17]
	v_mfma_f32_16x16x32_bf16 v[14:17], v[166:169], v[226:229], v[14:17]
	v_mfma_f32_16x16x32_bf16 v[10:13], v[170:173], v[222:225], v[10:13]
	v_mfma_f32_16x16x32_bf16 v[10:13], v[174:177], v[226:229], v[10:13]
	s_setprio 0
	s_setprio 1
	v_mfma_f32_16x16x32_bf16 v[54:57], v[178:181], v[194:197], v[54:57]
	v_mfma_f32_16x16x32_bf16 v[54:57], v[182:185], v[202:205], v[54:57]
	v_mfma_f32_16x16x32_bf16 v[50:53], v[186:189], v[194:197], v[50:53]
	v_mfma_f32_16x16x32_bf16 v[50:53], v[190:193], v[202:205], v[50:53]
	v_mfma_f32_16x16x32_bf16 v[38:41], v[178:181], v[206:209], v[38:41]
	v_mfma_f32_16x16x32_bf16 v[38:41], v[182:185], v[210:213], v[38:41]
	v_mfma_f32_16x16x32_bf16 v[34:37], v[186:189], v[206:209], v[34:37]
	v_mfma_f32_16x16x32_bf16 v[34:37], v[190:193], v[210:213], v[34:37]
	v_mfma_f32_16x16x32_bf16 v[22:25], v[178:181], v[214:217], v[22:25]
	v_mfma_f32_16x16x32_bf16 v[22:25], v[182:185], v[218:221], v[22:25]
	v_mfma_f32_16x16x32_bf16 v[18:21], v[186:189], v[214:217], v[18:21]
	v_mfma_f32_16x16x32_bf16 v[18:21], v[190:193], v[218:221], v[18:21]
	v_mfma_f32_16x16x32_bf16 v[6:9], v[178:181], v[222:225], v[6:9]
	v_mfma_f32_16x16x32_bf16 v[6:9], v[182:185], v[226:229], v[6:9]
	v_mfma_f32_16x16x32_bf16 v[2:5], v[186:189], v[222:225], v[2:5]
	v_mfma_f32_16x16x32_bf16 v[2:5], v[190:193], v[226:229], v[2:5]
	s_setprio 0
	s_barrier
	s_add_u32 s56, s56, 0x100
	s_addc_u32 s57, s57, 0
	s_add_u32 s90, s90, 0x100
	s_addc_u32 s91, s91, 0
	s_cmp_ge_i32 s92, s39
	s_mov_b32 s58, s92
	s_cbranch_scc0 .LBB0_1902
	s_and_b64 vcc, exec, s[24:25]
	s_cbranch_vccz .LBB0_1905

.LBB0_2138:
	ds_read_b128 v[146:149], v157
	ds_read_b128 v[164:167], v157 offset:1024
	ds_read_b128 v[168:171], v157 offset:2048
	ds_read_b128 v[172:175], v157 offset:3072
	ds_read_b128 v[176:179], v158
	ds_read_b128 v[180:183], v158 offset:1024
	ds_read_b128 v[184:187], v158 offset:2048
	ds_read_b128 v[188:191], v158 offset:3072
	s_add_u32 s24, s22, 0xfff00080
	s_addc_u32 s25, s23, -1
	s_cmp_eq_u32 s54, 60
	s_cselect_b32 s35, s15, s25
	s_cselect_b32 s34, s50, s24
	s_cselect_b32 s25, s13, s53
	s_cselect_b32 s24, s51, s52
	v_lshl_add_u64 v[150:151], s[22:23], 0, v[138:139]
	s_add_i32 m0, s21, 0xc000
	ds_read_b128 v[192:195], v159
	ds_read_b128 v[196:199], v159 offset:1024
	ds_read_b128 v[200:203], v159 offset:2048
	ds_read_b128 v[204:207], v159 offset:3072
	ds_read_b128 v[208:211], v159 offset:4096
	ds_read_b128 v[212:215], v159 offset:5120
	ds_read_b128 v[216:219], v159 offset:6144
	ds_read_b128 v[220:223], v159 offset:7168
	global_load_lds_dwordx4 v[150:151], off
	v_lshl_add_u64 v[150:151], s[22:23], 0, v[140:141]
	s_add_i32 m0, s21, 0xe000
	s_nop 0
	global_load_lds_dwordx4 v[150:151], off
	s_waitcnt vmcnt(8)
	s_waitcnt lgkmcnt(0)
	s_barrier
	s_setprio 1
	s_waitcnt lgkmcnt(0)
	v_mfma_f32_16x16x32_bf16 v[126:129], v[146:149], v[192:195], v[126:129]
	v_mfma_f32_16x16x32_bf16 v[126:129], v[164:167], v[196:199], v[126:129]
	v_mfma_f32_16x16x32_bf16 v[122:125], v[168:171], v[192:195], v[122:125]
	v_mfma_f32_16x16x32_bf16 v[122:125], v[172:175], v[196:199], v[122:125]
	v_mfma_f32_16x16x32_bf16 v[110:113], v[146:149], v[200:203], v[110:113]
	v_mfma_f32_16x16x32_bf16 v[110:113], v[164:167], v[204:207], v[110:113]
	v_mfma_f32_16x16x32_bf16 v[106:109], v[168:171], v[200:203], v[106:109]
	v_mfma_f32_16x16x32_bf16 v[106:109], v[172:175], v[204:207], v[106:109]
	v_mfma_f32_16x16x32_bf16 v[94:97], v[146:149], v[208:211], v[94:97]
	v_mfma_f32_16x16x32_bf16 v[94:97], v[164:167], v[212:215], v[94:97]
	v_mfma_f32_16x16x32_bf16 v[90:93], v[168:171], v[208:211], v[90:93]
	v_mfma_f32_16x16x32_bf16 v[90:93], v[172:175], v[212:215], v[90:93]
	v_mfma_f32_16x16x32_bf16 v[78:81], v[146:149], v[216:219], v[78:81]
	v_mfma_f32_16x16x32_bf16 v[78:81], v[164:167], v[220:223], v[78:81]
	v_mfma_f32_16x16x32_bf16 v[74:77], v[168:171], v[216:219], v[74:77]
	v_mfma_f32_16x16x32_bf16 v[74:77], v[172:175], v[220:223], v[74:77]
	s_setprio 0
	s_setprio 1
	v_mfma_f32_16x16x32_bf16 v[118:121], v[176:179], v[192:195], v[118:121]
	v_mfma_f32_16x16x32_bf16 v[118:121], v[180:183], v[196:199], v[118:121]
	v_mfma_f32_16x16x32_bf16 v[114:117], v[184:187], v[192:195], v[114:117]
	v_mfma_f32_16x16x32_bf16 v[114:117], v[188:191], v[196:199], v[114:117]
	v_mfma_f32_16x16x32_bf16 v[102:105], v[176:179], v[200:203], v[102:105]
	v_mfma_f32_16x16x32_bf16 v[102:105], v[180:183], v[204:207], v[102:105]
	v_mfma_f32_16x16x32_bf16 v[98:101], v[184:187], v[200:203], v[98:101]
	v_mfma_f32_16x16x32_bf16 v[98:101], v[188:191], v[204:207], v[98:101]
	v_mfma_f32_16x16x32_bf16 v[86:89], v[176:179], v[208:211], v[86:89]
	v_mfma_f32_16x16x32_bf16 v[86:89], v[180:183], v[212:215], v[86:89]
	v_mfma_f32_16x16x32_bf16 v[82:85], v[184:187], v[208:211], v[82:85]
	v_mfma_f32_16x16x32_bf16 v[82:85], v[188:191], v[212:215], v[82:85]
	v_mfma_f32_16x16x32_bf16 v[70:73], v[176:179], v[216:219], v[70:73]
	v_mfma_f32_16x16x32_bf16 v[70:73], v[180:183], v[220:223], v[70:73]
	v_mfma_f32_16x16x32_bf16 v[66:69], v[184:187], v[216:219], v[66:69]
	v_mfma_f32_16x16x32_bf16 v[66:69], v[188:191], v[220:223], v[66:69]
	s_setprio 0
	s_barrier
	s_add_i32 s55, s47, s27
	v_lshl_add_u64 v[150:151], s[24:25], 0, v[134:135]
	s_mov_b32 m0, s55
	ds_read_b128 v[192:195], v159 offset:16384
	ds_read_b128 v[196:199], v159 offset:17408
	ds_read_b128 v[200:203], v159 offset:18432
	ds_read_b128 v[204:207], v159 offset:19456
	ds_read_b128 v[208:211], v159 offset:20480
	ds_read_b128 v[212:215], v159 offset:21504
	ds_read_b128 v[216:219], v159 offset:22528
	ds_read_b128 v[220:223], v159 offset:23552
	global_load_lds_dwordx4 v[150:151], off
	s_add_i32 m0, s55, 0x2000
	s_add_u32 s56, s24, 0x100000
	v_lshl_add_u64 v[160:161], s[24:25], 0, v[130:131]
	s_addc_u32 s57, s25, 0
	s_add_i32 s55, s48, s27
	global_load_lds_dwordx4 v[160:161], off
	v_lshl_add_u64 v[224:225], s[56:57], 0, v[134:135]
	s_mov_b32 m0, s55
	v_lshl_add_u64 v[226:227], s[34:35], 0, v[132:133]
	global_load_lds_dwordx4 v[224:225], off
	v_lshl_add_u64 v[224:225], s[56:57], 0, v[130:131]
	s_add_i32 m0, s55, 0x2000
	s_nop 0
	global_load_lds_dwordx4 v[224:225], off
	v_lshl_add_u64 v[224:225], s[34:35], 0, v[136:137]
	s_mov_b32 m0, s21
	s_nop 0
	global_load_lds_dwordx4 v[224:225], off
	s_mov_b32 m0, s40
	s_nop 0
	global_load_lds_dwordx4 v[226:227], off
	s_waitcnt vmcnt(8)
	s_waitcnt lgkmcnt(0)
	s_barrier
	s_setprio 1
	s_waitcnt lgkmcnt(0)
	v_mfma_f32_16x16x32_bf16 v[62:65], v[146:149], v[192:195], v[62:65]
	v_mfma_f32_16x16x32_bf16 v[62:65], v[164:167], v[196:199], v[62:65]
	v_mfma_f32_16x16x32_bf16 v[58:61], v[168:171], v[192:195], v[58:61]
	v_mfma_f32_16x16x32_bf16 v[58:61], v[172:175], v[196:199], v[58:61]
	v_mfma_f32_16x16x32_bf16 v[46:49], v[146:149], v[200:203], v[46:49]
	v_mfma_f32_16x16x32_bf16 v[46:49], v[164:167], v[204:207], v[46:49]
	v_mfma_f32_16x16x32_bf16 v[42:45], v[168:171], v[200:203], v[42:45]
	v_mfma_f32_16x16x32_bf16 v[42:45], v[172:175], v[204:207], v[42:45]
	v_mfma_f32_16x16x32_bf16 v[30:33], v[146:149], v[208:211], v[30:33]
	v_mfma_f32_16x16x32_bf16 v[30:33], v[164:167], v[212:215], v[30:33]
	v_mfma_f32_16x16x32_bf16 v[26:29], v[168:171], v[208:211], v[26:29]
	v_mfma_f32_16x16x32_bf16 v[26:29], v[172:175], v[212:215], v[26:29]
	v_mfma_f32_16x16x32_bf16 v[14:17], v[146:149], v[216:219], v[14:17]
	v_mfma_f32_16x16x32_bf16 v[14:17], v[164:167], v[220:223], v[14:17]
	v_mfma_f32_16x16x32_bf16 v[10:13], v[168:171], v[216:219], v[10:13]
	v_mfma_f32_16x16x32_bf16 v[10:13], v[172:175], v[220:223], v[10:13]
	s_setprio 0
	s_setprio 1
	v_mfma_f32_16x16x32_bf16 v[54:57], v[176:179], v[192:195], v[54:57]
	v_mfma_f32_16x16x32_bf16 v[54:57], v[180:183], v[196:199], v[54:57]
	v_mfma_f32_16x16x32_bf16 v[50:53], v[184:187], v[192:195], v[50:53]
	v_mfma_f32_16x16x32_bf16 v[50:53], v[188:191], v[196:199], v[50:53]
	v_mfma_f32_16x16x32_bf16 v[38:41], v[176:179], v[200:203], v[38:41]
	v_mfma_f32_16x16x32_bf16 v[38:41], v[180:183], v[204:207], v[38:41]
	v_mfma_f32_16x16x32_bf16 v[34:37], v[184:187], v[200:203], v[34:37]
	v_mfma_f32_16x16x32_bf16 v[34:37], v[188:191], v[204:207], v[34:37]
	v_mfma_f32_16x16x32_bf16 v[22:25], v[176:179], v[208:211], v[22:25]
	v_mfma_f32_16x16x32_bf16 v[22:25], v[180:183], v[212:215], v[22:25]
	v_mfma_f32_16x16x32_bf16 v[18:21], v[184:187], v[208:211], v[18:21]
	v_mfma_f32_16x16x32_bf16 v[18:21], v[188:191], v[212:215], v[18:21]
	v_mfma_f32_16x16x32_bf16 v[6:9], v[176:179], v[216:219], v[6:9]
	v_mfma_f32_16x16x32_bf16 v[6:9], v[180:183], v[220:223], v[6:9]
	v_mfma_f32_16x16x32_bf16 v[2:5], v[184:187], v[216:219], v[2:5]
	v_mfma_f32_16x16x32_bf16 v[2:5], v[188:191], v[220:223], v[2:5]
	s_setprio 0
	s_barrier
	s_add_i32 s55, 0, 0x18000
	v_add_u32_e32 v162, s55, v155
	s_add_i32 s56, 0, 0x1c000
	ds_read_b128 v[146:149], v162
	ds_read_b128 v[164:167], v162 offset:1024
	ds_read_b128 v[168:171], v162 offset:2048
	ds_read_b128 v[172:175], v162 offset:3072
	v_add_u32_e32 v162, s56, v155
	ds_read_b128 v[176:179], v162
	ds_read_b128 v[180:183], v162 offset:1024
	ds_read_b128 v[184:187], v162 offset:2048
	ds_read_b128 v[188:191], v162 offset:3072
	s_add_u32 s34, s34, 0x100000
	s_addc_u32 s35, s35, 0
	s_mov_b32 m0, s41
	v_lshl_add_u64 v[228:229], s[34:35], 0, v[136:137]
	ds_read_b128 v[192:195], v159 offset:32768
	ds_read_b128 v[196:199], v159 offset:33792
	ds_read_b128 v[200:203], v159 offset:34816
	ds_read_b128 v[204:207], v159 offset:35840
	ds_read_b128 v[208:211], v159 offset:36864
	ds_read_b128 v[212:215], v159 offset:37888
	ds_read_b128 v[216:219], v159 offset:38912
	ds_read_b128 v[220:223], v159 offset:39936
	global_load_lds_dwordx4 v[228:229], off
	v_lshl_add_u64 v[228:229], s[34:35], 0, v[132:133]
	s_mov_b32 m0, s42
	s_nop 0
	global_load_lds_dwordx4 v[228:229], off
	s_waitcnt vmcnt(8)
	s_waitcnt lgkmcnt(0)
	s_barrier
	s_setprio 1
	s_waitcnt lgkmcnt(0)
	v_mfma_f32_16x16x32_bf16 v[126:129], v[146:149], v[192:195], v[126:129]
	v_mfma_f32_16x16x32_bf16 v[126:129], v[164:167], v[196:199], v[126:129]
	v_mfma_f32_16x16x32_bf16 v[122:125], v[168:171], v[192:195], v[122:125]
	v_mfma_f32_16x16x32_bf16 v[122:125], v[172:175], v[196:199], v[122:125]
	v_mfma_f32_16x16x32_bf16 v[110:113], v[146:149], v[200:203], v[110:113]
	v_mfma_f32_16x16x32_bf16 v[110:113], v[164:167], v[204:207], v[110:113]
	v_mfma_f32_16x16x32_bf16 v[106:109], v[168:171], v[200:203], v[106:109]
	v_mfma_f32_16x16x32_bf16 v[106:109], v[172:175], v[204:207], v[106:109]
	v_mfma_f32_16x16x32_bf16 v[94:97], v[146:149], v[208:211], v[94:97]
	v_mfma_f32_16x16x32_bf16 v[94:97], v[164:167], v[212:215], v[94:97]
	v_mfma_f32_16x16x32_bf16 v[90:93], v[168:171], v[208:211], v[90:93]
	v_mfma_f32_16x16x32_bf16 v[90:93], v[172:175], v[212:215], v[90:93]
	v_mfma_f32_16x16x32_bf16 v[78:81], v[146:149], v[216:219], v[78:81]
	v_mfma_f32_16x16x32_bf16 v[78:81], v[164:167], v[220:223], v[78:81]
	v_mfma_f32_16x16x32_bf16 v[74:77], v[168:171], v[216:219], v[74:77]
	v_mfma_f32_16x16x32_bf16 v[74:77], v[172:175], v[220:223], v[74:77]
	s_setprio 0
	s_setprio 1
	v_mfma_f32_16x16x32_bf16 v[118:121], v[176:179], v[192:195], v[118:121]
	v_mfma_f32_16x16x32_bf16 v[118:121], v[180:183], v[196:199], v[118:121]
	v_mfma_f32_16x16x32_bf16 v[114:117], v[184:187], v[192:195], v[114:117]
	v_mfma_f32_16x16x32_bf16 v[114:117], v[188:191], v[196:199], v[114:117]
	v_mfma_f32_16x16x32_bf16 v[102:105], v[176:179], v[200:203], v[102:105]
	v_mfma_f32_16x16x32_bf16 v[102:105], v[180:183], v[204:207], v[102:105]
	v_mfma_f32_16x16x32_bf16 v[98:101], v[184:187], v[200:203], v[98:101]
	v_mfma_f32_16x16x32_bf16 v[98:101], v[188:191], v[204:207], v[98:101]
	v_mfma_f32_16x16x32_bf16 v[86:89], v[176:179], v[208:211], v[86:89]
	v_mfma_f32_16x16x32_bf16 v[86:89], v[180:183], v[212:215], v[86:89]
	v_mfma_f32_16x16x32_bf16 v[82:85], v[184:187], v[208:211], v[82:85]
	v_mfma_f32_16x16x32_bf16 v[82:85], v[188:191], v[212:215], v[82:85]
	v_mfma_f32_16x16x32_bf16 v[70:73], v[176:179], v[216:219], v[70:73]
	v_mfma_f32_16x16x32_bf16 v[70:73], v[180:183], v[220:223], v[70:73]
	v_mfma_f32_16x16x32_bf16 v[66:69], v[184:187], v[216:219], v[66:69]
	v_mfma_f32_16x16x32_bf16 v[66:69], v[188:191], v[220:223], v[66:69]
	s_setprio 0
	s_barrier
	s_add_i32 s34, s55, s27
	v_lshl_add_u64 v[150:151], v[150:151], 0, s[8:9]
	s_mov_b32 m0, s34
	ds_read_b128 v[192:195], v159 offset:49152
	ds_read_b128 v[196:199], v159 offset:50176
	ds_read_b128 v[200:203], v159 offset:51200
	ds_read_b128 v[204:207], v159 offset:52224
	ds_read_b128 v[208:211], v159 offset:53248
	ds_read_b128 v[212:215], v159 offset:54272
	ds_read_b128 v[216:219], v159 offset:55296
	ds_read_b128 v[220:223], v159 offset:56320
	global_load_lds_dwordx4 v[150:151], off
	s_add_i32 m0, s34, 0x2000
	s_add_u32 s24, s24, 0x100080
	v_lshl_add_u64 v[150:151], v[160:161], 0, s[8:9]
	s_addc_u32 s25, s25, 0
	s_add_i32 s34, s56, s27
	global_load_lds_dwordx4 v[150:151], off
	v_lshl_add_u64 v[150:151], s[24:25], 0, v[134:135]
	s_mov_b32 m0, s34
	s_nop 0
	global_load_lds_dwordx4 v[150:151], off
	v_lshl_add_u64 v[150:151], s[24:25], 0, v[130:131]
	s_add_i32 m0, s34, 0x2000
	s_nop 0
	global_load_lds_dwordx4 v[150:151], off
	v_lshl_add_u64 v[150:151], v[224:225], 0, s[8:9]
	s_mov_b32 m0, s44
	s_nop 0
	global_load_lds_dwordx4 v[150:151], off
	v_lshl_add_u64 v[150:151], v[226:227], 0, s[8:9]
	s_mov_b32 m0, s45
	s_nop 0
	global_load_lds_dwordx4 v[150:151], off
	s_waitcnt vmcnt(8)
	s_waitcnt lgkmcnt(0)
	s_barrier
	s_setprio 1
	s_waitcnt lgkmcnt(0)
	v_mfma_f32_16x16x32_bf16 v[62:65], v[146:149], v[192:195], v[62:65]
	v_mfma_f32_16x16x32_bf16 v[62:65], v[164:167], v[196:199], v[62:65]
	v_mfma_f32_16x16x32_bf16 v[58:61], v[168:171], v[192:195], v[58:61]
	v_mfma_f32_16x16x32_bf16 v[58:61], v[172:175], v[196:199], v[58:61]
	v_mfma_f32_16x16x32_bf16 v[46:49], v[146:149], v[200:203], v[46:49]
	v_mfma_f32_16x16x32_bf16 v[46:49], v[164:167], v[204:207], v[46:49]
	v_mfma_f32_16x16x32_bf16 v[42:45], v[168:171], v[200:203], v[42:45]
	v_mfma_f32_16x16x32_bf16 v[42:45], v[172:175], v[204:207], v[42:45]
	v_mfma_f32_16x16x32_bf16 v[30:33], v[146:149], v[208:211], v[30:33]
	v_mfma_f32_16x16x32_bf16 v[30:33], v[164:167], v[212:215], v[30:33]
	v_mfma_f32_16x16x32_bf16 v[26:29], v[168:171], v[208:211], v[26:29]
	v_mfma_f32_16x16x32_bf16 v[26:29], v[172:175], v[212:215], v[26:29]
	v_mfma_f32_16x16x32_bf16 v[14:17], v[146:149], v[216:219], v[14:17]
	v_mfma_f32_16x16x32_bf16 v[14:17], v[164:167], v[220:223], v[14:17]
	v_mfma_f32_16x16x32_bf16 v[10:13], v[168:171], v[216:219], v[10:13]
	v_mfma_f32_16x16x32_bf16 v[10:13], v[172:175], v[220:223], v[10:13]
	s_setprio 0
	s_setprio 1
	v_mfma_f32_16x16x32_bf16 v[54:57], v[176:179], v[192:195], v[54:57]
	v_mfma_f32_16x16x32_bf16 v[54:57], v[180:183], v[196:199], v[54:57]
	v_mfma_f32_16x16x32_bf16 v[50:53], v[184:187], v[192:195], v[50:53]
	v_mfma_f32_16x16x32_bf16 v[50:53], v[188:191], v[196:199], v[50:53]
	v_mfma_f32_16x16x32_bf16 v[38:41], v[176:179], v[200:203], v[38:41]
	v_mfma_f32_16x16x32_bf16 v[38:41], v[180:183], v[204:207], v[38:41]
	v_mfma_f32_16x16x32_bf16 v[34:37], v[184:187], v[200:203], v[34:37]
	v_mfma_f32_16x16x32_bf16 v[34:37], v[188:191], v[204:207], v[34:37]
	v_mfma_f32_16x16x32_bf16 v[22:25], v[176:179], v[208:211], v[22:25]
	v_mfma_f32_16x16x32_bf16 v[22:25], v[180:183], v[212:215], v[22:25]
	v_mfma_f32_16x16x32_bf16 v[18:21], v[184:187], v[208:211], v[18:21]
	v_mfma_f32_16x16x32_bf16 v[18:21], v[188:191], v[212:215], v[18:21]
	v_mfma_f32_16x16x32_bf16 v[6:9], v[176:179], v[216:219], v[6:9]
	v_mfma_f32_16x16x32_bf16 v[6:9], v[180:183], v[220:223], v[6:9]
	v_mfma_f32_16x16x32_bf16 v[2:5], v[184:187], v[216:219], v[2:5]
	v_mfma_f32_16x16x32_bf16 v[2:5], v[188:191], v[220:223], v[2:5]
	s_setprio 0
	s_barrier
	s_add_i32 s54, s54, 2
	s_add_u32 s22, s22, 0x100
	s_addc_u32 s23, s23, 0
	s_add_u32 s52, s52, 0x100
	s_addc_u32 s53, s53, 0
	s_cmp_gt_u32 s54, 61
	s_cbranch_scc0 .LBB0_2138
	s_and_b64 vcc, exec, s[10:11]
	s_cbranch_vccz .LBB0_2141
	s_barrier

.LBB0_2158:
	ds_read_b128 v[146:149], v157
	ds_read_b128 v[164:167], v157 offset:1024
	ds_read_b128 v[168:171], v157 offset:2048
	ds_read_b128 v[172:175], v157 offset:3072
	ds_read_b128 v[176:179], v158
	ds_read_b128 v[180:183], v158 offset:1024
	ds_read_b128 v[184:187], v158 offset:2048
	ds_read_b128 v[188:191], v158 offset:3072
	s_add_u32 s26, s24, 0xfff00080
	s_addc_u32 s27, s25, -1
	s_cmp_eq_u32 s52, 60
	s_cselect_b32 s35, s17, s27
	s_cselect_b32 s34, s48, s26
	s_cselect_b32 s27, s15, s51
	s_cselect_b32 s26, s49, s50
	v_lshl_add_u64 v[150:151], s[24:25], 0, v[138:139]
	s_add_i32 m0, s23, 0xc000
	ds_read_b128 v[192:195], v159
	ds_read_b128 v[196:199], v159 offset:1024
	ds_read_b128 v[200:203], v159 offset:2048
	ds_read_b128 v[204:207], v159 offset:3072
	ds_read_b128 v[208:211], v159 offset:4096
	ds_read_b128 v[212:215], v159 offset:5120
	ds_read_b128 v[216:219], v159 offset:6144
	ds_read_b128 v[220:223], v159 offset:7168
	global_load_lds_dwordx4 v[150:151], off
	v_lshl_add_u64 v[150:151], s[24:25], 0, v[140:141]
	s_add_i32 m0, s23, 0xe000
	s_nop 0
	global_load_lds_dwordx4 v[150:151], off
	s_waitcnt vmcnt(8)
	s_waitcnt lgkmcnt(0)
	s_barrier
	s_setprio 1
	s_waitcnt lgkmcnt(0)
	v_mfma_f32_16x16x32_bf16 v[126:129], v[146:149], v[192:195], v[126:129]
	v_mfma_f32_16x16x32_bf16 v[126:129], v[164:167], v[196:199], v[126:129]
	v_mfma_f32_16x16x32_bf16 v[122:125], v[168:171], v[192:195], v[122:125]
	v_mfma_f32_16x16x32_bf16 v[122:125], v[172:175], v[196:199], v[122:125]
	v_mfma_f32_16x16x32_bf16 v[110:113], v[146:149], v[200:203], v[110:113]
	v_mfma_f32_16x16x32_bf16 v[110:113], v[164:167], v[204:207], v[110:113]
	v_mfma_f32_16x16x32_bf16 v[106:109], v[168:171], v[200:203], v[106:109]
	v_mfma_f32_16x16x32_bf16 v[106:109], v[172:175], v[204:207], v[106:109]
	v_mfma_f32_16x16x32_bf16 v[94:97], v[146:149], v[208:211], v[94:97]
	v_mfma_f32_16x16x32_bf16 v[94:97], v[164:167], v[212:215], v[94:97]
	v_mfma_f32_16x16x32_bf16 v[90:93], v[168:171], v[208:211], v[90:93]
	v_mfma_f32_16x16x32_bf16 v[90:93], v[172:175], v[212:215], v[90:93]
	v_mfma_f32_16x16x32_bf16 v[78:81], v[146:149], v[216:219], v[78:81]
	v_mfma_f32_16x16x32_bf16 v[78:81], v[164:167], v[220:223], v[78:81]
	v_mfma_f32_16x16x32_bf16 v[74:77], v[168:171], v[216:219], v[74:77]
	v_mfma_f32_16x16x32_bf16 v[74:77], v[172:175], v[220:223], v[74:77]
	s_setprio 0
	s_setprio 1
	v_mfma_f32_16x16x32_bf16 v[118:121], v[176:179], v[192:195], v[118:121]
	v_mfma_f32_16x16x32_bf16 v[118:121], v[180:183], v[196:199], v[118:121]
	v_mfma_f32_16x16x32_bf16 v[114:117], v[184:187], v[192:195], v[114:117]
	v_mfma_f32_16x16x32_bf16 v[114:117], v[188:191], v[196:199], v[114:117]
	v_mfma_f32_16x16x32_bf16 v[102:105], v[176:179], v[200:203], v[102:105]
	v_mfma_f32_16x16x32_bf16 v[102:105], v[180:183], v[204:207], v[102:105]
	v_mfma_f32_16x16x32_bf16 v[98:101], v[184:187], v[200:203], v[98:101]
	v_mfma_f32_16x16x32_bf16 v[98:101], v[188:191], v[204:207], v[98:101]
	v_mfma_f32_16x16x32_bf16 v[86:89], v[176:179], v[208:211], v[86:89]
	v_mfma_f32_16x16x32_bf16 v[86:89], v[180:183], v[212:215], v[86:89]
	v_mfma_f32_16x16x32_bf16 v[82:85], v[184:187], v[208:211], v[82:85]
	v_mfma_f32_16x16x32_bf16 v[82:85], v[188:191], v[212:215], v[82:85]
	v_mfma_f32_16x16x32_bf16 v[70:73], v[176:179], v[216:219], v[70:73]
	v_mfma_f32_16x16x32_bf16 v[70:73], v[180:183], v[220:223], v[70:73]
	v_mfma_f32_16x16x32_bf16 v[66:69], v[184:187], v[216:219], v[66:69]
	v_mfma_f32_16x16x32_bf16 v[66:69], v[188:191], v[220:223], v[66:69]
	s_setprio 0
	s_barrier
	s_add_i32 s53, s45, s38
	v_lshl_add_u64 v[150:151], s[26:27], 0, v[132:133]
	s_mov_b32 m0, s53
	ds_read_b128 v[192:195], v159 offset:16384
	ds_read_b128 v[196:199], v159 offset:17408
	ds_read_b128 v[200:203], v159 offset:18432
	ds_read_b128 v[204:207], v159 offset:19456
	ds_read_b128 v[208:211], v159 offset:20480
	ds_read_b128 v[212:215], v159 offset:21504
	ds_read_b128 v[216:219], v159 offset:22528
	ds_read_b128 v[220:223], v159 offset:23552
	global_load_lds_dwordx4 v[150:151], off
	s_add_i32 m0, s53, 0x2000
	s_add_u32 s54, s26, 0x100000
	v_lshl_add_u64 v[160:161], s[26:27], 0, v[134:135]
	s_addc_u32 s55, s27, 0
	s_add_i32 s53, s46, s38
	global_load_lds_dwordx4 v[160:161], off
	v_lshl_add_u64 v[224:225], s[54:55], 0, v[132:133]
	s_mov_b32 m0, s53
	v_lshl_add_u64 v[226:227], s[34:35], 0, v[136:137]
	global_load_lds_dwordx4 v[224:225], off
	v_lshl_add_u64 v[224:225], s[54:55], 0, v[134:135]
	s_add_i32 m0, s53, 0x2000
	s_nop 0
	global_load_lds_dwordx4 v[224:225], off
	v_lshl_add_u64 v[224:225], s[34:35], 0, v[130:131]
	s_mov_b32 m0, s23
	s_nop 0
	global_load_lds_dwordx4 v[224:225], off
	s_mov_b32 m0, s40
	s_nop 0
	global_load_lds_dwordx4 v[226:227], off
	s_waitcnt vmcnt(8)
	s_waitcnt lgkmcnt(0)
	s_barrier
	s_setprio 1
	s_waitcnt lgkmcnt(0)
	v_mfma_f32_16x16x32_bf16 v[62:65], v[146:149], v[192:195], v[62:65]
	v_mfma_f32_16x16x32_bf16 v[62:65], v[164:167], v[196:199], v[62:65]
	v_mfma_f32_16x16x32_bf16 v[58:61], v[168:171], v[192:195], v[58:61]
	v_mfma_f32_16x16x32_bf16 v[58:61], v[172:175], v[196:199], v[58:61]
	v_mfma_f32_16x16x32_bf16 v[46:49], v[146:149], v[200:203], v[46:49]
	v_mfma_f32_16x16x32_bf16 v[46:49], v[164:167], v[204:207], v[46:49]
	v_mfma_f32_16x16x32_bf16 v[42:45], v[168:171], v[200:203], v[42:45]
	v_mfma_f32_16x16x32_bf16 v[42:45], v[172:175], v[204:207], v[42:45]
	v_mfma_f32_16x16x32_bf16 v[30:33], v[146:149], v[208:211], v[30:33]
	v_mfma_f32_16x16x32_bf16 v[30:33], v[164:167], v[212:215], v[30:33]
	v_mfma_f32_16x16x32_bf16 v[26:29], v[168:171], v[208:211], v[26:29]
	v_mfma_f32_16x16x32_bf16 v[26:29], v[172:175], v[212:215], v[26:29]
	v_mfma_f32_16x16x32_bf16 v[14:17], v[146:149], v[216:219], v[14:17]
	v_mfma_f32_16x16x32_bf16 v[14:17], v[164:167], v[220:223], v[14:17]
	v_mfma_f32_16x16x32_bf16 v[10:13], v[168:171], v[216:219], v[10:13]
	v_mfma_f32_16x16x32_bf16 v[10:13], v[172:175], v[220:223], v[10:13]
	s_setprio 0
	s_setprio 1
	v_mfma_f32_16x16x32_bf16 v[54:57], v[176:179], v[192:195], v[54:57]
	v_mfma_f32_16x16x32_bf16 v[54:57], v[180:183], v[196:199], v[54:57]
	v_mfma_f32_16x16x32_bf16 v[50:53], v[184:187], v[192:195], v[50:53]
	v_mfma_f32_16x16x32_bf16 v[50:53], v[188:191], v[196:199], v[50:53]
	v_mfma_f32_16x16x32_bf16 v[38:41], v[176:179], v[200:203], v[38:41]
	v_mfma_f32_16x16x32_bf16 v[38:41], v[180:183], v[204:207], v[38:41]
	v_mfma_f32_16x16x32_bf16 v[34:37], v[184:187], v[200:203], v[34:37]
	v_mfma_f32_16x16x32_bf16 v[34:37], v[188:191], v[204:207], v[34:37]
	v_mfma_f32_16x16x32_bf16 v[22:25], v[176:179], v[208:211], v[22:25]
	v_mfma_f32_16x16x32_bf16 v[22:25], v[180:183], v[212:215], v[22:25]
	v_mfma_f32_16x16x32_bf16 v[18:21], v[184:187], v[208:211], v[18:21]
	v_mfma_f32_16x16x32_bf16 v[18:21], v[188:191], v[212:215], v[18:21]
	v_mfma_f32_16x16x32_bf16 v[6:9], v[176:179], v[216:219], v[6:9]
	v_mfma_f32_16x16x32_bf16 v[6:9], v[180:183], v[220:223], v[6:9]
	v_mfma_f32_16x16x32_bf16 v[2:5], v[184:187], v[216:219], v[2:5]
	v_mfma_f32_16x16x32_bf16 v[2:5], v[188:191], v[220:223], v[2:5]
	s_setprio 0
	s_barrier
	s_add_i32 s53, 0, 0x18000
	v_add_u32_e32 v162, s53, v155
	s_add_i32 s54, 0, 0x1c000
	ds_read_b128 v[146:149], v162
	ds_read_b128 v[164:167], v162 offset:1024
	ds_read_b128 v[168:171], v162 offset:2048
	ds_read_b128 v[172:175], v162 offset:3072
	v_add_u32_e32 v162, s54, v155
	ds_read_b128 v[176:179], v162
	ds_read_b128 v[180:183], v162 offset:1024
	ds_read_b128 v[184:187], v162 offset:2048
	ds_read_b128 v[188:191], v162 offset:3072
	s_add_u32 s34, s34, 0x100000
	s_addc_u32 s35, s35, 0
	s_mov_b32 m0, s41
	v_lshl_add_u64 v[228:229], s[34:35], 0, v[130:131]
	ds_read_b128 v[192:195], v159 offset:32768
	ds_read_b128 v[196:199], v159 offset:33792
	ds_read_b128 v[200:203], v159 offset:34816
	ds_read_b128 v[204:207], v159 offset:35840
	ds_read_b128 v[208:211], v159 offset:36864
	ds_read_b128 v[212:215], v159 offset:37888
	ds_read_b128 v[216:219], v159 offset:38912
	ds_read_b128 v[220:223], v159 offset:39936
	global_load_lds_dwordx4 v[228:229], off
	v_lshl_add_u64 v[228:229], s[34:35], 0, v[136:137]
	s_mov_b32 m0, s42
	s_nop 0
	global_load_lds_dwordx4 v[228:229], off
	s_waitcnt vmcnt(8)
	s_waitcnt lgkmcnt(0)
	s_barrier
	s_setprio 1
	s_waitcnt lgkmcnt(0)
	v_mfma_f32_16x16x32_bf16 v[126:129], v[146:149], v[192:195], v[126:129]
	v_mfma_f32_16x16x32_bf16 v[126:129], v[164:167], v[196:199], v[126:129]
	v_mfma_f32_16x16x32_bf16 v[122:125], v[168:171], v[192:195], v[122:125]
	v_mfma_f32_16x16x32_bf16 v[122:125], v[172:175], v[196:199], v[122:125]
	v_mfma_f32_16x16x32_bf16 v[110:113], v[146:149], v[200:203], v[110:113]
	v_mfma_f32_16x16x32_bf16 v[110:113], v[164:167], v[204:207], v[110:113]
	v_mfma_f32_16x16x32_bf16 v[106:109], v[168:171], v[200:203], v[106:109]
	v_mfma_f32_16x16x32_bf16 v[106:109], v[172:175], v[204:207], v[106:109]
	v_mfma_f32_16x16x32_bf16 v[94:97], v[146:149], v[208:211], v[94:97]
	v_mfma_f32_16x16x32_bf16 v[94:97], v[164:167], v[212:215], v[94:97]
	v_mfma_f32_16x16x32_bf16 v[90:93], v[168:171], v[208:211], v[90:93]
	v_mfma_f32_16x16x32_bf16 v[90:93], v[172:175], v[212:215], v[90:93]
	v_mfma_f32_16x16x32_bf16 v[78:81], v[146:149], v[216:219], v[78:81]
	v_mfma_f32_16x16x32_bf16 v[78:81], v[164:167], v[220:223], v[78:81]
	v_mfma_f32_16x16x32_bf16 v[74:77], v[168:171], v[216:219], v[74:77]
	v_mfma_f32_16x16x32_bf16 v[74:77], v[172:175], v[220:223], v[74:77]
	s_setprio 0
	s_setprio 1
	v_mfma_f32_16x16x32_bf16 v[118:121], v[176:179], v[192:195], v[118:121]
	v_mfma_f32_16x16x32_bf16 v[118:121], v[180:183], v[196:199], v[118:121]
	v_mfma_f32_16x16x32_bf16 v[114:117], v[184:187], v[192:195], v[114:117]
	v_mfma_f32_16x16x32_bf16 v[114:117], v[188:191], v[196:199], v[114:117]
	v_mfma_f32_16x16x32_bf16 v[102:105], v[176:179], v[200:203], v[102:105]
	v_mfma_f32_16x16x32_bf16 v[102:105], v[180:183], v[204:207], v[102:105]
	v_mfma_f32_16x16x32_bf16 v[98:101], v[184:187], v[200:203], v[98:101]
	v_mfma_f32_16x16x32_bf16 v[98:101], v[188:191], v[204:207], v[98:101]
	v_mfma_f32_16x16x32_bf16 v[86:89], v[176:179], v[208:211], v[86:89]
	v_mfma_f32_16x16x32_bf16 v[86:89], v[180:183], v[212:215], v[86:89]
	v_mfma_f32_16x16x32_bf16 v[82:85], v[184:187], v[208:211], v[82:85]
	v_mfma_f32_16x16x32_bf16 v[82:85], v[188:191], v[212:215], v[82:85]
	v_mfma_f32_16x16x32_bf16 v[70:73], v[176:179], v[216:219], v[70:73]
	v_mfma_f32_16x16x32_bf16 v[70:73], v[180:183], v[220:223], v[70:73]
	v_mfma_f32_16x16x32_bf16 v[66:69], v[184:187], v[216:219], v[66:69]
	v_mfma_f32_16x16x32_bf16 v[66:69], v[188:191], v[220:223], v[66:69]
	s_setprio 0
	s_barrier
	s_add_i32 s34, s53, s38
	v_lshl_add_u64 v[150:151], v[150:151], 0, s[10:11]
	s_mov_b32 m0, s34
	ds_read_b128 v[192:195], v159 offset:49152
	ds_read_b128 v[196:199], v159 offset:50176
	ds_read_b128 v[200:203], v159 offset:51200
	ds_read_b128 v[204:207], v159 offset:52224
	ds_read_b128 v[208:211], v159 offset:53248
	ds_read_b128 v[212:215], v159 offset:54272
	ds_read_b128 v[216:219], v159 offset:55296
	ds_read_b128 v[220:223], v159 offset:56320
	global_load_lds_dwordx4 v[150:151], off
	s_add_i32 m0, s34, 0x2000
	s_add_u32 s26, s26, 0x100080
	v_lshl_add_u64 v[150:151], v[160:161], 0, s[10:11]
	s_addc_u32 s27, s27, 0
	s_add_i32 s34, s54, s38
	global_load_lds_dwordx4 v[150:151], off
	v_lshl_add_u64 v[150:151], s[26:27], 0, v[132:133]
	s_mov_b32 m0, s34
	s_nop 0
	global_load_lds_dwordx4 v[150:151], off
	v_lshl_add_u64 v[150:151], s[26:27], 0, v[134:135]
	s_add_i32 m0, s34, 0x2000
	s_nop 0
	global_load_lds_dwordx4 v[150:151], off
	v_lshl_add_u64 v[150:151], v[224:225], 0, s[10:11]
	s_mov_b32 m0, s43
	s_nop 0
	global_load_lds_dwordx4 v[150:151], off
	v_lshl_add_u64 v[150:151], v[226:227], 0, s[10:11]
	s_mov_b32 m0, s44
	s_nop 0
	global_load_lds_dwordx4 v[150:151], off
	s_waitcnt vmcnt(8)
	s_waitcnt lgkmcnt(0)
	s_barrier
	s_setprio 1
	s_waitcnt lgkmcnt(0)
	v_mfma_f32_16x16x32_bf16 v[62:65], v[146:149], v[192:195], v[62:65]
	v_mfma_f32_16x16x32_bf16 v[62:65], v[164:167], v[196:199], v[62:65]
	v_mfma_f32_16x16x32_bf16 v[58:61], v[168:171], v[192:195], v[58:61]
	v_mfma_f32_16x16x32_bf16 v[58:61], v[172:175], v[196:199], v[58:61]
	v_mfma_f32_16x16x32_bf16 v[46:49], v[146:149], v[200:203], v[46:49]
	v_mfma_f32_16x16x32_bf16 v[46:49], v[164:167], v[204:207], v[46:49]
	v_mfma_f32_16x16x32_bf16 v[42:45], v[168:171], v[200:203], v[42:45]
	v_mfma_f32_16x16x32_bf16 v[42:45], v[172:175], v[204:207], v[42:45]
	v_mfma_f32_16x16x32_bf16 v[30:33], v[146:149], v[208:211], v[30:33]
	v_mfma_f32_16x16x32_bf16 v[30:33], v[164:167], v[212:215], v[30:33]
	v_mfma_f32_16x16x32_bf16 v[26:29], v[168:171], v[208:211], v[26:29]
	v_mfma_f32_16x16x32_bf16 v[26:29], v[172:175], v[212:215], v[26:29]
	v_mfma_f32_16x16x32_bf16 v[14:17], v[146:149], v[216:219], v[14:17]
	v_mfma_f32_16x16x32_bf16 v[14:17], v[164:167], v[220:223], v[14:17]
	v_mfma_f32_16x16x32_bf16 v[10:13], v[168:171], v[216:219], v[10:13]
	v_mfma_f32_16x16x32_bf16 v[10:13], v[172:175], v[220:223], v[10:13]
	s_setprio 0
	s_setprio 1
	v_mfma_f32_16x16x32_bf16 v[54:57], v[176:179], v[192:195], v[54:57]
	v_mfma_f32_16x16x32_bf16 v[54:57], v[180:183], v[196:199], v[54:57]
	v_mfma_f32_16x16x32_bf16 v[50:53], v[184:187], v[192:195], v[50:53]
	v_mfma_f32_16x16x32_bf16 v[50:53], v[188:191], v[196:199], v[50:53]
	v_mfma_f32_16x16x32_bf16 v[38:41], v[176:179], v[200:203], v[38:41]
	v_mfma_f32_16x16x32_bf16 v[38:41], v[180:183], v[204:207], v[38:41]
	v_mfma_f32_16x16x32_bf16 v[34:37], v[184:187], v[200:203], v[34:37]
	v_mfma_f32_16x16x32_bf16 v[34:37], v[188:191], v[204:207], v[34:37]
	v_mfma_f32_16x16x32_bf16 v[22:25], v[176:179], v[208:211], v[22:25]
	v_mfma_f32_16x16x32_bf16 v[22:25], v[180:183], v[212:215], v[22:25]
	v_mfma_f32_16x16x32_bf16 v[18:21], v[184:187], v[208:211], v[18:21]
	v_mfma_f32_16x16x32_bf16 v[18:21], v[188:191], v[212:215], v[18:21]
	v_mfma_f32_16x16x32_bf16 v[6:9], v[176:179], v[216:219], v[6:9]
	v_mfma_f32_16x16x32_bf16 v[6:9], v[180:183], v[220:223], v[6:9]
	v_mfma_f32_16x16x32_bf16 v[2:5], v[184:187], v[216:219], v[2:5]
	v_mfma_f32_16x16x32_bf16 v[2:5], v[188:191], v[220:223], v[2:5]
	s_setprio 0
	s_barrier
	s_add_i32 s52, s52, 2
	s_add_u32 s24, s24, 0x100
	s_addc_u32 s25, s25, 0
	s_add_u32 s50, s50, 0x100
	s_addc_u32 s51, s51, 0
	s_cmp_gt_u32 s52, 61
	s_cbranch_scc0 .LBB0_2158
	s_and_b64 vcc, exec, s[12:13]
	s_cbranch_vccz .LBB0_2161
	s_barrier
